# silu epilogues (gemm1/kvq) IEEE div -> v_rcp*x; prep2 IEEE 1/x -> v_rcp, tighter dead-code removal; write-through 16B epilogue stores in gemm1/kvq
# speedup vs baseline: 1.0876x; 1.0161x over previous
.LBB0_173:
	v_cvt_pk_bf16_f32 v48, v48, s0
	v_add_u32_e32 v81, v149, v151
	ds_write_b16 v81, v48
	v_cvt_pk_bf16_f32 v48, v49, s0
	ds_write_b16 v81, v48 offset:144
	v_cvt_pk_bf16_f32 v48, v50, s0
	ds_write_b16 v81, v48 offset:288
	v_cvt_pk_bf16_f32 v48, v51, s0
	v_add_u32_e32 v49, v149, v180
	ds_write_b16 v49, v48
	v_cvt_pk_bf16_f32 v48, v52, s0
	ds_write_b16 v81, v48 offset:1152
	v_cvt_pk_bf16_f32 v48, v53, s0
	ds_write_b16 v81, v48 offset:1296
	v_cvt_pk_bf16_f32 v48, v54, s0
	ds_write_b16 v81, v48 offset:1440
	v_cvt_pk_bf16_f32 v48, v55, s0
	v_add_u32_e32 v49, v149, v181
	ds_write_b16 v49, v48
	v_cvt_pk_bf16_f32 v48, v56, s0
	ds_write_b16 v81, v48 offset:2304
	v_cvt_pk_bf16_f32 v48, v57, s0
	ds_write_b16 v81, v48 offset:2448
	v_cvt_pk_bf16_f32 v48, v58, s0
	ds_write_b16 v81, v48 offset:2592
	v_cvt_pk_bf16_f32 v48, v59, s0
	v_add_u32_e32 v49, v149, v182
	ds_write_b16 v49, v48
	v_cvt_pk_bf16_f32 v48, v60, s0
	ds_write_b16 v81, v48 offset:3456
	v_cvt_pk_bf16_f32 v48, v61, s0
	ds_write_b16 v81, v48 offset:3600
	v_cvt_pk_bf16_f32 v48, v62, s0
	ds_write_b16 v81, v48 offset:3744
	v_cvt_pk_bf16_f32 v48, v63, s0
	v_add_u32_e32 v49, v149, v183
	ds_write_b16 v49, v48
	v_cvt_pk_bf16_f32 v32, v32, s0
	v_add_u32_e32 v48, v184, v151
	ds_write_b16 v48, v32
	v_cvt_pk_bf16_f32 v32, v33, s0
	ds_write_b16 v48, v32 offset:144
	v_cvt_pk_bf16_f32 v32, v34, s0
	ds_write_b16 v48, v32 offset:288
	v_cvt_pk_bf16_f32 v32, v35, s0
	v_add_u32_e32 v33, v184, v180
	ds_write_b16 v33, v32
	v_cvt_pk_bf16_f32 v32, v36, s0
	ds_write_b16 v48, v32 offset:1152
	v_cvt_pk_bf16_f32 v32, v37, s0
	ds_write_b16 v48, v32 offset:1296
	v_cvt_pk_bf16_f32 v32, v38, s0
	ds_write_b16 v48, v32 offset:1440
	v_cvt_pk_bf16_f32 v32, v39, s0
	v_add_u32_e32 v33, v184, v181
	ds_write_b16 v33, v32
	v_cvt_pk_bf16_f32 v32, v40, s0
	ds_write_b16 v48, v32 offset:2304
	v_cvt_pk_bf16_f32 v32, v41, s0
	ds_write_b16 v48, v32 offset:2448
	v_cvt_pk_bf16_f32 v32, v42, s0
	ds_write_b16 v48, v32 offset:2592
	v_cvt_pk_bf16_f32 v32, v43, s0
	v_add_u32_e32 v33, v184, v182
	ds_write_b16 v33, v32
	v_cvt_pk_bf16_f32 v32, v44, s0
	ds_write_b16 v48, v32 offset:3456
	v_cvt_pk_bf16_f32 v32, v45, s0
	ds_write_b16 v48, v32 offset:3600
	v_cvt_pk_bf16_f32 v32, v46, s0
	ds_write_b16 v48, v32 offset:3744
	v_cvt_pk_bf16_f32 v32, v47, s0
	v_add_u32_e32 v33, v184, v183
	v_cvt_pk_bf16_f32 v16, v16, s0
	ds_write_b16 v33, v32
	ds_write_b16 v81, v16 offset:4608
	v_cvt_pk_bf16_f32 v16, v17, s0
	ds_write_b16 v81, v16 offset:4752
	v_cvt_pk_bf16_f32 v16, v18, s0
	ds_write_b16 v81, v16 offset:4896
	v_cvt_pk_bf16_f32 v16, v19, s0
	v_add_u32_e32 v17, v149, v185
	ds_write_b16 v17, v16
	v_cvt_pk_bf16_f32 v16, v20, s0
	ds_write_b16 v81, v16 offset:5760
	v_cvt_pk_bf16_f32 v16, v21, s0
	ds_write_b16 v81, v16 offset:5904
	v_cvt_pk_bf16_f32 v16, v22, s0
	ds_write_b16 v81, v16 offset:6048
	v_cvt_pk_bf16_f32 v16, v23, s0
	v_add_u32_e32 v17, v149, v186
	ds_write_b16 v17, v16
	v_cvt_pk_bf16_f32 v16, v24, s0
	ds_write_b16 v81, v16 offset:6912
	v_cvt_pk_bf16_f32 v16, v25, s0
	ds_write_b16 v81, v16 offset:7056
	v_cvt_pk_bf16_f32 v16, v26, s0
	ds_write_b16 v81, v16 offset:7200
	v_cvt_pk_bf16_f32 v16, v27, s0
	v_add_u32_e32 v17, v149, v187
	ds_write_b16 v17, v16
	v_cvt_pk_bf16_f32 v16, v28, s0
	ds_write_b16 v81, v16 offset:8064
	v_cvt_pk_bf16_f32 v16, v29, s0
	ds_write_b16 v81, v16 offset:8208
	v_cvt_pk_bf16_f32 v16, v30, s0
	ds_write_b16 v81, v16 offset:8352
	v_cvt_pk_bf16_f32 v16, v31, s0
	v_add_u32_e32 v17, v149, v188
	v_cvt_pk_bf16_f32 v0, v0, s0
	ds_write_b16 v17, v16
	ds_write_b16 v48, v0 offset:4608
	v_cvt_pk_bf16_f32 v0, v1, s0
	ds_write_b16 v48, v0 offset:4752
	v_cvt_pk_bf16_f32 v0, v2, s0
	ds_write_b16 v48, v0 offset:4896
	v_cvt_pk_bf16_f32 v0, v3, s0
	v_add_u32_e32 v1, v184, v185
	ds_write_b16 v1, v0
	v_cvt_pk_bf16_f32 v0, v4, s0
	ds_write_b16 v48, v0 offset:5760
	v_cvt_pk_bf16_f32 v0, v5, s0
	ds_write_b16 v48, v0 offset:5904
	v_cvt_pk_bf16_f32 v0, v6, s0
	ds_write_b16 v48, v0 offset:6048
	v_cvt_pk_bf16_f32 v0, v7, s0
	v_add_u32_e32 v1, v184, v186
	ds_write_b16 v1, v0
	v_cvt_pk_bf16_f32 v0, v8, s0
	ds_write_b16 v48, v0 offset:6912
	v_cvt_pk_bf16_f32 v0, v9, s0
	s_cmp_eq_u32 s15, 2
	s_brev_b32 s20, 8
	ds_write_b16 v48, v0 offset:7056
	v_cvt_pk_bf16_f32 v0, v10, s0
	s_cselect_b32 s20, s20, 0x14000000
	s_cmp_lg_u32 s15, 1
	ds_write_b16 v48, v0 offset:7200
	v_cvt_pk_bf16_f32 v0, v11, s0
	v_add_u32_e32 v1, v184, v187
	s_cselect_b32 s15, s20, 0xc000000
	s_cmp_gt_u32 s14, 7
	ds_write_b16 v1, v0
	v_cvt_pk_bf16_f32 v0, v12, s0
	s_cselect_b32 s15, s15, 0x8000000
	v_lshl_add_u32 v82, s88, 7, v133
	ds_write_b16 v48, v0 offset:8064
	v_cvt_pk_bf16_f32 v0, v13, s0
	s_add_u32 s20, s0, s15
	v_ashrrev_i32_e32 v83, 31, v82
	ds_write_b16 v48, v0 offset:8208
	v_cvt_pk_bf16_f32 v0, v14, s0
	s_addc_u32 s21, s1, 0
	v_lshlrev_b64 v[82:83], 11, v[82:83]
	s_lshl_b32 s14, s14, 8
	ds_write_b16 v48, v0 offset:8352
	v_cvt_pk_bf16_f32 v0, v15, s0
	v_add_u32_e32 v1, v184, v188
	v_add_u32_e32 v8, v189, v190
	v_lshl_add_u64 v[82:83], s[20:21], 0, v[82:83]
	s_and_b32 s74, s14, 0x700
	ds_write_b16 v1, v0
	ds_read_b128 v[0:3], v8
	v_lshl_add_u64 v[82:83], v[82:83], 0, s[74:75]
	v_mov_b32_e32 v159, v80
	v_lshl_add_u64 v[82:83], v[82:83], 0, v[158:159]
	v_lshlrev_b32_e32 v4, 1, v132
	v_mov_b32_e32 v5, v80
	v_lshl_add_u64 v[4:5], v[82:83], 0, v[4:5]
	v_mov_b32_e32 v161, v80
	v_lshl_add_u64 v[6:7], v[4:5], 0, v[160:161]
	s_waitcnt lgkmcnt(0)
	global_store_dwordx4 v[6:7], v[0:3], off sc0 sc1
	ds_read_b128 v[0:3], v8 offset:1152
	v_mov_b32_e32 v163, v80
	v_lshl_add_u64 v[6:7], v[4:5], 0, v[162:163]
	v_mov_b32_e32 v165, v80
	v_mov_b32_e32 v167, v80
	s_waitcnt lgkmcnt(0)
	global_store_dwordx4 v[6:7], v[0:3], off sc0 sc1
	ds_read_b128 v[0:3], v8 offset:2304
	v_lshl_add_u64 v[6:7], v[4:5], 0, v[164:165]
	v_mov_b32_e32 v169, v80
	v_mov_b32_e32 v171, v80
	v_mov_b32_e32 v173, v80
	s_waitcnt lgkmcnt(0)
	global_store_dwordx4 v[6:7], v[0:3], off sc0 sc1
	ds_read_b128 v[0:3], v8 offset:3456
	v_lshl_add_u64 v[6:7], v[4:5], 0, v[166:167]
	v_mov_b32_e32 v175, v80
	s_waitcnt lgkmcnt(0)
	global_store_dwordx4 v[6:7], v[0:3], off sc0 sc1
	ds_read_b128 v[0:3], v8 offset:4608
	v_lshl_add_u64 v[6:7], v[4:5], 0, v[168:169]
	s_waitcnt lgkmcnt(0)
	global_store_dwordx4 v[6:7], v[0:3], off sc0 sc1
	ds_read_b128 v[0:3], v8 offset:5760
	v_lshl_add_u64 v[6:7], v[4:5], 0, v[170:171]
	s_waitcnt lgkmcnt(0)
	global_store_dwordx4 v[6:7], v[0:3], off sc0 sc1
	ds_read_b128 v[0:3], v8 offset:6912
	v_lshl_add_u64 v[6:7], v[4:5], 0, v[172:173]
	v_lshl_add_u64 v[4:5], v[4:5], 0, v[174:175]
	s_waitcnt lgkmcnt(0)
	global_store_dwordx4 v[6:7], v[0:3], off sc0 sc1
	ds_read_b128 v[0:3], v8 offset:8064
	s_waitcnt lgkmcnt(0)
	global_store_dwordx4 v[4:5], v[0:3], off sc0 sc1

.LBB0_460:
	s_or_b64 exec, exec, s[76:77]
	v_lshl_add_u32 v146, s88, 7, v133
	v_ashrrev_i32_e32 v147, 31, v146
	v_lshl_add_u64 v[82:83], s[0:1], 0, v[82:83]
	v_lshlrev_b64 v[146:147], 7, v[146:147]
	v_lshl_add_u64 v[82:83], v[82:83], 0, v[146:147]
	v_cvt_pk_bf16_f32 v145, v201, s0
	v_add_u32_e32 v146, v149, v151
	ds_write_b16 v146, v145
	v_cvt_pk_bf16_f32 v145, v198, s0
	ds_write_b16 v146, v145 offset:144
	v_cvt_pk_bf16_f32 v145, v199, s0
	ds_write_b16 v146, v145 offset:288
	v_cvt_pk_bf16_f32 v145, v200, s0
	v_add_u32_e32 v147, v149, v180
	ds_write_b16 v147, v145
	v_cvt_pk_bf16_f32 v145, v193, s0
	ds_write_b16 v146, v145 offset:1152
	v_cvt_pk_bf16_f32 v145, v194, s0
	ds_write_b16 v146, v145 offset:1296
	v_cvt_pk_bf16_f32 v145, v195, s0
	ds_write_b16 v146, v145 offset:1440
	v_cvt_pk_bf16_f32 v145, v197, s0
	v_add_u32_e32 v147, v149, v181
	v_cvt_pk_bf16_f32 v143, v143, s0
	ds_write_b16 v147, v145
	ds_write_b16 v146, v143 offset:2304
	v_cvt_pk_bf16_f32 v143, v153, s0
	ds_write_b16 v146, v143 offset:2448
	v_cvt_pk_bf16_f32 v143, v155, s0
	ds_write_b16 v146, v143 offset:2592
	v_cvt_pk_bf16_f32 v143, v157, s0
	v_add_u32_e32 v145, v149, v182
	v_cvt_pk_bf16_f32 v135, v135, s0
	ds_write_b16 v145, v143
	ds_write_b16 v146, v135 offset:3456
	v_cvt_pk_bf16_f32 v135, v137, s0
	ds_write_b16 v146, v135 offset:3600
	v_cvt_pk_bf16_f32 v135, v139, s0
	ds_write_b16 v146, v135 offset:3744
	v_cvt_pk_bf16_f32 v135, v141, s0
	v_add_u32_e32 v137, v149, v183
	ds_write_b16 v137, v135
	v_cvt_pk_bf16_f32 v135, v217, s0
	v_add_u32_e32 v137, v184, v151
	ds_write_b16 v137, v135
	v_cvt_pk_bf16_f32 v135, v214, s0
	ds_write_b16 v137, v135 offset:144
	v_cvt_pk_bf16_f32 v135, v215, s0
	ds_write_b16 v137, v135 offset:288
	v_cvt_pk_bf16_f32 v135, v216, s0
	v_add_u32_e32 v139, v184, v180
	ds_write_b16 v139, v135
	v_cvt_pk_bf16_f32 v135, v210, s0
	ds_write_b16 v137, v135 offset:1152
	v_cvt_pk_bf16_f32 v135, v211, s0
	ds_write_b16 v137, v135 offset:1296
	v_cvt_pk_bf16_f32 v135, v212, s0
	ds_write_b16 v137, v135 offset:1440
	v_cvt_pk_bf16_f32 v135, v213, s0
	v_add_u32_e32 v139, v184, v181
	ds_write_b16 v139, v135
	v_cvt_pk_bf16_f32 v135, v176, s0
	ds_write_b16 v137, v135 offset:2304
	v_cvt_pk_bf16_f32 v135, v177, s0
	ds_write_b16 v137, v135 offset:2448
	v_cvt_pk_bf16_f32 v135, v178, s0
	ds_write_b16 v137, v135 offset:2592
	v_cvt_pk_bf16_f32 v135, v179, s0
	v_add_u32_e32 v139, v184, v182
	ds_write_b16 v139, v135
	v_cvt_pk_bf16_f32 v135, v169, s0
	ds_write_b16 v137, v135 offset:3456
	v_cvt_pk_bf16_f32 v135, v171, s0
	ds_write_b16 v137, v135 offset:3600
	v_cvt_pk_bf16_f32 v135, v173, s0
	ds_write_b16 v137, v135 offset:3744
	v_cvt_pk_bf16_f32 v135, v175, s0
	v_add_u32_e32 v139, v184, v183
	ds_write_b16 v139, v135
	v_cvt_pk_bf16_f32 v135, v237, s0
	ds_write_b16 v146, v135 offset:4608
	v_cvt_pk_bf16_f32 v135, v238, s0
	ds_write_b16 v146, v135 offset:4752
	v_cvt_pk_bf16_f32 v135, v239, s0
	ds_write_b16 v146, v135 offset:4896
	v_cvt_pk_bf16_f32 v135, v240, s0
	v_add_u32_e32 v139, v149, v185
	ds_write_b16 v139, v135
	v_cvt_pk_bf16_f32 v135, v226, s0
	ds_write_b16 v146, v135 offset:5760
	v_cvt_pk_bf16_f32 v135, v234, s0
	ds_write_b16 v146, v135 offset:5904
	v_cvt_pk_bf16_f32 v135, v235, s0
	ds_write_b16 v146, v135 offset:6048
	v_cvt_pk_bf16_f32 v135, v236, s0
	v_add_u32_e32 v139, v149, v186
	ds_write_b16 v139, v135
	v_cvt_pk_bf16_f32 v135, v206, s0
	ds_write_b16 v146, v135 offset:6912
	v_cvt_pk_bf16_f32 v135, v207, s0
	ds_write_b16 v146, v135 offset:7056
	v_cvt_pk_bf16_f32 v135, v208, s0
	ds_write_b16 v146, v135 offset:7200
	v_cvt_pk_bf16_f32 v135, v209, s0
	v_add_u32_e32 v139, v149, v187
	ds_write_b16 v139, v135
	v_cvt_pk_bf16_f32 v135, v202, s0
	ds_write_b16 v146, v135 offset:8064
	v_cvt_pk_bf16_f32 v135, v203, s0
	ds_write_b16 v146, v135 offset:8208
	v_cvt_pk_bf16_f32 v135, v204, s0
	ds_write_b16 v146, v135 offset:8352
	v_cvt_pk_bf16_f32 v135, v205, s0
	v_add_u32_e32 v139, v149, v188
	ds_write_b16 v139, v135
	v_cvt_pk_bf16_f32 v135, v230, s0
	ds_write_b16 v137, v135 offset:4608
	v_cvt_pk_bf16_f32 v135, v231, s0
	ds_write_b16 v137, v135 offset:4752
	v_cvt_pk_bf16_f32 v135, v232, s0
	ds_write_b16 v137, v135 offset:4896
	v_cvt_pk_bf16_f32 v135, v233, s0
	v_add_u32_e32 v139, v184, v185
	ds_write_b16 v139, v135
	v_cvt_pk_bf16_f32 v135, v227, s0
	ds_write_b16 v137, v135 offset:5760
	v_cvt_pk_bf16_f32 v135, v228, s0
	ds_write_b16 v137, v135 offset:5904
	v_cvt_pk_bf16_f32 v135, v229, s0
	ds_write_b16 v137, v135 offset:6048
	v_cvt_pk_bf16_f32 v135, v225, s0
	v_add_u32_e32 v139, v184, v186
	ds_write_b16 v139, v135
	v_cvt_pk_bf16_f32 v135, v221, s0
	ds_write_b16 v137, v135 offset:6912
	v_cvt_pk_bf16_f32 v135, v222, s0
	ds_write_b16 v137, v135 offset:7056
	v_cvt_pk_bf16_f32 v135, v223, s0
	ds_write_b16 v137, v135 offset:7200
	v_cvt_pk_bf16_f32 v135, v224, s0
	v_add_u32_e32 v139, v184, v187
	ds_write_b16 v139, v135
	v_cvt_pk_bf16_f32 v135, v218, s0
	ds_write_b16 v137, v135 offset:8064
	v_cvt_pk_bf16_f32 v135, v219, s0
	ds_write_b16 v137, v135 offset:8208
	v_cvt_pk_bf16_f32 v135, v220, s0
	ds_write_b16 v137, v135 offset:8352
	v_cvt_pk_bf16_f32 v81, v81, s0
	v_add_u32_e32 v135, v184, v188
	ds_write_b16 v135, v81
	v_add_u32_e32 v81, v189, v190
	ds_read_b128 v[176:179], v81
	v_lshlrev_b32_e32 v146, 1, v132
	v_mov_b32_e32 v147, v80
	v_lshl_add_u64 v[82:83], v[82:83], 0, v[146:147]
	v_mov_b32_e32 v135, v80
	v_lshl_add_u64 v[146:147], v[82:83], 0, v[134:135]
	s_waitcnt lgkmcnt(0)
	global_store_dwordx4 v[146:147], v[176:179], off sc0 sc1
	ds_read_b128 v[176:179], v81 offset:1152
	v_mov_b32_e32 v137, v80
	v_lshl_add_u64 v[146:147], v[82:83], 0, v[136:137]
	v_mov_b32_e32 v139, v80
	v_mov_b32_e32 v141, v80
	s_waitcnt lgkmcnt(0)
	global_store_dwordx4 v[146:147], v[176:179], off sc0 sc1
	ds_read_b128 v[176:179], v81 offset:2304
	v_lshl_add_u64 v[146:147], v[82:83], 0, v[138:139]
	v_mov_b32_e32 v143, v80
	v_mov_b32_e32 v153, v80
	v_mov_b32_e32 v155, v80
	s_waitcnt lgkmcnt(0)
	global_store_dwordx4 v[146:147], v[176:179], off sc0 sc1
	ds_read_b128 v[176:179], v81 offset:3456
	v_lshl_add_u64 v[146:147], v[82:83], 0, v[140:141]
	v_mov_b32_e32 v157, v80
	s_waitcnt lgkmcnt(0)
	global_store_dwordx4 v[146:147], v[176:179], off sc0 sc1
	ds_read_b128 v[176:179], v81 offset:4608
	v_lshl_add_u64 v[146:147], v[82:83], 0, v[142:143]
	s_waitcnt lgkmcnt(0)
	global_store_dwordx4 v[146:147], v[176:179], off sc0 sc1
	ds_read_b128 v[176:179], v81 offset:5760
	v_lshl_add_u64 v[146:147], v[82:83], 0, v[152:153]
	s_waitcnt lgkmcnt(0)
	global_store_dwordx4 v[146:147], v[176:179], off sc0 sc1
	ds_read_b128 v[176:179], v81 offset:6912
	v_lshl_add_u64 v[146:147], v[82:83], 0, v[154:155]
	v_lshl_add_u64 v[82:83], v[82:83], 0, v[156:157]
	s_waitcnt lgkmcnt(0)
	global_store_dwordx4 v[146:147], v[176:179], off sc0 sc1
	ds_read_b128 v[176:179], v81 offset:8064
	s_waitcnt lgkmcnt(0)
	global_store_dwordx4 v[82:83], v[176:179], off sc0 sc1
	s_branch .LBB0_174
.LBB0_461:
	s_and_b64 vcc, exec, s[76:77]
	s_cbranch_vccz .LBB0_174
	s_ashr_i32 s15, s14, 3
	s_cmp_lg_u32 s15, 3
	s_cbranch_scc1 .LBB0_173
	v_mul_f32_e32 v81, 0xbfb8aa3b, v48
	v_exp_f32_e32 v146, v81
	v_mul_f32_e32 v81, 0xbfb8aa3b, v49
	v_exp_f32_e32 v147, v81
	v_mul_f32_e32 v81, 0xbfb8aa3b, v50
	v_exp_f32_e32 v178, v81
	v_mul_f32_e32 v81, 0xbfb8aa3b, v51
	v_exp_f32_e32 v179, v81
	v_mul_f32_e32 v81, 0xbfb8aa3b, v52
	v_exp_f32_e32 v194, v81
	v_mul_f32_e32 v81, 0xbfb8aa3b, v53
	v_exp_f32_e32 v195, v81
	v_mul_f32_e32 v81, 0xbfb8aa3b, v54
	v_exp_f32_e32 v198, v81
	v_mul_f32_e32 v81, 0xbfb8aa3b, v55
	v_exp_f32_e32 v199, v81
	v_mul_f32_e32 v81, 0xbfb8aa3b, v56
	v_exp_f32_e32 v200, v81
	v_mul_f32_e32 v81, 0xbfb8aa3b, v57
	v_pk_add_f32 v[146:147], v[146:147], 1.0 op_sel_hi:[1,0]
	v_mul_f32_e32 v135, 0xbfb8aa3b, v59
	v_exp_f32_e32 v201, v81
	v_exp_f32_e32 v203, v135
	v_mul_f32_e32 v137, 0xbfb8aa3b, v61
	v_exp_f32_e32 v177, v137
	v_pk_add_f32 v[178:179], v[178:179], 1.0 op_sel_hi:[1,0]
	v_rcp_f32_e32 v81, v146
	s_nop 0
	v_mul_f32_e32 v48, v48, v81
	v_pk_add_f32 v[194:195], v[194:195], 1.0 op_sel_hi:[1,0]
	v_rcp_f32_e32 v81, v147
	s_nop 0
	v_mul_f32_e32 v49, v49, v81
	v_pk_add_f32 v[198:199], v[198:199], 1.0 op_sel_hi:[1,0]
	v_rcp_f32_e32 v81, v178
	s_nop 0
	v_mul_f32_e32 v50, v50, v81
	v_pk_add_f32 v[200:201], v[200:201], 1.0 op_sel_hi:[1,0]
	v_rcp_f32_e32 v81, v179
	s_nop 0
	v_mul_f32_e32 v51, v51, v81
	v_mul_f32_e32 v82, 0xbfb8aa3b, v58
	v_rcp_f32_e32 v81, v194
	s_nop 0
	v_mul_f32_e32 v52, v52, v81
	v_exp_f32_e32 v202, v82
	v_rcp_f32_e32 v81, v195
	s_nop 0
	v_mul_f32_e32 v53, v53, v81
	v_pk_add_f32 v[202:203], v[202:203], 1.0 op_sel_hi:[1,0]
	v_rcp_f32_e32 v81, v198
	s_nop 0
	v_mul_f32_e32 v54, v54, v81
	v_mul_f32_e32 v82, 0xbfb8aa3b, v60
	v_rcp_f32_e32 v81, v199
	s_nop 0
	v_mul_f32_e32 v55, v55, v81
	v_exp_f32_e32 v176, v82
	v_rcp_f32_e32 v81, v200
	s_nop 0
	v_mul_f32_e32 v56, v56, v81
	v_pk_add_f32 v[176:177], v[176:177], 1.0 op_sel_hi:[1,0]
	v_rcp_f32_e32 v81, v201
	s_nop 0
	v_mul_f32_e32 v57, v57, v81
	v_mul_f32_e32 v82, 0xbfb8aa3b, v62
	v_rcp_f32_e32 v81, v202
	s_nop 0
	v_mul_f32_e32 v58, v58, v81
	v_mul_f32_e32 v83, 0xbfb8aa3b, v63
	v_rcp_f32_e32 v81, v203
	s_nop 0
	v_mul_f32_e32 v59, v59, v81
	v_exp_f32_e32 v82, v82
	v_exp_f32_e32 v83, v83
	v_rcp_f32_e32 v81, v176
	s_nop 0
	v_mul_f32_e32 v60, v60, v81
	v_pk_add_f32 v[82:83], v[82:83], 1.0 op_sel_hi:[1,0]
	v_rcp_f32_e32 v81, v177
	s_nop 0
	v_mul_f32_e32 v61, v61, v81
	v_rcp_f32_e32 v81, v82
	s_nop 0
	v_mul_f32_e32 v62, v62, v81
	v_rcp_f32_e32 v81, v83
	s_nop 0
	v_mul_f32_e32 v63, v63, v81
	v_mul_f32_e32 v81, 0xbfb8aa3b, v32
	v_exp_f32_e32 v146, v81
	v_mul_f32_e32 v81, 0xbfb8aa3b, v33
	v_exp_f32_e32 v147, v81
	v_mul_f32_e32 v81, 0xbfb8aa3b, v34
	v_exp_f32_e32 v178, v81
	v_mul_f32_e32 v81, 0xbfb8aa3b, v35
	v_exp_f32_e32 v179, v81
	v_mul_f32_e32 v81, 0xbfb8aa3b, v36
	v_exp_f32_e32 v194, v81
	v_mul_f32_e32 v81, 0xbfb8aa3b, v37
	v_exp_f32_e32 v195, v81
	v_mul_f32_e32 v81, 0xbfb8aa3b, v38
	v_exp_f32_e32 v198, v81
	v_mul_f32_e32 v81, 0xbfb8aa3b, v39
	v_exp_f32_e32 v199, v81
	v_mul_f32_e32 v81, 0xbfb8aa3b, v40
	v_exp_f32_e32 v200, v81
	v_mul_f32_e32 v81, 0xbfb8aa3b, v41
	v_pk_add_f32 v[146:147], v[146:147], 1.0 op_sel_hi:[1,0]
	v_mul_f32_e32 v135, 0xbfb8aa3b, v43
	v_exp_f32_e32 v201, v81
	v_exp_f32_e32 v203, v135
	v_mul_f32_e32 v137, 0xbfb8aa3b, v45
	v_exp_f32_e32 v177, v137
	v_pk_add_f32 v[178:179], v[178:179], 1.0 op_sel_hi:[1,0]
	v_rcp_f32_e32 v81, v146
	s_nop 0
	v_mul_f32_e32 v32, v32, v81
	v_pk_add_f32 v[194:195], v[194:195], 1.0 op_sel_hi:[1,0]
	v_rcp_f32_e32 v81, v147
	s_nop 0
	v_mul_f32_e32 v33, v33, v81
	v_pk_add_f32 v[198:199], v[198:199], 1.0 op_sel_hi:[1,0]
	v_rcp_f32_e32 v81, v178
	s_nop 0
	v_mul_f32_e32 v34, v34, v81
	v_pk_add_f32 v[200:201], v[200:201], 1.0 op_sel_hi:[1,0]
	v_rcp_f32_e32 v81, v179
	s_nop 0
	v_mul_f32_e32 v35, v35, v81
	v_mul_f32_e32 v82, 0xbfb8aa3b, v42
	v_rcp_f32_e32 v81, v194
	s_nop 0
	v_mul_f32_e32 v36, v36, v81
	v_exp_f32_e32 v202, v82
	v_rcp_f32_e32 v81, v195
	s_nop 0
	v_mul_f32_e32 v37, v37, v81
	v_pk_add_f32 v[202:203], v[202:203], 1.0 op_sel_hi:[1,0]
	v_rcp_f32_e32 v81, v198
	s_nop 0
	v_mul_f32_e32 v38, v38, v81
	v_mul_f32_e32 v82, 0xbfb8aa3b, v44
	v_rcp_f32_e32 v81, v199
	s_nop 0
	v_mul_f32_e32 v39, v39, v81
	v_exp_f32_e32 v176, v82
	v_rcp_f32_e32 v81, v200
	s_nop 0
	v_mul_f32_e32 v40, v40, v81
	v_pk_add_f32 v[176:177], v[176:177], 1.0 op_sel_hi:[1,0]
	v_rcp_f32_e32 v81, v201
	s_nop 0
	v_mul_f32_e32 v41, v41, v81
	v_mul_f32_e32 v82, 0xbfb8aa3b, v46
	v_rcp_f32_e32 v81, v202
	s_nop 0
	v_mul_f32_e32 v42, v42, v81
	v_mul_f32_e32 v83, 0xbfb8aa3b, v47
	v_rcp_f32_e32 v81, v203
	s_nop 0
	v_mul_f32_e32 v43, v43, v81
	v_exp_f32_e32 v82, v82
	v_exp_f32_e32 v83, v83
	v_rcp_f32_e32 v81, v176
	s_nop 0
	v_mul_f32_e32 v44, v44, v81
	v_pk_add_f32 v[82:83], v[82:83], 1.0 op_sel_hi:[1,0]
	v_rcp_f32_e32 v81, v177
	s_nop 0
	v_mul_f32_e32 v45, v45, v81
	v_rcp_f32_e32 v81, v82
	s_nop 0
	v_mul_f32_e32 v46, v46, v81
	v_rcp_f32_e32 v81, v83
	s_nop 0
	v_mul_f32_e32 v47, v47, v81
	v_mul_f32_e32 v81, 0xbfb8aa3b, v16
	v_exp_f32_e32 v146, v81
	v_mul_f32_e32 v81, 0xbfb8aa3b, v17
	v_exp_f32_e32 v147, v81
	v_mul_f32_e32 v81, 0xbfb8aa3b, v18
	v_exp_f32_e32 v178, v81
	v_mul_f32_e32 v81, 0xbfb8aa3b, v19
	v_exp_f32_e32 v179, v81
	v_mul_f32_e32 v81, 0xbfb8aa3b, v20
	v_exp_f32_e32 v194, v81
	v_mul_f32_e32 v81, 0xbfb8aa3b, v21
	v_exp_f32_e32 v195, v81
	v_mul_f32_e32 v81, 0xbfb8aa3b, v22
	v_exp_f32_e32 v198, v81
	v_mul_f32_e32 v81, 0xbfb8aa3b, v23
	v_exp_f32_e32 v199, v81
	v_mul_f32_e32 v81, 0xbfb8aa3b, v24
	v_exp_f32_e32 v200, v81
	v_mul_f32_e32 v81, 0xbfb8aa3b, v25
	v_pk_add_f32 v[146:147], v[146:147], 1.0 op_sel_hi:[1,0]
	v_mul_f32_e32 v135, 0xbfb8aa3b, v27
	v_exp_f32_e32 v201, v81
	v_exp_f32_e32 v203, v135
	v_mul_f32_e32 v137, 0xbfb8aa3b, v29
	v_exp_f32_e32 v177, v137
	v_pk_add_f32 v[178:179], v[178:179], 1.0 op_sel_hi:[1,0]
	v_rcp_f32_e32 v81, v146
	s_nop 0
	v_mul_f32_e32 v16, v16, v81
	v_pk_add_f32 v[194:195], v[194:195], 1.0 op_sel_hi:[1,0]
	v_rcp_f32_e32 v81, v147
	s_nop 0
	v_mul_f32_e32 v17, v17, v81
	v_pk_add_f32 v[198:199], v[198:199], 1.0 op_sel_hi:[1,0]
	v_rcp_f32_e32 v81, v178
	s_nop 0
	v_mul_f32_e32 v18, v18, v81
	v_pk_add_f32 v[200:201], v[200:201], 1.0 op_sel_hi:[1,0]
	v_rcp_f32_e32 v81, v179
	s_nop 0
	v_mul_f32_e32 v19, v19, v81
	v_mul_f32_e32 v82, 0xbfb8aa3b, v26
	v_rcp_f32_e32 v81, v194
	s_nop 0
	v_mul_f32_e32 v20, v20, v81
	v_exp_f32_e32 v202, v82
	v_rcp_f32_e32 v81, v195
	s_nop 0
	v_mul_f32_e32 v21, v21, v81
	v_pk_add_f32 v[202:203], v[202:203], 1.0 op_sel_hi:[1,0]
	v_rcp_f32_e32 v81, v198
	s_nop 0
	v_mul_f32_e32 v22, v22, v81
	v_mul_f32_e32 v82, 0xbfb8aa3b, v28
	v_rcp_f32_e32 v81, v199
	s_nop 0
	v_mul_f32_e32 v23, v23, v81
	v_exp_f32_e32 v176, v82
	v_rcp_f32_e32 v81, v200
	s_nop 0
	v_mul_f32_e32 v24, v24, v81
	v_pk_add_f32 v[176:177], v[176:177], 1.0 op_sel_hi:[1,0]
	v_rcp_f32_e32 v81, v201
	s_nop 0
	v_mul_f32_e32 v25, v25, v81
	v_mul_f32_e32 v82, 0xbfb8aa3b, v30
	v_rcp_f32_e32 v81, v202
	s_nop 0
	v_mul_f32_e32 v26, v26, v81
	v_mul_f32_e32 v83, 0xbfb8aa3b, v31
	v_rcp_f32_e32 v81, v203
	s_nop 0
	v_mul_f32_e32 v27, v27, v81
	v_exp_f32_e32 v82, v82
	v_exp_f32_e32 v83, v83
	v_rcp_f32_e32 v81, v176
	s_nop 0
	v_mul_f32_e32 v28, v28, v81
	v_pk_add_f32 v[82:83], v[82:83], 1.0 op_sel_hi:[1,0]
	v_rcp_f32_e32 v81, v177
	s_nop 0
	v_mul_f32_e32 v29, v29, v81
	v_rcp_f32_e32 v81, v82
	s_nop 0
	v_mul_f32_e32 v30, v30, v81
	v_rcp_f32_e32 v81, v83
	s_nop 0
	v_mul_f32_e32 v31, v31, v81
	v_mul_f32_e32 v81, 0xbfb8aa3b, v0
	v_exp_f32_e32 v146, v81
	v_mul_f32_e32 v81, 0xbfb8aa3b, v1
	v_exp_f32_e32 v147, v81
	v_mul_f32_e32 v81, 0xbfb8aa3b, v2
	v_exp_f32_e32 v178, v81
	v_mul_f32_e32 v81, 0xbfb8aa3b, v3
	v_exp_f32_e32 v179, v81
	v_mul_f32_e32 v81, 0xbfb8aa3b, v4
	v_exp_f32_e32 v194, v81
	v_mul_f32_e32 v81, 0xbfb8aa3b, v5
	v_exp_f32_e32 v195, v81
	v_mul_f32_e32 v81, 0xbfb8aa3b, v6
	v_exp_f32_e32 v198, v81
	v_mul_f32_e32 v81, 0xbfb8aa3b, v7
	v_exp_f32_e32 v199, v81
	v_mul_f32_e32 v81, 0xbfb8aa3b, v8
	v_exp_f32_e32 v200, v81
	v_mul_f32_e32 v81, 0xbfb8aa3b, v9
	v_pk_add_f32 v[146:147], v[146:147], 1.0 op_sel_hi:[1,0]
	v_mul_f32_e32 v135, 0xbfb8aa3b, v11
	v_exp_f32_e32 v201, v81
	v_exp_f32_e32 v203, v135
	v_mul_f32_e32 v137, 0xbfb8aa3b, v13
	v_exp_f32_e32 v177, v137
	v_pk_add_f32 v[178:179], v[178:179], 1.0 op_sel_hi:[1,0]
	v_rcp_f32_e32 v81, v146
	s_nop 0
	v_mul_f32_e32 v0, v0, v81
	v_pk_add_f32 v[194:195], v[194:195], 1.0 op_sel_hi:[1,0]
	v_rcp_f32_e32 v81, v147
	s_nop 0
	v_mul_f32_e32 v1, v1, v81
	v_pk_add_f32 v[198:199], v[198:199], 1.0 op_sel_hi:[1,0]
	v_rcp_f32_e32 v81, v178
	s_nop 0
	v_mul_f32_e32 v2, v2, v81
	v_pk_add_f32 v[200:201], v[200:201], 1.0 op_sel_hi:[1,0]
	v_rcp_f32_e32 v81, v179
	s_nop 0
	v_mul_f32_e32 v3, v3, v81
	v_mul_f32_e32 v82, 0xbfb8aa3b, v10
	v_rcp_f32_e32 v81, v194
	s_nop 0
	v_mul_f32_e32 v4, v4, v81
	v_exp_f32_e32 v202, v82
	v_rcp_f32_e32 v81, v195
	s_nop 0
	v_mul_f32_e32 v5, v5, v81
	v_pk_add_f32 v[202:203], v[202:203], 1.0 op_sel_hi:[1,0]
	v_rcp_f32_e32 v81, v198
	s_nop 0
	v_mul_f32_e32 v6, v6, v81
	v_mul_f32_e32 v82, 0xbfb8aa3b, v12
	v_rcp_f32_e32 v81, v199
	s_nop 0
	v_mul_f32_e32 v7, v7, v81
	v_exp_f32_e32 v176, v82
	v_rcp_f32_e32 v81, v200
	s_nop 0
	v_mul_f32_e32 v8, v8, v81
	v_pk_add_f32 v[176:177], v[176:177], 1.0 op_sel_hi:[1,0]
	v_rcp_f32_e32 v81, v201
	s_nop 0
	v_mul_f32_e32 v9, v9, v81
	v_mul_f32_e32 v82, 0xbfb8aa3b, v14
	v_rcp_f32_e32 v81, v202
	s_nop 0
	v_mul_f32_e32 v10, v10, v81
	v_mul_f32_e32 v83, 0xbfb8aa3b, v15
	v_rcp_f32_e32 v81, v203
	s_nop 0
	v_mul_f32_e32 v11, v11, v81
	v_exp_f32_e32 v82, v82
	v_exp_f32_e32 v83, v83
	v_rcp_f32_e32 v81, v176
	s_nop 0
	v_mul_f32_e32 v12, v12, v81
	v_pk_add_f32 v[82:83], v[82:83], 1.0 op_sel_hi:[1,0]
	v_div_scale_f32 v137, s[20:21], v82, v82, v14
	v_rcp_f32_e32 v139, v137
	v_rcp_f32_e32 v81, v177
	s_nop 0
	v_mul_f32_e32 v13, v13, v81
	v_fma_f32 v81, -v137, v139, 1.0
	v_fmac_f32_e32 v139, v81, v139
	v_div_scale_f32 v137, s[20:21], v83, v83, v15
	v_rcp_f32_e32 v141, v137
	v_rcp_f32_e32 v81, v82
	s_nop 0
	v_mul_f32_e32 v14, v14, v81
	v_fma_f32 v81, -v137, v141, 1.0
	v_fmac_f32_e32 v141, v81, v141
	v_div_scale_f32 v81, vcc, v15, v83, v15
	v_mul_f32_e32 v82, v81, v141
	v_fma_f32 v135, -v137, v82, v81
	v_fmac_f32_e32 v82, v135, v141
	v_fma_f32 v81, -v137, v82, v81
	v_div_fmas_f32 v81, v81, v141, v82
	v_div_fixup_f32 v15, v81, v83, v15
	s_branch .LBB0_173

.LBB0_539:
	s_and_b32 s0, s47, 0xffffff80
	v_add_u32_e32 v99, s0, v151
	v_or_b32_e32 v0, v99, v149
	v_ashrrev_i32_e32 v1, 31, v0
	v_lshlrev_b64 v[8:9], 7, v[0:1]
	v_lshl_add_u64 v[146:147], v[88:89], 0, v[8:9]
	global_load_dwordx4 v[0:3], v[146:147], off
	s_and_b32 s10, s87, 15
	v_lshl_or_b32 v68, s10, 13, v200
	s_waitcnt lgkmcnt(0)
	v_lshl_add_u64 v[4:5], v[72:73], 0, v[68:69]
	global_load_dwordx4 v[4:7], v[4:5], off
	v_lshl_add_u64 v[160:161], v[90:91], 0, v[8:9]
	global_load_dwordx4 v[8:11], v[160:161], off
	v_mov_b32_e32 v163, v69
	v_or_b32_e32 v162, 0x1000, v68
	v_lshl_add_u64 v[16:17], v[72:73], 0, v[162:163]
	v_lshl_add_u64 v[12:13], v[74:75], 0, v[68:69]
	global_load_dwordx4 v[16:19], v[16:17], off
	v_lshl_add_u64 v[20:21], v[74:75], 0, v[162:163]
	global_load_dwordx4 v[12:15], v[12:13], off
	s_nop 0
	global_load_dwordx4 v[64:67], v[20:21], off
	global_load_dwordx4 v[100:103], v[146:147], off offset:32
	v_lshl_add_u64 v[164:165], s[68:69], 0, v[68:69]
	v_lshl_add_u64 v[20:21], v[164:165], 0, v[92:93]
	v_lshl_add_u64 v[166:167], s[4:5], 0, v[68:69]
	global_load_dwordx4 v[104:107], v[20:21], off
	global_load_dwordx4 v[108:111], v[160:161], off offset:32
	v_lshl_add_u64 v[20:21], v[166:167], 0, v[92:93]
	global_load_dwordx4 v[112:115], v[20:21], off
	v_lshl_add_u64 v[20:21], v[76:77], 0, v[162:163]
	global_load_dwordx4 v[116:119], v[20:21], off
	v_lshl_add_u64 v[20:21], v[78:79], 0, v[162:163]
	global_load_dwordx4 v[120:123], v[20:21], off
	global_load_dwordx4 v[124:127], v[146:147], off offset:64
	v_lshl_add_u64 v[20:21], v[164:165], 0, v[94:95]
	global_load_dwordx4 v[128:131], v[20:21], off
	global_load_dwordx4 v[132:135], v[160:161], off offset:64
	v_lshl_add_u64 v[152:153], v[82:83], 0, v[162:163]
	v_lshl_or_b32 v211, s10, 6, v149
	v_lshlrev_b32_e32 v145, 2, v211
	s_lshl_b32 s70, s10, 7
	s_waitcnt vmcnt(13)
	v_mfma_f32_32x32x16_bf16 v[48:63], v[0:3], v[4:7], 0
	v_lshl_add_u64 v[4:5], v[166:167], 0, v[94:95]
	global_load_dwordx4 v[136:139], v[4:5], off
	v_lshl_add_u64 v[4:5], v[80:81], 0, v[162:163]
	global_load_dwordx4 v[140:143], v[4:5], off
	s_nop 0
	global_load_dwordx4 v[152:155], v[152:153], off
	s_nop 0
	global_load_dwordx4 v[156:159], v[146:147], off offset:96
	v_lshl_add_u64 v[146:147], v[166:167], 0, v[96:97]
	s_waitcnt vmcnt(15)
	v_mfma_f32_32x32x16_bf16 v[16:31], v[0:3], v[16:19], 0
	s_waitcnt vmcnt(14)
	v_mfma_f32_32x32x16_bf16 v[32:47], v[8:11], v[12:15], 0
	s_waitcnt vmcnt(13)
	v_mfma_f32_32x32x16_bf16 v[0:15], v[8:11], v[64:67], 0
	v_lshl_add_u64 v[64:65], v[164:165], 0, v[96:97]
	s_waitcnt vmcnt(11)
	v_mfma_f32_32x32x16_bf16 v[48:63], v[100:103], v[104:107], v[48:63]
	global_load_dwordx4 v[104:107], v[64:65], off
	s_nop 0
	global_load_dwordx4 v[64:67], v[160:161], off offset:96
	s_waitcnt vmcnt(10)
	v_mfma_f32_32x32x16_bf16 v[16:31], v[100:103], v[116:119], v[16:31]
	v_lshl_add_u64 v[100:101], v[86:87], 0, v[162:163]
	v_or_b32_e32 v102, v99, v198
	v_or_b32_e32 v170, 1, v102
	v_or_b32_e32 v160, 2, v102
	v_ashrrev_i32_e32 v171, 31, v170
	v_ashrrev_i32_e32 v161, 31, v160
	v_ashrrev_i32_e32 v103, 31, v102
	v_mfma_f32_32x32x16_bf16 v[32:47], v[108:111], v[112:115], v[32:47]
	global_load_dwordx4 v[112:115], v[146:147], off
	v_lshlrev_b64 v[180:181], 11, v[102:103]
	v_lshl_or_b32 v190, v211, 1, v180
	v_mov_b32_e32 v191, v181
	v_mov_b32_e32 v183, v181
	v_or_b32_e32 v182, 64, v190
	v_lshl_add_u64 v[192:193], s[26:27], 0, v[190:191]
	s_waitcnt vmcnt(10)
	v_mfma_f32_32x32x16_bf16 v[0:15], v[108:111], v[120:123], v[0:15]
	global_load_dwordx4 v[108:111], v[100:101], off
	v_lshl_add_u64 v[146:147], v[84:85], 0, v[162:163]
	global_load_dwordx4 v[116:119], v[146:147], off
	v_lshlrev_b64 v[100:101], 10, v[170:171]
	v_lshlrev_b64 v[120:121], 10, v[160:161]
	v_or_b32_e32 v100, v100, v211
	v_or_b32_e32 v120, v120, v211
	v_lshlrev_b64 v[176:177], 1, v[100:101]
	v_or_b32_e32 v100, 32, v100
	v_lshlrev_b64 v[166:167], 1, v[120:121]
	v_or_b32_e32 v120, 32, v120
	v_lshl_add_u64 v[122:123], s[30:31], 0, v[190:191]
	v_lshlrev_b64 v[172:173], 1, v[100:101]
	v_lshlrev_b64 v[162:163], 1, v[120:121]
	s_waitcnt vmcnt(10)
	v_mfma_f32_32x32x16_bf16 v[48:63], v[124:127], v[128:131], v[48:63]
	v_lshl_add_u64 v[184:185], s[26:27], 0, v[182:183]
	v_lshl_add_u64 v[100:101], s[30:31], 0, v[166:167]
	v_lshl_add_u64 v[120:121], s[30:31], 0, v[172:173]
	v_lshl_add_u64 v[128:129], s[30:31], 0, v[162:163]
	v_lshl_add_u64 v[178:179], s[26:27], 0, v[176:177]
	v_lshl_add_u64 v[174:175], s[26:27], 0, v[172:173]
	v_lshl_add_u64 v[168:169], s[26:27], 0, v[166:167]
	v_lshl_add_u64 v[164:165], s[26:27], 0, v[162:163]
	s_waitcnt vmcnt(8)
	v_mfma_f32_32x32x16_bf16 v[32:47], v[132:135], v[136:139], v[32:47]
	s_waitcnt vmcnt(7)
	v_mfma_f32_32x32x16_bf16 v[16:31], v[124:127], v[140:143], v[16:31]
	v_lshl_add_u64 v[124:125], s[30:31], 0, v[182:183]
	v_lshl_add_u64 v[126:127], s[30:31], 0, v[176:177]
	global_load_ushort v197, v[122:123], off
	global_load_ushort v238, v[124:125], off
	global_load_ushort v237, v[126:127], off
	global_load_ushort v234, v[120:121], off
	global_load_ushort v233, v[100:101], off
	global_load_ushort v230, v[128:129], off
	global_load_ushort v99, v[184:185], off
	global_load_ushort v188, v[192:193], off
	global_load_dword v210, v145, s[24:25]
	global_load_dword v209, v145, s[28:29]
	global_load_dword v100, v145, s[36:37]
	global_load_dword v208, v145, s[38:39]
	global_load_dword v68, v145, s[40:41]
	global_load_dword v101, v145, s[36:37] offset:128
	global_load_dword v207, v145, s[24:25] offset:128
	global_load_dword v206, v145, s[28:29] offset:128
	global_load_dword v205, v145, s[38:39] offset:128
	global_load_dword v204, v145, s[40:41] offset:128
	v_or_b32_e32 v142, 3, v102
	v_ashrrev_i32_e32 v143, 31, v142
	v_or_b32_e32 v122, 9, v102
	s_waitcnt vmcnt(24)
	v_mfma_f32_32x32x16_bf16 v[0:15], v[132:135], v[152:155], v[0:15]
	v_or_b32_e32 v132, 8, v102
	v_ashrrev_i32_e32 v133, 31, v132
	v_ashrrev_i32_e32 v123, 31, v122
	s_waitcnt vmcnt(22)
	v_mfma_f32_32x32x16_bf16 v[48:63], v[156:159], v[104:107], v[48:63]
	v_lshlrev_b64 v[104:105], 10, v[142:143]
	v_or_b32_e32 v104, v104, v211
	s_waitcnt vmcnt(9)
	s_nop 8
	v_add_f32_e32 v48, v48, v210
	v_mfma_f32_32x32x16_bf16 v[32:47], v[64:67], v[112:115], v[32:47]
	v_or_b32_e32 v112, 10, v102
	v_ashrrev_i32_e32 v113, 31, v112
	v_lshlrev_b64 v[114:115], 10, v[112:113]
	v_or_b32_e32 v114, v114, v211
	v_max_f32_e64 v252, -v48, 0
	s_waitcnt vmcnt(8)
	s_nop 5
	v_add_f32_e32 v32, v32, v209
	v_mfma_f32_32x32x16_bf16 v[16:31], v[156:159], v[116:119], v[16:31]
	v_lshlrev_b64 v[156:157], 1, v[104:105]
	v_or_b32_e32 v104, 32, v104
	v_lshlrev_b64 v[152:153], 1, v[104:105]
	v_lshlrev_b64 v[104:105], 10, v[132:133]
	v_or_b32_e32 v104, v104, v211
	v_lshlrev_b64 v[118:119], 1, v[114:115]
	v_or_b32_e32 v114, 32, v114
	v_mfma_f32_32x32x16_bf16 v[0:15], v[64:67], v[108:111], v[0:15]
	v_lshlrev_b64 v[108:109], 10, v[122:123]
	v_or_b32_e32 v108, v108, v211
	v_lshlrev_b64 v[138:139], 1, v[104:105]
	v_or_b32_e32 v104, 32, v104
	v_lshlrev_b64 v[128:129], 1, v[108:109]
	v_or_b32_e32 v108, 32, v108
	v_lshlrev_b64 v[114:115], 1, v[114:115]
	v_lshl_add_u64 v[64:65], s[30:31], 0, v[156:157]
	v_lshlrev_b64 v[134:135], 1, v[104:105]
	v_lshlrev_b64 v[124:125], 1, v[108:109]
	v_lshl_add_u64 v[186:187], s[30:31], 0, v[114:115]
	v_lshl_add_u64 v[158:159], s[26:27], 0, v[156:157]
	v_lshl_add_u64 v[154:155], s[26:27], 0, v[152:153]
	v_lshl_add_u64 v[66:67], s[30:31], 0, v[152:153]
	v_lshl_add_u64 v[140:141], s[26:27], 0, v[138:139]
	v_lshl_add_u64 v[106:107], s[30:31], 0, v[138:139]
	v_lshl_add_u64 v[136:137], s[26:27], 0, v[134:135]
	global_load_ushort v239, v[178:179], off
	global_load_ushort v240, v[174:175], off
	global_load_ushort v235, v[168:169], off
	global_load_ushort v236, v[164:165], off
	global_load_ushort v231, v[158:159], off
	global_load_ushort v232, v[154:155], off
	global_load_ushort v226, v[140:141], off
	global_load_ushort v227, v[136:137], off
	v_lshl_add_u64 v[104:105], s[30:31], 0, v[134:135]
	v_lshl_add_u64 v[110:111], s[30:31], 0, v[128:129]
	v_lshl_add_u64 v[108:109], s[30:31], 0, v[124:125]
	v_lshl_add_u64 v[146:147], s[30:31], 0, v[118:119]
	global_load_ushort v229, v[64:65], off
	global_load_ushort v228, v[66:67], off
	global_load_ushort v225, v[106:107], off
	global_load_ushort v224, v[104:105], off
	global_load_ushort v221, v[110:111], off
	global_load_ushort v220, v[108:109], off
	global_load_ushort v217, v[146:147], off
	global_load_ushort v216, v[186:187], off
	v_lshlrev_b32_e32 v186, 16, v188
	v_lshlrev_b32_e32 v187, 16, v99
	s_waitcnt vmcnt(20)
	v_pk_mul_f32 v[188:189], v[100:101], v[186:187]
	v_or_b32_e32 v66, 11, v102
	v_pk_mul_f32 v[104:105], v[188:189], v[188:189]
	v_ashrrev_i32_e32 v67, 31, v66
	v_add_f32_e32 v99, v104, v105
	v_lshlrev_b64 v[64:65], 10, v[66:67]
	v_or_b32_e32 v64, v64, v211
	v_add_f32_dpp v99, v99, v99 quad_perm:[1,0,3,2] row_mask:0xf bank_mask:0xf bound_ctrl:1
	v_lshlrev_b64 v[108:109], 1, v[64:65]
	v_or_b32_e32 v64, 32, v64
	v_add_f32_dpp v99, v99, v99 quad_perm:[2,3,0,1] row_mask:0xf bank_mask:0xf bound_ctrl:1
	v_lshlrev_b64 v[104:105], 1, v[64:65]
	v_lshl_add_u64 v[130:131], s[26:27], 0, v[128:129]
	v_add_f32_dpp v99, v99, v99 row_half_mirror row_mask:0xf bank_mask:0xf bound_ctrl:1
	v_lshl_add_u64 v[146:147], s[30:31], 0, v[108:109]
	v_lshl_add_u64 v[126:127], s[26:27], 0, v[124:125]
	v_add_f32_dpp v99, v99, v99 row_mirror row_mask:0xf bank_mask:0xf bound_ctrl:1
	ds_bpermute_b32 v145, v199, v99
	v_lshl_add_u64 v[120:121], s[26:27], 0, v[118:119]
	v_lshl_add_u64 v[116:117], s[26:27], 0, v[114:115]
	v_lshl_add_u64 v[110:111], s[26:27], 0, v[108:109]
	v_lshl_add_u64 v[106:107], s[26:27], 0, v[104:105]
	s_waitcnt lgkmcnt(0)
	v_add_f32_e32 v64, v99, v145
	v_mul_f32_e32 v65, 0x4f800000, v64
	v_cmp_gt_f32_e32 vcc, s75, v64
	global_load_ushort v222, v[130:131], off
	global_load_ushort v223, v[126:127], off
	global_load_ushort v218, v[120:121], off
	global_load_ushort v219, v[116:117], off
	global_load_ushort v214, v[110:111], off
	global_load_ushort v215, v[106:107], off
	v_cndmask_b32_e32 v64, v64, v65, vcc
	v_sqrt_f32_e32 v65, v64
	s_waitcnt vmcnt(25)
	v_add_f32_e32 v16, v16, v207
	s_waitcnt vmcnt(24)
	v_add_f32_e32 v0, v0, v206
	v_add_u32_e32 v99, -1, v65
	v_fma_f32 v145, -v99, v65, v64
	v_cmp_ge_f32_e64 s[0:1], 0, v145
	v_add_u32_e32 v145, 1, v65
	s_nop 0
	v_cndmask_b32_e64 v99, v65, v99, s[0:1]
	v_fma_f32 v65, -v145, v65, v64
	v_cmp_lt_f32_e64 s[0:1], 0, v65
	s_nop 1
	v_cndmask_b32_e64 v65, v99, v145, s[0:1]
	v_mul_f32_e32 v99, 0x37800000, v65
	v_cndmask_b32_e32 v65, v65, v99, vcc
	v_cmp_class_f32_e32 vcc, v64, v201
	s_nop 1
	v_cndmask_b32_e32 v64, v65, v64, vcc
	v_max_f32_e32 v145, 0x2b8cbccc, v64
	v_lshl_add_u64 v[64:65], s[30:31], 0, v[104:105]
	global_load_ushort v213, v[146:147], off
	global_load_ushort v212, v[64:65], off
	s_nop 1
	v_mul_f32_e64 v48, |v48|, s76
	v_exp_f32_e32 v48, v48
	v_lshl_add_u64 v[194:195], s[54:55], 0, v[190:191]
	s_nop 0
	v_add_f32_e32 v64, 1.0, v48
	v_log_f32_e32 v64, v64
	s_nop 0
	v_mul_f32_e32 v48, 0x3f317218, v64
	v_add_f32_e32 v48, v252, v48
	v_sub_f32_e32 v48, -0.5, v48
	v_rcp_f32_e32 v145, v145
	s_nop 1
	v_mul_f32_e32 v32, 0xbfb8aa3b, v32
	v_exp_f32_e32 v32, v32
	s_nop 0
	v_add_f32_e32 v32, 1.0, v32
	s_lshl_b32 s0, s10, 3
	s_add_u32 s72, s97, s0
	s_addc_u32 s73, s46, 0
	s_nop 0
	v_mul_f32_e32 v48, 0x3fb8aa3b, v48
	v_exp_f32_e32 v48, v48
	v_rcp_f32_e32 v32, v32
	s_nop 0
	v_add_f32_e32 v65, -1.0, v32
	v_fma_f32 v65, v208, v65, 1.0
	v_mul_f32_e32 v64, v188, v145
	v_mul_f32_e32 v65, v65, v186
	v_cvt_pk_bf16_f32 v48, v48, 0
	v_cvt_pk_bf16_f32 v99, v65, 0
	v_cvt_pk_bf16_f32 v186, v64, 0
	v_mul_f32_e32 v32, v32, v64
	v_lshl_add_u64 v[64:65], s[20:21], 0, v[190:191]
	global_store_short v[194:195], v48, off
	global_store_short v[192:193], v99, off
	global_store_short v[64:65], v186, off
	v_lshl_add_u64 v[64:65], s[18:19], 0, v[190:191]
	v_lshlrev_b32_e32 v191, 16, v99
	v_cvt_pk_bf16_f32 v32, v32, 0
	v_lshlrev_b32_e32 v48, 16, v48
	v_mul_f32_e64 v99, |v16|, s76
	v_exp_f32_e32 v99, v99
	global_store_short v[64:65], v32, off
	v_lshlrev_b32_e32 v190, 16, v197
	v_mov_b32_e32 v64, v99
	v_max_f32_e64 v16, -v16, 0
	v_lshlrev_b32_e32 v32, 16, v32
	v_mov_b32_e32 v241, v64
	v_fma_f32 v32, v32, v190, 0
	v_lshlrev_b32_e32 v186, 16, v186
	v_mov_b32_e32 v99, v190
	v_pk_mul_f32 v[242:243], v[98:99], v[190:191]
	v_mov_b32_e32 v242, v191
	v_mov_b32_e32 v191, v68
	v_lshl_add_u64 v[64:65], v[70:71], 0, s[70:71]
	v_lshl_add_u64 v[180:181], v[64:65], 0, v[180:181]
	v_add_f32_e32 v146, 1.0, v241
	v_log_f32_e32 v146, v146
	s_nop 0
	v_mul_f32_e32 v146, 0x3f317218, v146
	v_add_f32_e32 v16, v16, v146
	v_sub_f32_e32 v16, -0.5, v16
	s_nop 1
	v_mul_f32_e32 v48, 0xbfb8aa3b, v48
	v_exp_f32_e32 v48, v48
	s_nop 1
	v_mul_f32_e32 v0, 0xbfb8aa3b, v0
	v_exp_f32_e32 v0, v0
	s_nop 0
	v_add_f32_e32 v0, 1.0, v0
	v_div_scale_f32 v146, s[0:1], v0, v0, 1.0
	s_nop 1
	v_mul_f32_e32 v16, 0x3fb8aa3b, v16
	v_exp_f32_e32 v16, v16
	v_rcp_f32_e32 v0, v0
	v_mul_f32_e32 v99, v189, v145
	v_add_f32_e32 v145, -1.0, v0
	s_waitcnt vmcnt(29)
	v_fma_f32 v145, v205, v145, 1.0
	v_mul_f32_e32 v145, v145, v187
	v_cvt_pk_bf16_f32 v16, v16, 0
	v_cvt_pk_bf16_f32 v145, v145, 0
	v_cvt_pk_bf16_f32 v187, v99, 0
	v_mul_f32_e32 v0, v0, v99
	global_store_short v[194:195], v16, off offset:64
	global_store_short v[184:185], v145, off
	v_lshl_add_u64 v[146:147], s[20:21], 0, v[182:183]
	v_lshlrev_b32_e32 v16, 16, v16
	v_cvt_pk_bf16_f32 v0, v0, 0
	global_store_short v[146:147], v187, off
	v_lshl_add_u64 v[146:147], s[18:19], 0, v[182:183]
	global_store_short v[146:147], v0, off
	v_lshlrev_b32_e32 v147, 16, v145
	v_mul_f32_e32 v145, 0xbfb8aa3b, v16
	v_exp_f32_e32 v145, v145
	v_lshlrev_b32_e32 v146, 16, v238
	v_mov_b32_e32 v99, v146
	v_lshlrev_b32_e32 v0, 16, v0
	v_pk_mul_f32 v[182:183], v[98:99], v[146:147]
	v_fmac_f32_e32 v32, v0, v146
	v_mov_b32_e32 v0, v145
	v_pk_fma_f32 v[184:185], v[242:243], v[190:191], 0 op_sel_hi:[1,1,0]
	v_mov_b32_e32 v182, v147
	s_waitcnt vmcnt(32)
	v_mov_b32_e32 v147, v204
	v_pk_fma_f32 v[182:183], v[182:183], v[146:147], v[184:185]
	v_add_f32_dpp v32, v32, v32 quad_perm:[1,0,3,2] row_mask:0xf bank_mask:0xf bound_ctrl:1
	s_nop 0
	v_mov_b32_dpp v184, v182 quad_perm:[1,0,3,2] row_mask:0xf bank_mask:0xf bound_ctrl:1
	v_mov_b32_dpp v185, v183 quad_perm:[1,0,3,2] row_mask:0xf bank_mask:0xf bound_ctrl:1
	v_add_f32_dpp v32, v32, v32 quad_perm:[2,3,0,1] row_mask:0xf bank_mask:0xf bound_ctrl:1
	v_pk_add_f32 v[182:183], v[182:183], v[184:185]
	s_nop 0
	v_add_f32_dpp v32, v32, v32 row_half_mirror row_mask:0xf bank_mask:0xf bound_ctrl:1
	v_mov_b32_dpp v184, v182 quad_perm:[2,3,0,1] row_mask:0xf bank_mask:0xf bound_ctrl:1
	v_mov_b32_dpp v185, v183 quad_perm:[2,3,0,1] row_mask:0xf bank_mask:0xf bound_ctrl:1
	v_add_f32_dpp v32, v32, v32 row_mirror row_mask:0xf bank_mask:0xf bound_ctrl:1
	v_pk_add_f32 v[182:183], v[182:183], v[184:185]
	ds_bpermute_b32 v99, v199, v32
	s_nop 0
	v_mov_b32_dpp v184, v182 row_half_mirror row_mask:0xf bank_mask:0xf bound_ctrl:1
	v_mov_b32_dpp v185, v183 row_half_mirror row_mask:0xf bank_mask:0xf bound_ctrl:1
	v_pk_add_f32 v[182:183], v[182:183], v[184:185]
	v_lshlrev_b32_e32 v16, 16, v187
	s_waitcnt lgkmcnt(0)
	v_add_f32_e32 v32, v32, v99
	v_mov_b32_dpp v184, v182 row_mirror row_mask:0xf bank_mask:0xf bound_ctrl:1
	v_mov_b32_dpp v185, v183 row_mirror row_mask:0xf bank_mask:0xf bound_ctrl:1
	v_pk_add_f32 v[182:183], v[182:183], v[184:185]
	ds_bpermute_b32 v184, v199, v182
	ds_bpermute_b32 v185, v199, v183
	v_mul_f32_e32 v99, v32, v186
	v_mul_f32_e32 v16, v32, v16
	v_fma_f32 v48, v48, v190, -v99
	v_fma_f32 v0, v0, v146, -v16
	v_cvt_pk_bf16_f32 v48, v48, s0
	v_cvt_pk_bf16_f32 v0, v0, s0
	global_store_short v[180:181], v48, off
	global_store_short v[180:181], v0, off offset:64
	s_and_saveexec_b64 s[0:1], s[2:3]
	s_cbranch_execz .LBB0_541
	v_lshlrev_b64 v[146:147], 7, v[102:103]
	v_lshl_add_u64 v[146:147], s[72:73], 0, v[146:147]
	s_waitcnt lgkmcnt(0)
	v_pk_add_f32 v[180:181], v[182:183], v[184:185]
	global_store_dwordx2 v[146:147], v[180:181], off
.LBB0_541:
	s_or_b64 exec, exec, s[0:1]
	s_waitcnt vmcnt(32)
	v_lshlrev_b32_e32 v181, 16, v240
	v_lshlrev_b32_e32 v180, 16, v239
	v_pk_mul_f32 v[182:183], v[100:101], v[180:181]
	v_add_f32_e32 v49, v49, v210
	v_pk_mul_f32 v[146:147], v[182:183], v[182:183]
	v_add_f32_e32 v0, v146, v147
	s_nop 1
	v_add_f32_dpp v0, v0, v0 quad_perm:[1,0,3,2] row_mask:0xf bank_mask:0xf bound_ctrl:1
	s_nop 1
	v_add_f32_dpp v0, v0, v0 quad_perm:[2,3,0,1] row_mask:0xf bank_mask:0xf bound_ctrl:1
	s_nop 1
	v_add_f32_dpp v0, v0, v0 row_half_mirror row_mask:0xf bank_mask:0xf bound_ctrl:1
	v_max_f32_e64 v194, -v49, 0
	s_nop 0
	v_add_f32_dpp v0, v0, v0 row_mirror row_mask:0xf bank_mask:0xf bound_ctrl:1
	ds_bpermute_b32 v16, v199, v0
	v_add_f32_e32 v33, v33, v209
	v_add_f32_e32 v17, v17, v207
	v_add_f32_e32 v1, v1, v206
	s_waitcnt lgkmcnt(0)
	v_add_f32_e32 v0, v0, v16
	v_mul_f32_e32 v16, 0x4f800000, v0
	v_cmp_gt_f32_e32 vcc, s75, v0
	s_nop 1
	v_cndmask_b32_e32 v0, v0, v16, vcc
	v_sqrt_f32_e32 v16, v0
	s_nop 0
	v_add_u32_e32 v32, -1, v16
	v_add_u32_e32 v48, 1, v16
	v_fma_f32 v99, -v32, v16, v0
	v_fma_f32 v103, -v48, v16, v0
	v_cmp_ge_f32_e64 s[0:1], 0, v99
	s_nop 1
	v_cndmask_b32_e64 v16, v16, v32, s[0:1]
	v_cmp_lt_f32_e64 s[0:1], 0, v103
	s_nop 1
	v_cndmask_b32_e64 v16, v16, v48, s[0:1]
	v_mul_f32_e32 v32, 0x37800000, v16
	v_cndmask_b32_e32 v16, v16, v32, vcc
	v_cmp_class_f32_e32 vcc, v0, v201
	s_nop 1
	v_cndmask_b32_e32 v0, v16, v0, vcc
	v_max_f32_e32 v0, 0x2b8cbccc, v0
	v_mul_f32_e64 v145, |v49|, s76
	v_exp_f32_e32 v145, v145
	v_rcp_f32_e32 v0, v0
	s_nop 0
	v_max_f32_e64 v192, -v17, 0
	v_lshl_add_u64 v[184:185], s[54:55], 0, v[176:177]
	s_nop 0
	v_add_f32_e32 v48, 1.0, v145
	v_log_f32_e32 v48, v48
	s_nop 0
	v_mul_f32_e32 v48, 0x3f317218, v48
	v_add_f32_e32 v48, v194, v48
	v_sub_f32_e32 v48, -0.5, v48
	v_mul_f32_e32 v49, 0x3fb8aa3b, v48
	v_exp_f32_e32 v49, v49
	s_nop 0
	v_mov_b32_e32 v16, v49
	s_nop 0
	v_mul_f32_e32 v32, 0xbfb8aa3b, v33
	v_exp_f32_e32 v32, v32
	s_nop 0
	v_add_f32_e32 v32, 1.0, v32
	v_rcp_f32_e32 v32, v32
	v_mul_f32_e32 v33, v182, v0
	v_add_f32_e32 v48, -1.0, v32
	v_fma_f32 v48, v208, v48, 1.0
	v_cvt_pk_bf16_f32 v16, v16, 0
	v_mul_f32_e32 v32, v32, v33
	v_mul_f32_e32 v48, v48, v180
	v_cvt_pk_bf16_f32 v103, v33, 0
	v_cvt_pk_bf16_f32 v49, v32, 0
	v_lshl_add_u64 v[32:33], s[20:21], 0, v[176:177]
	v_lshlrev_b32_e32 v145, 16, v16
	v_cvt_pk_bf16_f32 v48, v48, 0
	global_store_short v[184:185], v16, off
	global_store_short v[178:179], v48, off
	global_store_short v[32:33], v103, off
	v_lshl_add_u64 v[32:33], s[18:19], 0, v[176:177]
	global_store_short v[32:33], v49, off
	v_lshlrev_b32_e32 v33, 16, v48
	v_lshlrev_b32_e32 v48, 16, v49
	v_lshlrev_b32_e32 v32, 16, v237
	v_mov_b32_e32 v49, v32
	v_fma_f32 v180, v48, v32, 0
	v_pk_mul_f32 v[48:49], v[48:49], v[32:33]
	v_mul_f32_e32 v0, v183, v0
	v_lshlrev_b32_e32 v103, 16, v103
	s_nop 1
	v_mul_f32_e64 v48, |v17|, s76
	v_exp_f32_e32 v48, v48
	s_nop 1
	v_add_f32_e32 v16, 1.0, v48
	v_log_f32_e32 v16, v16
	s_nop 0
	v_mul_f32_e32 v16, 0x3f317218, v16
	v_add_f32_e32 v16, v192, v16
	v_sub_f32_e32 v16, -0.5, v16
	v_mul_f32_e32 v145, 0xbfb8aa3b, v145
	v_exp_f32_e32 v145, v145
	s_nop 1
	v_mul_f32_e32 v1, 0xbfb8aa3b, v1
	v_exp_f32_e32 v1, v1
	s_nop 0
	v_add_f32_e32 v1, 1.0, v1
	v_div_scale_f32 v48, s[0:1], v1, v1, 1.0
	s_nop 1
	v_mul_f32_e32 v16, 0x3fb8aa3b, v16
	v_exp_f32_e32 v16, v16
	v_rcp_f32_e32 v1, v1
	s_nop 0
	v_add_f32_e32 v17, -1.0, v1
	v_fma_f32 v17, v205, v17, 1.0
	v_cvt_pk_bf16_f32 v48, v0, 0
	v_mul_f32_e32 v0, v1, v0
	v_mul_f32_e32 v17, v17, v181
	v_cvt_pk_bf16_f32 v16, v16, 0
	v_cvt_pk_bf16_f32 v99, v0, 0
	v_lshl_add_u64 v[0:1], s[20:21], 0, v[172:173]
	v_cvt_pk_bf16_f32 v17, v17, 0
	global_store_short v[184:185], v16, off offset:64
	global_store_short v[174:175], v17, off
	global_store_short v[0:1], v48, off
	v_lshl_add_u64 v[0:1], s[18:19], 0, v[172:173]
	v_lshlrev_b32_e32 v16, 16, v16
	global_store_short v[0:1], v99, off
	v_lshlrev_b32_e32 v147, 16, v17
	v_lshlrev_b32_e32 v0, 16, v99
	v_lshlrev_b32_e32 v146, 16, v234
	v_mov_b32_e32 v1, v146
	v_fmac_f32_e32 v180, v0, v146
	v_pk_mul_f32 v[0:1], v[0:1], v[146:147]
	s_nop 0
	v_add_f32_dpp v17, v180, v180 quad_perm:[1,0,3,2] row_mask:0xf bank_mask:0xf bound_ctrl:1
	s_nop 1
	v_add_f32_dpp v17, v17, v17 quad_perm:[2,3,0,1] row_mask:0xf bank_mask:0xf bound_ctrl:1
	v_lshlrev_b32_e32 v173, 16, v48
	v_mov_b32_e32 v48, v33
	v_add_f32_dpp v17, v17, v17 row_half_mirror row_mask:0xf bank_mask:0xf bound_ctrl:1
	v_mov_b32_e32 v33, v68
	v_mul_f32_e32 v172, 0xbfb8aa3b, v16
	v_exp_f32_e32 v172, v172
	v_add_f32_dpp v17, v17, v17 row_mirror row_mask:0xf bank_mask:0xf bound_ctrl:1
	ds_bpermute_b32 v99, v199, v17
	v_mov_b32_e32 v0, v147
	v_mov_b32_e32 v147, v204
	s_waitcnt lgkmcnt(0)
	v_add_f32_e32 v99, v17, v99
	v_pk_fma_f32 v[16:17], v[48:49], v[32:33], 0 op_sel_hi:[1,1,0]
	v_mul_f32_e32 v33, v99, v103
	v_pk_fma_f32 v[0:1], v[0:1], v[146:147], v[16:17]
	v_lshlrev_b64 v[48:49], 11, v[170:171]
	v_fma_f32 v32, v145, v32, -v33
	v_mov_b32_dpp v16, v0 quad_perm:[1,0,3,2] row_mask:0xf bank_mask:0xf bound_ctrl:1
	v_mov_b32_dpp v17, v1 quad_perm:[1,0,3,2] row_mask:0xf bank_mask:0xf bound_ctrl:1
	v_pk_add_f32 v[0:1], v[0:1], v[16:17]
	v_lshl_add_u64 v[48:49], v[64:65], 0, v[48:49]
	v_cvt_pk_bf16_f32 v32, v32, s0
	v_mov_b32_dpp v16, v0 quad_perm:[2,3,0,1] row_mask:0xf bank_mask:0xf bound_ctrl:1
	v_mov_b32_dpp v17, v1 quad_perm:[2,3,0,1] row_mask:0xf bank_mask:0xf bound_ctrl:1
	v_pk_add_f32 v[0:1], v[0:1], v[16:17]
	global_store_short v[48:49], v32, off
	v_mul_f32_e32 v32, v99, v173
	v_mov_b32_dpp v16, v0 row_half_mirror row_mask:0xf bank_mask:0xf bound_ctrl:1
	v_mov_b32_dpp v17, v1 row_half_mirror row_mask:0xf bank_mask:0xf bound_ctrl:1
	v_pk_add_f32 v[0:1], v[0:1], v[16:17]
	v_fma_f32 v32, v172, v146, -v32
	v_cvt_pk_bf16_f32 v32, v32, s0
	v_mov_b32_dpp v16, v0 row_mirror row_mask:0xf bank_mask:0xf bound_ctrl:1
	v_mov_b32_dpp v17, v1 row_mirror row_mask:0xf bank_mask:0xf bound_ctrl:1
	v_pk_add_f32 v[0:1], v[0:1], v[16:17]
	ds_bpermute_b32 v16, v199, v0
	ds_bpermute_b32 v17, v199, v1
	global_store_short v[48:49], v32, off offset:64
	s_and_saveexec_b64 s[0:1], s[2:3]
	s_cbranch_execz .LBB0_543
	v_lshlrev_b64 v[32:33], 7, v[170:171]
	v_lshl_add_u64 v[32:33], s[72:73], 0, v[32:33]
	s_waitcnt lgkmcnt(0)
	v_pk_add_f32 v[0:1], v[0:1], v[16:17]
	global_store_dwordx2 v[32:33], v[0:1], off
.LBB0_543:
	s_or_b64 exec, exec, s[0:1]
	s_waitcnt vmcnt(40)
	v_lshlrev_b32_e32 v1, 16, v236
	v_lshlrev_b32_e32 v0, 16, v235
	s_waitcnt lgkmcnt(0)
	v_pk_mul_f32 v[16:17], v[100:101], v[0:1]
	v_add_f32_e32 v34, v34, v209
	v_pk_mul_f32 v[32:33], v[16:17], v[16:17]
	v_add_f32_e32 v18, v18, v207
	v_add_f32_e32 v32, v32, v33
	v_add_f32_e32 v2, v2, v206
	s_nop 0
	v_add_f32_dpp v32, v32, v32 quad_perm:[1,0,3,2] row_mask:0xf bank_mask:0xf bound_ctrl:1
	s_nop 1
	v_add_f32_dpp v32, v32, v32 quad_perm:[2,3,0,1] row_mask:0xf bank_mask:0xf bound_ctrl:1
	s_nop 1
	v_add_f32_dpp v32, v32, v32 row_half_mirror row_mask:0xf bank_mask:0xf bound_ctrl:1
	s_nop 1
	v_add_f32_dpp v32, v32, v32 row_mirror row_mask:0xf bank_mask:0xf bound_ctrl:1
	ds_bpermute_b32 v33, v199, v32
	s_waitcnt lgkmcnt(0)
	v_add_f32_e32 v32, v32, v33
	v_mul_f32_e32 v33, 0x4f800000, v32
	v_cmp_gt_f32_e32 vcc, s75, v32
	s_nop 1
	v_cndmask_b32_e32 v32, v32, v33, vcc
	v_sqrt_f32_e32 v33, v32
	s_nop 0
	v_add_u32_e32 v48, -1, v33
	v_add_u32_e32 v49, 1, v33
	v_fma_f32 v99, -v48, v33, v32
	v_fma_f32 v103, -v49, v33, v32
	v_cmp_ge_f32_e64 s[0:1], 0, v99
	s_nop 1
	v_cndmask_b32_e64 v33, v33, v48, s[0:1]
	v_cmp_lt_f32_e64 s[0:1], 0, v103
	s_nop 1
	v_cndmask_b32_e64 v33, v33, v49, s[0:1]
	v_mul_f32_e32 v48, 0x37800000, v33
	v_cndmask_b32_e32 v33, v33, v48, vcc
	v_cmp_class_f32_e32 vcc, v32, v201
	v_add_f32_e32 v49, v50, v210
	s_nop 0
	v_cndmask_b32_e32 v32, v33, v32, vcc
	v_max_f32_e32 v103, 0x2b8cbccc, v32
	v_max_f32_e64 v180, -v49, 0
	s_nop 0
	s_nop 1
	v_mul_f32_e64 v50, |v49|, s76
	v_exp_f32_e32 v50, v50
	v_lshl_add_u64 v[170:171], s[54:55], 0, v[166:167]
	s_nop 0
	v_add_f32_e32 v32, 1.0, v50
	v_log_f32_e32 v32, v32
	s_nop 0
	v_mul_f32_e32 v32, 0x3f317218, v32
	v_add_f32_e32 v32, v180, v32
	v_sub_f32_e32 v32, -0.5, v32
	v_rcp_f32_e32 v103, v103
	s_nop 0
	v_mul_f32_e32 v16, v16, v103
	v_max_f32_e64 v180, -v18, 0
	v_mul_f32_e32 v34, 0xbfb8aa3b, v34
	v_exp_f32_e32 v34, v34
	s_nop 0
	v_add_f32_e32 v34, 1.0, v34
	s_nop 1
	v_mul_f32_e32 v32, 0x3fb8aa3b, v32
	v_exp_f32_e32 v32, v32
	v_rcp_f32_e32 v33, v34
	s_nop 0
	v_add_f32_e32 v34, -1.0, v33
	v_fma_f32 v34, v208, v34, 1.0
	v_mul_f32_e32 v0, v34, v0
	v_cvt_pk_bf16_f32 v34, v32, 0
	v_cvt_pk_bf16_f32 v50, v16, 0
	v_mul_f32_e32 v16, v33, v16
	v_lshl_add_u64 v[32:33], s[20:21], 0, v[166:167]
	v_cvt_pk_bf16_f32 v0, v0, 0
	v_cvt_pk_bf16_f32 v16, v16, 0
	global_store_short v[170:171], v34, off
	global_store_short v[168:169], v0, off
	global_store_short v[32:33], v50, off
	v_lshl_add_u64 v[32:33], s[18:19], 0, v[166:167]
	global_store_short v[32:33], v16, off
	v_lshlrev_b32_e32 v33, 16, v0
	v_lshlrev_b32_e32 v0, 16, v16
	v_lshlrev_b32_e32 v16, 16, v34
	v_mul_f32_e32 v34, 0xbfb8aa3b, v16
	v_fma_f32 v48, v16, s76, -v34
	v_fmac_f32_e32 v48, 0xb2a5705f, v16
	v_mul_f32_e32 v34, 0xbfb8aa3b, v16
	v_exp_f32_e32 v34, v34
	v_lshlrev_b32_e32 v32, 16, v233
	v_mov_b32_e32 v49, v32
	v_fma_f32 v145, v0, v32, 0
	v_pk_mul_f32 v[48:49], v[48:49], v[32:33]
	v_mov_b32_e32 v0, v34
	v_lshlrev_b32_e32 v50, 16, v50
	s_nop 1
	v_mul_f32_e64 v18, |v18|, s76
	v_exp_f32_e32 v18, v18
	s_nop 1
	v_add_f32_e32 v34, 1.0, v18
	v_log_f32_e32 v34, v34
	s_nop 0
	v_mul_f32_e32 v18, 0x3f317218, v34
	v_add_f32_e32 v18, v180, v18
	v_sub_f32_e32 v18, -0.5, v18
	v_mul_f32_e32 v34, 0x3fb8aa3b, v18
	v_exp_f32_e32 v34, v34
	v_mov_b32_e32 v166, v0
	v_mov_b32_e32 v0, v34
	v_lshlrev_b32_e32 v146, 16, v230
	s_nop 1
	v_mul_f32_e32 v2, 0xbfb8aa3b, v2
	v_exp_f32_e32 v2, v2
	s_nop 0
	v_add_f32_e32 v2, 1.0, v2
	v_div_scale_f32 v16, s[0:1], v2, v2, 1.0
	v_rcp_f32_e32 v2, v2
	v_mul_f32_e32 v16, v17, v103
	v_add_f32_e32 v17, -1.0, v2
	v_fma_f32 v17, v205, v17, 1.0
	v_mul_f32_e32 v1, v17, v1
	v_cvt_pk_bf16_f32 v17, v0, 0
	v_mul_f32_e32 v0, v2, v16
	v_cvt_pk_bf16_f32 v18, v1, 0
	v_cvt_pk_bf16_f32 v34, v16, 0
	v_cvt_pk_bf16_f32 v2, v0, 0
	v_lshl_add_u64 v[0:1], s[20:21], 0, v[162:163]
	global_store_short v[170:171], v17, off offset:64
	global_store_short v[164:165], v18, off
	global_store_short v[0:1], v34, off
	v_lshl_add_u64 v[0:1], s[18:19], 0, v[162:163]
	global_store_short v[0:1], v2, off
	v_lshlrev_b32_e32 v0, 16, v2
	v_lshlrev_b32_e32 v2, 16, v17
	v_lshlrev_b32_e32 v147, 16, v18
	v_mov_b32_e32 v1, v146
	v_fmac_f32_e32 v145, v0, v146
	v_pk_mul_f32 v[0:1], v[0:1], v[146:147]
	s_nop 0
	v_add_f32_dpp v16, v145, v145 quad_perm:[1,0,3,2] row_mask:0xf bank_mask:0xf bound_ctrl:1
	s_nop 1
	v_add_f32_dpp v16, v16, v16 quad_perm:[2,3,0,1] row_mask:0xf bank_mask:0xf bound_ctrl:1
	v_mov_b32_e32 v48, v33
	v_mov_b32_e32 v33, v68
	v_add_f32_dpp v16, v16, v16 row_half_mirror row_mask:0xf bank_mask:0xf bound_ctrl:1
	v_mul_f32_e32 v2, 0xbfb8aa3b, v2
	v_exp_f32_e32 v2, v2
	v_lshlrev_b32_e32 v18, 16, v34
	v_add_f32_dpp v16, v16, v16 row_mirror row_mask:0xf bank_mask:0xf bound_ctrl:1
	ds_bpermute_b32 v17, v199, v16
	v_mov_b32_e32 v0, v147
	v_mov_b32_e32 v147, v204
	s_waitcnt lgkmcnt(0)
	v_add_f32_e32 v34, v16, v17
	v_pk_fma_f32 v[16:17], v[48:49], v[32:33], 0 op_sel_hi:[1,1,0]
	v_mul_f32_e32 v33, v34, v50
	v_pk_fma_f32 v[0:1], v[0:1], v[146:147], v[16:17]
	v_mul_f32_e32 v18, v34, v18
	v_lshlrev_b64 v[48:49], 11, v[160:161]
	v_mov_b32_dpp v16, v0 quad_perm:[1,0,3,2] row_mask:0xf bank_mask:0xf bound_ctrl:1
	v_mov_b32_dpp v17, v1 quad_perm:[1,0,3,2] row_mask:0xf bank_mask:0xf bound_ctrl:1
	v_pk_add_f32 v[0:1], v[0:1], v[16:17]
	v_fma_f32 v32, v166, v32, -v33
	v_fma_f32 v2, v2, v146, -v18
	v_mov_b32_dpp v16, v0 quad_perm:[2,3,0,1] row_mask:0xf bank_mask:0xf bound_ctrl:1
	v_mov_b32_dpp v17, v1 quad_perm:[2,3,0,1] row_mask:0xf bank_mask:0xf bound_ctrl:1
	v_pk_add_f32 v[0:1], v[0:1], v[16:17]
	v_lshl_add_u64 v[48:49], v[64:65], 0, v[48:49]
	v_cvt_pk_bf16_f32 v32, v32, s0
	v_mov_b32_dpp v16, v0 row_half_mirror row_mask:0xf bank_mask:0xf bound_ctrl:1
	v_mov_b32_dpp v17, v1 row_half_mirror row_mask:0xf bank_mask:0xf bound_ctrl:1
	v_pk_add_f32 v[0:1], v[0:1], v[16:17]
	v_cvt_pk_bf16_f32 v2, v2, s0
	global_store_short v[48:49], v32, off
	v_mov_b32_dpp v16, v0 row_mirror row_mask:0xf bank_mask:0xf bound_ctrl:1
	v_mov_b32_dpp v17, v1 row_mirror row_mask:0xf bank_mask:0xf bound_ctrl:1
	v_pk_add_f32 v[0:1], v[0:1], v[16:17]
	ds_bpermute_b32 v16, v199, v0
	ds_bpermute_b32 v17, v199, v1
	global_store_short v[48:49], v2, off offset:64
	s_and_saveexec_b64 s[0:1], s[2:3]
	s_cbranch_execz .LBB0_545
	v_lshlrev_b64 v[32:33], 7, v[160:161]
	v_lshl_add_u64 v[32:33], s[72:73], 0, v[32:33]
	s_waitcnt lgkmcnt(0)
	v_pk_add_f32 v[0:1], v[0:1], v[16:17]
	global_store_dwordx2 v[32:33], v[0:1], off
.LBB0_545:
	s_or_b64 exec, exec, s[0:1]
	s_waitcnt vmcnt(48)
	v_lshlrev_b32_e32 v1, 16, v232
	v_lshlrev_b32_e32 v0, 16, v231
	s_waitcnt lgkmcnt(0)
	v_pk_mul_f32 v[16:17], v[100:101], v[0:1]
	v_add_f32_e32 v35, v35, v209
	v_pk_mul_f32 v[32:33], v[16:17], v[16:17]
	v_add_f32_e32 v3, v3, v206
	v_add_f32_e32 v2, v32, v33
	s_nop 1
	v_add_f32_dpp v2, v2, v2 quad_perm:[1,0,3,2] row_mask:0xf bank_mask:0xf bound_ctrl:1
	s_nop 1
	v_add_f32_dpp v2, v2, v2 quad_perm:[2,3,0,1] row_mask:0xf bank_mask:0xf bound_ctrl:1
	s_nop 1
	v_add_f32_dpp v2, v2, v2 row_half_mirror row_mask:0xf bank_mask:0xf bound_ctrl:1
	s_nop 1
	v_add_f32_dpp v2, v2, v2 row_mirror row_mask:0xf bank_mask:0xf bound_ctrl:1
	ds_bpermute_b32 v18, v199, v2
	s_waitcnt lgkmcnt(0)
	v_add_f32_e32 v2, v2, v18
	v_mul_f32_e32 v18, 0x4f800000, v2
	v_cmp_gt_f32_e32 vcc, s75, v2
	s_nop 1
	v_cndmask_b32_e32 v2, v2, v18, vcc
	v_sqrt_f32_e32 v18, v2
	s_nop 0
	v_add_u32_e32 v32, -1, v18
	v_add_u32_e32 v33, 1, v18
	v_fma_f32 v34, -v32, v18, v2
	v_fma_f32 v48, -v33, v18, v2
	v_cmp_ge_f32_e64 s[0:1], 0, v34
	s_nop 1
	v_cndmask_b32_e64 v18, v18, v32, s[0:1]
	v_cmp_lt_f32_e64 s[0:1], 0, v48
	v_add_f32_e32 v48, v51, v210
	s_nop 0
	v_cndmask_b32_e64 v18, v18, v33, s[0:1]
	v_mul_f32_e32 v32, 0x37800000, v18
	v_cndmask_b32_e32 v18, v18, v32, vcc
	v_cmp_class_f32_e32 vcc, v2, v201
	s_nop 1
	v_cndmask_b32_e32 v2, v18, v2, vcc
	v_max_f32_e32 v2, 0x2b8cbccc, v2
	v_max_f32_e64 v145, -v48, 0
	v_rcp_f32_e32 v2, v2
	v_mul_f32_e64 v166, |v48|, s76
	v_exp_f32_e32 v166, v166
	v_mul_f32_e32 v16, v16, v2
	v_cvt_pk_bf16_f32 v103, v16, 0
	v_mul_f32_e32 v2, v17, v2
	s_nop 1
	v_add_f32_e32 v32, 1.0, v166
	v_log_f32_e32 v32, v32
	s_nop 0
	v_mul_f32_e32 v32, 0x3f317218, v32
	v_add_f32_e32 v32, v145, v32
	v_sub_f32_e32 v32, -0.5, v32
	v_mul_f32_e32 v33, 0x3fb8aa3b, v32
	v_exp_f32_e32 v33, v33
	s_nop 0
	v_mov_b32_e32 v18, v33
	s_nop 1
	v_mul_f32_e32 v33, 0xbfb8aa3b, v35
	v_exp_f32_e32 v33, v33
	s_nop 0
	v_add_f32_e32 v33, 1.0, v33
	v_rcp_f32_e32 v32, v33
	s_nop 0
	v_add_f32_e32 v33, -1.0, v32
	v_fma_f32 v33, v208, v33, 1.0
	v_mul_f32_e32 v0, v33, v0
	v_cvt_pk_bf16_f32 v18, v18, 0
	v_mul_f32_e32 v16, v32, v16
	v_lshl_add_u64 v[48:49], s[54:55], 0, v[156:157]
	v_lshl_add_u64 v[32:33], s[20:21], 0, v[156:157]
	v_cvt_pk_bf16_f32 v0, v0, 0
	v_cvt_pk_bf16_f32 v16, v16, 0
	global_store_short v[48:49], v18, off
	global_store_short v[158:159], v0, off
	global_store_short v[32:33], v103, off
	v_lshl_add_u64 v[32:33], s[18:19], 0, v[156:157]
	global_store_short v[32:33], v16, off
	v_lshlrev_b32_e32 v33, 16, v0
	v_lshlrev_b32_e32 v0, 16, v16
	v_lshlrev_b32_e32 v16, 16, v18
	v_mul_f32_e32 v18, 0xbfb8aa3b, v16
	v_fma_f32 v34, v16, s76, -v18
	v_fmac_f32_e32 v34, 0xb2a5705f, v16
	v_mul_f32_e32 v18, 0xbfb8aa3b, v16
	v_exp_f32_e32 v18, v18
	s_waitcnt vmcnt(49)
	v_lshlrev_b32_e32 v32, 16, v229
	v_fma_f32 v145, v0, v32, 0
	v_mov_b32_e32 v35, v32
	v_mov_b32_e32 v0, v18
	v_add_f32_e32 v18, v19, v207
	v_pk_mul_f32 v[34:35], v[34:35], v[32:33]
	v_max_f32_e64 v164, -v18, 0
	v_lshlrev_b32_e32 v103, 16, v103
	s_nop 1
	v_mul_f32_e64 v34, |v18|, s76
	v_exp_f32_e32 v34, v34
	s_nop 1
	v_add_f32_e32 v18, 1.0, v34
	v_log_f32_e32 v18, v18
	s_nop 0
	v_mul_f32_e32 v18, 0x3f317218, v18
	v_add_f32_e32 v18, v164, v18
	v_sub_f32_e32 v18, -0.5, v18
	v_mul_f32_e32 v19, 0x3fb8aa3b, v18
	v_exp_f32_e32 v19, v19
	v_mov_b32_e32 v99, v0
	v_mov_b32_e32 v0, v19
	s_nop 0
	s_nop 1
	v_mul_f32_e32 v3, 0xbfb8aa3b, v3
	v_exp_f32_e32 v3, v3
	s_nop 0
	v_add_f32_e32 v3, 1.0, v3
	v_div_scale_f32 v16, s[0:1], v3, v3, 1.0
	v_rcp_f32_e32 v3, v3
	s_nop 0
	v_add_f32_e32 v16, -1.0, v3
	v_fma_f32 v16, v205, v16, 1.0
	v_mul_f32_e32 v1, v16, v1
	v_cvt_pk_bf16_f32 v18, v0, 0
	v_mul_f32_e32 v0, v3, v2
	v_cvt_pk_bf16_f32 v16, v1, 0
	v_cvt_pk_bf16_f32 v19, v2, 0
	v_cvt_pk_bf16_f32 v2, v0, 0
	v_lshl_add_u64 v[0:1], s[20:21], 0, v[152:153]
	global_store_short v[48:49], v18, off offset:64
	global_store_short v[154:155], v16, off
	global_store_short v[0:1], v19, off
	v_lshl_add_u64 v[0:1], s[18:19], 0, v[152:153]
	global_store_short v[0:1], v2, off
	v_lshlrev_b32_e32 v0, 16, v2
	v_lshlrev_b32_e32 v2, 16, v18
	v_lshlrev_b32_e32 v17, 16, v16
	s_waitcnt vmcnt(52)
	v_lshlrev_b32_e32 v16, 16, v228
	v_mov_b32_e32 v1, v16
	v_fmac_f32_e32 v145, v0, v16
	v_pk_mul_f32 v[0:1], v[0:1], v[16:17]
	s_nop 0
	v_add_f32_dpp v3, v145, v145 quad_perm:[1,0,3,2] row_mask:0xf bank_mask:0xf bound_ctrl:1
	s_nop 1
	v_add_f32_dpp v3, v3, v3 quad_perm:[2,3,0,1] row_mask:0xf bank_mask:0xf bound_ctrl:1
	v_mov_b32_e32 v34, v33
	v_mov_b32_e32 v33, v68
	v_add_f32_dpp v3, v3, v3 row_half_mirror row_mask:0xf bank_mask:0xf bound_ctrl:1
	v_mul_f32_e32 v48, 0xbfb8aa3b, v2
	v_exp_f32_e32 v48, v48
	v_mov_b32_e32 v0, v17
	v_add_f32_dpp v3, v3, v3 row_mirror row_mask:0xf bank_mask:0xf bound_ctrl:1
	ds_bpermute_b32 v18, v199, v3
	v_mov_b32_e32 v17, v204
	v_lshlrev_b32_e32 v49, 16, v19
	s_waitcnt lgkmcnt(0)
	v_add_f32_e32 v50, v3, v18
	v_pk_fma_f32 v[2:3], v[34:35], v[32:33], 0 op_sel_hi:[1,1,0]
	v_lshlrev_b64 v[18:19], 11, v[142:143]
	v_pk_fma_f32 v[0:1], v[0:1], v[16:17], v[2:3]
	v_mul_f32_e32 v17, v50, v103
	v_fma_f32 v17, v99, v32, -v17
	v_mov_b32_dpp v2, v0 quad_perm:[1,0,3,2] row_mask:0xf bank_mask:0xf bound_ctrl:1
	v_mov_b32_dpp v3, v1 quad_perm:[1,0,3,2] row_mask:0xf bank_mask:0xf bound_ctrl:1
	v_pk_add_f32 v[0:1], v[0:1], v[2:3]
	v_lshl_add_u64 v[18:19], v[64:65], 0, v[18:19]
	v_cvt_pk_bf16_f32 v17, v17, s0
	v_mov_b32_dpp v2, v0 quad_perm:[2,3,0,1] row_mask:0xf bank_mask:0xf bound_ctrl:1
	v_mov_b32_dpp v3, v1 quad_perm:[2,3,0,1] row_mask:0xf bank_mask:0xf bound_ctrl:1
	v_pk_add_f32 v[0:1], v[0:1], v[2:3]
	global_store_short v[18:19], v17, off
	v_mul_f32_e32 v17, v50, v49
	v_mov_b32_dpp v2, v0 row_half_mirror row_mask:0xf bank_mask:0xf bound_ctrl:1
	v_mov_b32_dpp v3, v1 row_half_mirror row_mask:0xf bank_mask:0xf bound_ctrl:1
	v_pk_add_f32 v[0:1], v[0:1], v[2:3]
	v_fma_f32 v16, v48, v16, -v17
	v_cvt_pk_bf16_f32 v16, v16, s0
	v_mov_b32_dpp v2, v0 row_mirror row_mask:0xf bank_mask:0xf bound_ctrl:1
	v_mov_b32_dpp v3, v1 row_mirror row_mask:0xf bank_mask:0xf bound_ctrl:1
	v_pk_add_f32 v[0:1], v[0:1], v[2:3]
	ds_bpermute_b32 v2, v199, v0
	ds_bpermute_b32 v3, v199, v1
	global_store_short v[18:19], v16, off offset:64
	s_and_saveexec_b64 s[0:1], s[2:3]
	s_cbranch_execz .LBB0_547
	v_lshlrev_b64 v[16:17], 7, v[142:143]
	v_lshl_add_u64 v[16:17], s[72:73], 0, v[16:17]
	s_waitcnt lgkmcnt(0)
	v_pk_add_f32 v[0:1], v[0:1], v[2:3]
	global_store_dwordx2 v[16:17], v[0:1], off
.LBB0_547:
	s_or_b64 exec, exec, s[0:1]
	v_lshlrev_b32_e32 v1, 16, v227
	v_lshlrev_b32_e32 v0, 16, v226
	s_waitcnt lgkmcnt(0)
	v_pk_mul_f32 v[2:3], v[100:101], v[0:1]
	v_add_f32_e32 v4, v4, v206
	v_pk_mul_f32 v[16:17], v[2:3], v[2:3]
	s_nop 0
	v_add_f32_e32 v16, v16, v17
	s_nop 1
	v_add_f32_dpp v16, v16, v16 quad_perm:[1,0,3,2] row_mask:0xf bank_mask:0xf bound_ctrl:1
	s_nop 1
	v_add_f32_dpp v16, v16, v16 quad_perm:[2,3,0,1] row_mask:0xf bank_mask:0xf bound_ctrl:1
	s_nop 1
	v_add_f32_dpp v16, v16, v16 row_half_mirror row_mask:0xf bank_mask:0xf bound_ctrl:1
	s_nop 1
	v_add_f32_dpp v16, v16, v16 row_mirror row_mask:0xf bank_mask:0xf bound_ctrl:1
	ds_bpermute_b32 v17, v199, v16
	s_waitcnt lgkmcnt(0)
	v_add_f32_e32 v16, v16, v17
	v_mul_f32_e32 v17, 0x4f800000, v16
	v_cmp_gt_f32_e32 vcc, s75, v16
	s_nop 1
	v_cndmask_b32_e32 v16, v16, v17, vcc
	v_sqrt_f32_e32 v17, v16
	s_nop 0
	v_add_u32_e32 v18, -1, v17
	v_add_u32_e32 v19, 1, v17
	v_fma_f32 v32, -v18, v17, v16
	v_fma_f32 v33, -v19, v17, v16
	v_cmp_ge_f32_e64 s[0:1], 0, v32
	s_nop 1
	v_cndmask_b32_e64 v17, v17, v18, s[0:1]
	v_cmp_lt_f32_e64 s[0:1], 0, v33
	s_nop 1
	v_cndmask_b32_e64 v17, v17, v19, s[0:1]
	v_mul_f32_e32 v18, 0x37800000, v17
	v_cndmask_b32_e32 v17, v17, v18, vcc
	v_cmp_class_f32_e32 vcc, v16, v201
	v_add_f32_e32 v19, v52, v210
	s_nop 0
	v_cndmask_b32_e32 v16, v17, v16, vcc
	v_max_f32_e32 v103, 0x2b8cbccc, v16
	v_max_f32_e64 v147, -v19, 0
	s_nop 0
	s_nop 1
	v_mul_f32_e64 v152, |v19|, s76
	v_exp_f32_e32 v152, v152
	s_nop 1
	v_add_f32_e32 v16, 1.0, v152
	v_log_f32_e32 v16, v16
	s_nop 0
	v_mul_f32_e32 v16, 0x3f317218, v16
	v_add_f32_e32 v16, v147, v16
	v_sub_f32_e32 v16, -0.5, v16
	v_add_f32_e32 v19, v36, v209
	v_rcp_f32_e32 v36, v103
	s_nop 0
	v_mul_f32_e32 v2, v2, v36
	v_cvt_pk_bf16_f32 v52, v2, 0
	v_mul_f32_e32 v18, 0xbfb8aa3b, v19
	v_exp_f32_e32 v18, v18
	s_nop 0
	v_add_f32_e32 v18, 1.0, v18
	v_mul_f32_e32 v3, v3, v36
	s_nop 0
	s_nop 1
	v_mul_f32_e32 v16, 0x3fb8aa3b, v16
	v_exp_f32_e32 v16, v16
	v_rcp_f32_e32 v17, v18
	s_nop 0
	v_add_f32_e32 v18, -1.0, v17
	v_fma_f32 v18, v208, v18, 1.0
	v_mul_f32_e32 v0, v18, v0
	v_cvt_pk_bf16_f32 v18, v16, 0
	v_mul_f32_e32 v2, v17, v2
	v_lshl_add_u64 v[32:33], s[54:55], 0, v[138:139]
	v_lshl_add_u64 v[16:17], s[20:21], 0, v[138:139]
	v_cvt_pk_bf16_f32 v0, v0, 0
	v_cvt_pk_bf16_f32 v2, v2, 0
	global_store_short v[32:33], v18, off
	global_store_short v[140:141], v0, off
	global_store_short v[16:17], v52, off
	v_lshl_add_u64 v[16:17], s[18:19], 0, v[138:139]
	global_store_short v[16:17], v2, off
	v_lshlrev_b32_e32 v17, 16, v0
	v_lshlrev_b32_e32 v0, 16, v2
	v_lshlrev_b32_e32 v2, 16, v18
	v_mul_f32_e32 v18, 0xbfb8aa3b, v2
	v_fma_f32 v19, v2, s76, -v18
	v_rndne_f32_e32 v34, v18
	v_fmac_f32_e32 v19, 0xb2a5705f, v2
	v_sub_f32_e32 v18, v18, v34
	s_waitcnt vmcnt(57)
	v_lshlrev_b32_e32 v16, 16, v225
	v_add_f32_e32 v18, v18, v19
	v_mul_f32_e32 v35, 0xbfb8aa3b, v2
	v_exp_f32_e32 v35, v35
	v_mov_b32_e32 v19, v16
	v_pk_mul_f32 v[18:19], v[18:19], v[16:17]
	v_fma_f32 v103, v0, v16, 0
	v_add_f32_e32 v18, v20, v207
	v_mov_b32_e32 v0, v35
	v_max_f32_e64 v145, -v18, 0
	s_nop 1
	v_mul_f32_e64 v18, |v18|, s76
	v_exp_f32_e32 v18, v18
	v_lshlrev_b32_e32 v50, 16, v52
	s_nop 0
	v_add_f32_e32 v20, 1.0, v18
	v_log_f32_e32 v20, v20
	s_nop 0
	v_mul_f32_e32 v18, 0x3f317218, v20
	v_add_f32_e32 v18, v145, v18
	v_sub_f32_e32 v18, -0.5, v18
	v_mul_f32_e32 v20, 0x3fb8aa3b, v18
	v_exp_f32_e32 v20, v20
	v_mov_b32_e32 v49, v0
	v_mov_b32_e32 v0, v20
	s_nop 0
	s_nop 1
	v_mul_f32_e32 v2, 0xbfb8aa3b, v4
	v_exp_f32_e32 v2, v2
	s_nop 0
	v_add_f32_e32 v2, 1.0, v2
	v_div_scale_f32 v4, s[0:1], v2, v2, 1.0
	v_rcp_f32_e32 v2, v2
	s_nop 0
	v_add_f32_e32 v4, -1.0, v2
	v_fma_f32 v4, v205, v4, 1.0
	v_mul_f32_e32 v1, v4, v1
	v_cvt_pk_bf16_f32 v4, v0, 0
	v_mul_f32_e32 v0, v2, v3
	v_cvt_pk_bf16_f32 v18, v1, 0
	v_cvt_pk_bf16_f32 v20, v3, 0
	v_cvt_pk_bf16_f32 v2, v0, 0
	v_lshl_add_u64 v[0:1], s[20:21], 0, v[134:135]
	global_store_short v[32:33], v4, off offset:64
	global_store_short v[136:137], v18, off
	global_store_short v[0:1], v20, off
	v_lshl_add_u64 v[0:1], s[18:19], 0, v[134:135]
	global_store_short v[0:1], v2, off
	v_lshlrev_b32_e32 v0, 16, v2
	v_lshlrev_b32_e32 v2, 16, v4
	s_waitcnt vmcnt(60)
	v_lshlrev_b32_e32 v32, 16, v224
	v_lshlrev_b32_e32 v33, 16, v18
	v_mov_b32_e32 v1, v32
	v_fmac_f32_e32 v103, v0, v32
	v_pk_mul_f32 v[0:1], v[0:1], v[32:33]
	s_nop 0
	v_add_f32_dpp v3, v103, v103 quad_perm:[1,0,3,2] row_mask:0xf bank_mask:0xf bound_ctrl:1
	s_nop 1
	v_add_f32_dpp v3, v3, v3 quad_perm:[2,3,0,1] row_mask:0xf bank_mask:0xf bound_ctrl:1
	v_mov_b32_e32 v18, v17
	v_mov_b32_e32 v17, v68
	v_add_f32_dpp v3, v3, v3 row_half_mirror row_mask:0xf bank_mask:0xf bound_ctrl:1
	v_mul_f32_e32 v34, 0xbfb8aa3b, v2
	v_exp_f32_e32 v34, v34
	v_mov_b32_e32 v0, v33
	v_add_f32_dpp v3, v3, v3 row_mirror row_mask:0xf bank_mask:0xf bound_ctrl:1
	ds_bpermute_b32 v4, v199, v3
	v_mov_b32_e32 v33, v204
	v_lshlrev_b32_e32 v20, 16, v20
	s_waitcnt lgkmcnt(0)
	v_add_f32_e32 v4, v3, v4
	v_pk_fma_f32 v[2:3], v[18:19], v[16:17], 0 op_sel_hi:[1,1,0]
	v_mul_f32_e32 v17, v4, v50
	v_pk_fma_f32 v[0:1], v[0:1], v[32:33], v[2:3]
	v_mul_f32_e32 v4, v4, v20
	v_lshlrev_b64 v[18:19], 11, v[132:133]
	v_mov_b32_dpp v2, v0 quad_perm:[1,0,3,2] row_mask:0xf bank_mask:0xf bound_ctrl:1
	v_mov_b32_dpp v3, v1 quad_perm:[1,0,3,2] row_mask:0xf bank_mask:0xf bound_ctrl:1
	v_pk_add_f32 v[0:1], v[0:1], v[2:3]
	v_fma_f32 v16, v49, v16, -v17
	v_fma_f32 v4, v34, v32, -v4
	v_mov_b32_dpp v2, v0 quad_perm:[2,3,0,1] row_mask:0xf bank_mask:0xf bound_ctrl:1
	v_mov_b32_dpp v3, v1 quad_perm:[2,3,0,1] row_mask:0xf bank_mask:0xf bound_ctrl:1
	v_pk_add_f32 v[0:1], v[0:1], v[2:3]
	v_lshl_add_u64 v[18:19], v[64:65], 0, v[18:19]
	v_cvt_pk_bf16_f32 v16, v16, s0
	v_mov_b32_dpp v2, v0 row_half_mirror row_mask:0xf bank_mask:0xf bound_ctrl:1
	v_mov_b32_dpp v3, v1 row_half_mirror row_mask:0xf bank_mask:0xf bound_ctrl:1
	v_pk_add_f32 v[0:1], v[0:1], v[2:3]
	v_cvt_pk_bf16_f32 v4, v4, s0
	global_store_short v[18:19], v16, off
	v_mov_b32_dpp v2, v0 row_mirror row_mask:0xf bank_mask:0xf bound_ctrl:1
	v_mov_b32_dpp v3, v1 row_mirror row_mask:0xf bank_mask:0xf bound_ctrl:1
	v_pk_add_f32 v[0:1], v[0:1], v[2:3]
	ds_bpermute_b32 v2, v199, v0
	ds_bpermute_b32 v3, v199, v1
	global_store_short v[18:19], v4, off offset:64
	s_and_saveexec_b64 s[0:1], s[2:3]
	s_cbranch_execz .LBB0_549
	v_lshlrev_b64 v[16:17], 7, v[132:133]
	v_lshl_add_u64 v[16:17], s[72:73], 0, v[16:17]
	s_waitcnt lgkmcnt(0)
	v_pk_add_f32 v[0:1], v[0:1], v[2:3]
	global_store_dwordx2 v[16:17], v[0:1], off
.LBB0_549:
	s_or_b64 exec, exec, s[0:1]
	s_waitcnt vmcnt(56)
	v_lshlrev_b32_e32 v1, 16, v223
	v_lshlrev_b32_e32 v0, 16, v222
	s_waitcnt lgkmcnt(0)
	v_pk_mul_f32 v[2:3], v[100:101], v[0:1]
	v_add_f32_e32 v5, v5, v206
	v_pk_mul_f32 v[16:17], v[2:3], v[2:3]
	s_nop 0
	v_add_f32_e32 v4, v16, v17
	s_nop 1
	v_add_f32_dpp v4, v4, v4 quad_perm:[1,0,3,2] row_mask:0xf bank_mask:0xf bound_ctrl:1
	s_nop 1
	v_add_f32_dpp v4, v4, v4 quad_perm:[2,3,0,1] row_mask:0xf bank_mask:0xf bound_ctrl:1
	s_nop 1
	v_add_f32_dpp v4, v4, v4 row_half_mirror row_mask:0xf bank_mask:0xf bound_ctrl:1
	s_nop 1
	v_add_f32_dpp v4, v4, v4 row_mirror row_mask:0xf bank_mask:0xf bound_ctrl:1
	ds_bpermute_b32 v16, v199, v4
	s_waitcnt lgkmcnt(0)
	v_add_f32_e32 v4, v4, v16
	v_mul_f32_e32 v16, 0x4f800000, v4
	v_cmp_gt_f32_e32 vcc, s75, v4
	s_nop 1
	v_cndmask_b32_e32 v4, v4, v16, vcc
	v_sqrt_f32_e32 v16, v4
	s_nop 0
	v_add_u32_e32 v17, -1, v16
	v_add_u32_e32 v18, 1, v16
	v_fma_f32 v19, -v17, v16, v4
	v_fma_f32 v20, -v18, v16, v4
	v_cmp_ge_f32_e64 s[0:1], 0, v19
	v_add_f32_e32 v19, v53, v210
	s_nop 0
	v_cndmask_b32_e64 v16, v16, v17, s[0:1]
	v_cmp_lt_f32_e64 s[0:1], 0, v20
	s_nop 1
	v_cndmask_b32_e64 v16, v16, v18, s[0:1]
	v_mul_f32_e32 v17, 0x37800000, v16
	v_cndmask_b32_e32 v16, v16, v17, vcc
	v_cmp_class_f32_e32 vcc, v4, v201
	s_nop 1
	v_cndmask_b32_e32 v4, v16, v4, vcc
	v_max_f32_e32 v4, 0x2b8cbccc, v4
	v_max_f32_e64 v132, -v19, 0
	v_rcp_f32_e32 v4, v4
	s_nop 0
	v_mul_f32_e32 v2, v2, v4
	v_mul_f32_e64 v133, |v19|, s76
	v_exp_f32_e32 v133, v133
	v_cvt_pk_bf16_f32 v103, v2, 0
	v_mul_f32_e32 v3, v3, v4
	s_nop 1
	v_add_f32_e32 v16, 1.0, v133
	v_log_f32_e32 v16, v16
	s_nop 0
	v_mul_f32_e32 v16, 0x3f317218, v16
	v_add_f32_e32 v16, v132, v16
	v_sub_f32_e32 v16, -0.5, v16
	v_add_f32_e32 v19, v37, v209
	s_nop 1
	v_mul_f32_e32 v18, 0xbfb8aa3b, v19
	v_exp_f32_e32 v18, v18
	s_nop 0
	v_add_f32_e32 v18, 1.0, v18
	s_nop 1
	v_mul_f32_e32 v16, 0x3fb8aa3b, v16
	v_exp_f32_e32 v16, v16
	v_rcp_f32_e32 v17, v18
	s_nop 0
	v_add_f32_e32 v18, -1.0, v17
	v_fma_f32 v18, v208, v18, 1.0
	v_mul_f32_e32 v0, v18, v0
	v_cvt_pk_bf16_f32 v18, v16, 0
	v_mul_f32_e32 v2, v17, v2
	v_lshl_add_u64 v[32:33], s[54:55], 0, v[128:129]
	v_lshl_add_u64 v[16:17], s[20:21], 0, v[128:129]
	v_cvt_pk_bf16_f32 v0, v0, 0
	v_cvt_pk_bf16_f32 v2, v2, 0
	global_store_short v[32:33], v18, off
	global_store_short v[130:131], v0, off
	global_store_short v[16:17], v103, off
	v_lshl_add_u64 v[16:17], s[18:19], 0, v[128:129]
	global_store_short v[16:17], v2, off
	v_lshlrev_b32_e32 v17, 16, v0
	v_lshlrev_b32_e32 v0, 16, v2
	v_lshlrev_b32_e32 v2, 16, v18
	v_mul_f32_e32 v18, 0xbfb8aa3b, v2
	v_fma_f32 v19, v2, s76, -v18
	v_rndne_f32_e32 v20, v18
	v_fmac_f32_e32 v19, 0xb2a5705f, v2
	v_sub_f32_e32 v18, v18, v20
	v_add_f32_e32 v18, v18, v19
	v_lshlrev_b32_e32 v16, 16, v221
	v_mul_f32_e32 v34, 0xbfb8aa3b, v2
	v_exp_f32_e32 v34, v34
	v_mov_b32_e32 v19, v16
	v_pk_mul_f32 v[18:19], v[18:19], v[16:17]
	v_fma_f32 v130, v0, v16, 0
	v_add_f32_e32 v18, v21, v207
	v_mov_b32_e32 v0, v34
	v_max_f32_e64 v131, -v18, 0
	s_nop 1
	v_mul_f32_e64 v18, |v18|, s76
	v_exp_f32_e32 v18, v18
	v_lshlrev_b32_e32 v37, 16, v103
	s_nop 0
	v_add_f32_e32 v20, 1.0, v18
	v_log_f32_e32 v20, v20
	s_nop 0
	v_mul_f32_e32 v18, 0x3f317218, v20
	v_add_f32_e32 v18, v131, v18
	v_sub_f32_e32 v18, -0.5, v18
	v_mul_f32_e32 v20, 0x3fb8aa3b, v18
	v_exp_f32_e32 v20, v20
	v_mov_b32_e32 v36, v0
	v_mov_b32_e32 v0, v20
	s_nop 0
	s_nop 1
	v_mul_f32_e32 v2, 0xbfb8aa3b, v5
	v_exp_f32_e32 v2, v2
	s_nop 0
	v_add_f32_e32 v2, 1.0, v2
	v_div_scale_f32 v5, s[0:1], v2, v2, 1.0
	v_rcp_f32_e32 v2, v2
	s_nop 0
	v_add_f32_e32 v4, -1.0, v2
	v_fma_f32 v4, v205, v4, 1.0
	v_mul_f32_e32 v1, v4, v1
	v_cvt_pk_bf16_f32 v18, v0, 0
	v_mul_f32_e32 v0, v2, v3
	v_cvt_pk_bf16_f32 v4, v1, 0
	v_cvt_pk_bf16_f32 v20, v3, 0
	v_cvt_pk_bf16_f32 v2, v0, 0
	v_lshl_add_u64 v[0:1], s[20:21], 0, v[124:125]
	global_store_short v[32:33], v18, off offset:64
	global_store_short v[126:127], v4, off
	global_store_short v[0:1], v20, off
	v_lshl_add_u64 v[0:1], s[18:19], 0, v[124:125]
	global_store_short v[0:1], v2, off
	v_lshlrev_b32_e32 v0, 16, v2
	v_lshlrev_b32_e32 v2, 16, v18
	v_lshlrev_b32_e32 v5, 16, v4
	v_lshlrev_b32_e32 v4, 16, v220
	v_mov_b32_e32 v1, v4
	v_fmac_f32_e32 v130, v0, v4
	v_pk_mul_f32 v[0:1], v[0:1], v[4:5]
	s_nop 0
	v_add_f32_dpp v3, v130, v130 quad_perm:[1,0,3,2] row_mask:0xf bank_mask:0xf bound_ctrl:1
	s_nop 1
	v_add_f32_dpp v3, v3, v3 quad_perm:[2,3,0,1] row_mask:0xf bank_mask:0xf bound_ctrl:1
	v_lshlrev_b32_e32 v20, 16, v20
	v_mul_f32_e32 v21, 0xbfb8aa3b, v2
	v_exp_f32_e32 v21, v21
	v_add_f32_dpp v3, v3, v3 row_half_mirror row_mask:0xf bank_mask:0xf bound_ctrl:1
	v_mov_b32_e32 v0, v5
	v_mov_b32_e32 v5, v204
	v_add_f32_dpp v3, v3, v3 row_mirror row_mask:0xf bank_mask:0xf bound_ctrl:1
	ds_bpermute_b32 v18, v199, v3
	s_waitcnt lgkmcnt(0)
	v_add_f32_e32 v32, v3, v18
	v_mov_b32_e32 v18, v17
	v_mov_b32_e32 v17, v68
	v_pk_fma_f32 v[2:3], v[18:19], v[16:17], 0 op_sel_hi:[1,1,0]
	v_lshlrev_b64 v[18:19], 11, v[122:123]
	v_pk_fma_f32 v[0:1], v[0:1], v[4:5], v[2:3]
	v_mul_f32_e32 v5, v32, v37
	v_fma_f32 v5, v36, v16, -v5
	v_mov_b32_dpp v2, v0 quad_perm:[1,0,3,2] row_mask:0xf bank_mask:0xf bound_ctrl:1
	v_mov_b32_dpp v3, v1 quad_perm:[1,0,3,2] row_mask:0xf bank_mask:0xf bound_ctrl:1
	v_pk_add_f32 v[0:1], v[0:1], v[2:3]
	v_lshl_add_u64 v[18:19], v[64:65], 0, v[18:19]
	v_cvt_pk_bf16_f32 v5, v5, s0
	v_mov_b32_dpp v2, v0 quad_perm:[2,3,0,1] row_mask:0xf bank_mask:0xf bound_ctrl:1
	v_mov_b32_dpp v3, v1 quad_perm:[2,3,0,1] row_mask:0xf bank_mask:0xf bound_ctrl:1
	v_pk_add_f32 v[0:1], v[0:1], v[2:3]
	global_store_short v[18:19], v5, off
	v_mul_f32_e32 v5, v32, v20
	v_mov_b32_dpp v2, v0 row_half_mirror row_mask:0xf bank_mask:0xf bound_ctrl:1
	v_mov_b32_dpp v3, v1 row_half_mirror row_mask:0xf bank_mask:0xf bound_ctrl:1
	v_pk_add_f32 v[0:1], v[0:1], v[2:3]
	v_fma_f32 v4, v21, v4, -v5
	v_cvt_pk_bf16_f32 v4, v4, s0
	v_mov_b32_dpp v2, v0 row_mirror row_mask:0xf bank_mask:0xf bound_ctrl:1
	v_mov_b32_dpp v3, v1 row_mirror row_mask:0xf bank_mask:0xf bound_ctrl:1
	v_pk_add_f32 v[0:1], v[0:1], v[2:3]
	ds_bpermute_b32 v2, v199, v0
	ds_bpermute_b32 v3, v199, v1
	global_store_short v[18:19], v4, off offset:64
	s_and_saveexec_b64 s[0:1], s[2:3]
	s_cbranch_execz .LBB0_551
	v_lshlrev_b64 v[4:5], 7, v[122:123]
	v_lshl_add_u64 v[4:5], s[72:73], 0, v[4:5]
	s_waitcnt lgkmcnt(0)
	v_pk_add_f32 v[0:1], v[0:1], v[2:3]
	global_store_dwordx2 v[4:5], v[0:1], off
.LBB0_551:
	s_or_b64 exec, exec, s[0:1]
	s_waitcnt vmcnt(62)
	v_lshlrev_b32_e32 v1, 16, v219
	v_lshlrev_b32_e32 v0, 16, v218
	s_waitcnt lgkmcnt(0)
	v_pk_mul_f32 v[2:3], v[100:101], v[0:1]
	v_add_f32_e32 v6, v6, v206
	v_pk_mul_f32 v[4:5], v[2:3], v[2:3]
	s_nop 0
	v_add_f32_e32 v4, v4, v5
	s_nop 1
	v_add_f32_dpp v4, v4, v4 quad_perm:[1,0,3,2] row_mask:0xf bank_mask:0xf bound_ctrl:1
	s_nop 1
	v_add_f32_dpp v4, v4, v4 quad_perm:[2,3,0,1] row_mask:0xf bank_mask:0xf bound_ctrl:1
	s_nop 1
	v_add_f32_dpp v4, v4, v4 row_half_mirror row_mask:0xf bank_mask:0xf bound_ctrl:1
	s_nop 1
	v_add_f32_dpp v4, v4, v4 row_mirror row_mask:0xf bank_mask:0xf bound_ctrl:1
	ds_bpermute_b32 v5, v199, v4
	s_waitcnt lgkmcnt(0)
	v_add_f32_e32 v4, v4, v5
	v_mul_f32_e32 v5, 0x4f800000, v4
	v_cmp_gt_f32_e32 vcc, s75, v4
	s_nop 1
	v_cndmask_b32_e32 v4, v4, v5, vcc
	v_sqrt_f32_e32 v5, v4
	s_nop 0
	v_add_u32_e32 v16, -1, v5
	v_add_u32_e32 v17, 1, v5
	v_fma_f32 v18, -v16, v5, v4
	v_fma_f32 v19, -v17, v5, v4
	v_cmp_ge_f32_e64 s[0:1], 0, v18
	s_nop 1
	v_cndmask_b32_e64 v5, v5, v16, s[0:1]
	v_cmp_lt_f32_e64 s[0:1], 0, v19
	s_nop 1
	v_cndmask_b32_e64 v5, v5, v17, s[0:1]
	v_mul_f32_e32 v16, 0x37800000, v5
	v_cndmask_b32_e32 v5, v5, v16, vcc
	v_cmp_class_f32_e32 vcc, v4, v201
	v_add_f32_e32 v17, v54, v210
	s_nop 0
	v_cndmask_b32_e32 v4, v5, v4, vcc
	v_max_f32_e32 v48, 0x2b8cbccc, v4
	v_max_f32_e64 v52, -v17, 0
	s_nop 0
	s_nop 1
	v_mul_f32_e64 v53, |v17|, s76
	v_exp_f32_e32 v53, v53
	s_nop 1
	v_add_f32_e32 v4, 1.0, v53
	v_log_f32_e32 v4, v4
	s_nop 0
	v_mul_f32_e32 v4, 0x3f317218, v4
	v_add_f32_e32 v4, v52, v4
	v_sub_f32_e32 v4, -0.5, v4
	v_add_f32_e32 v17, v38, v209
	v_rcp_f32_e32 v38, v48
	s_nop 0
	v_mul_f32_e32 v2, v2, v38
	v_cvt_pk_bf16_f32 v54, v2, 0
	v_mul_f32_e32 v16, 0xbfb8aa3b, v17
	v_exp_f32_e32 v16, v16
	s_nop 0
	v_add_f32_e32 v16, 1.0, v16
	v_mul_f32_e32 v3, v3, v38
	s_nop 0
	s_nop 1
	v_mul_f32_e32 v4, 0x3fb8aa3b, v4
	v_exp_f32_e32 v4, v4
	v_rcp_f32_e32 v5, v16
	s_nop 0
	v_add_f32_e32 v16, -1.0, v5
	v_fma_f32 v16, v208, v16, 1.0
	v_mul_f32_e32 v0, v16, v0
	v_cvt_pk_bf16_f32 v16, v4, 0
	v_mul_f32_e32 v2, v5, v2
	v_lshl_add_u64 v[18:19], s[54:55], 0, v[118:119]
	v_lshl_add_u64 v[4:5], s[20:21], 0, v[118:119]
	v_cvt_pk_bf16_f32 v0, v0, 0
	v_cvt_pk_bf16_f32 v2, v2, 0
	global_store_short v[18:19], v16, off
	global_store_short v[120:121], v0, off
	global_store_short v[4:5], v54, off
	v_lshl_add_u64 v[4:5], s[18:19], 0, v[118:119]
	global_store_short v[4:5], v2, off
	v_lshlrev_b32_e32 v5, 16, v0
	v_lshlrev_b32_e32 v0, 16, v2
	v_lshlrev_b32_e32 v2, 16, v16
	v_mul_f32_e32 v16, 0xbfb8aa3b, v2
	v_fma_f32 v17, v2, s76, -v16
	v_rndne_f32_e32 v20, v16
	v_fmac_f32_e32 v17, 0xb2a5705f, v2
	v_sub_f32_e32 v16, v16, v20
	v_add_f32_e32 v16, v16, v17
	v_lshlrev_b32_e32 v4, 16, v217
	v_mul_f32_e32 v21, 0xbfb8aa3b, v2
	v_exp_f32_e32 v21, v21
	v_mov_b32_e32 v17, v4
	v_pk_mul_f32 v[16:17], v[16:17], v[4:5]
	v_fma_f32 v103, v0, v4, 0
	v_add_f32_e32 v16, v22, v207
	v_mov_b32_e32 v0, v21
	v_max_f32_e64 v22, -v16, 0
	s_nop 1
	v_mul_f32_e64 v16, |v16|, s76
	v_exp_f32_e32 v16, v16
	v_lshlrev_b32_e32 v34, 16, v54
	s_nop 0
	v_add_f32_e32 v20, 1.0, v16
	v_log_f32_e32 v20, v20
	s_nop 0
	v_mul_f32_e32 v16, 0x3f317218, v20
	v_add_f32_e32 v16, v22, v16
	v_sub_f32_e32 v16, -0.5, v16
	v_mul_f32_e32 v20, 0x3fb8aa3b, v16
	v_exp_f32_e32 v20, v20
	v_mov_b32_e32 v33, v0
	v_mov_b32_e32 v0, v20
	s_nop 0
	s_nop 1
	v_mul_f32_e32 v2, 0xbfb8aa3b, v6
	v_exp_f32_e32 v2, v2
	s_nop 0
	v_add_f32_e32 v2, 1.0, v2
	v_div_scale_f32 v6, s[0:1], v2, v2, 1.0
	v_rcp_f32_e32 v2, v2
	s_nop 0
	v_add_f32_e32 v6, -1.0, v2
	v_fma_f32 v6, v205, v6, 1.0
	v_mul_f32_e32 v1, v6, v1
	v_cvt_pk_bf16_f32 v6, v0, 0
	v_mul_f32_e32 v0, v2, v3
	v_cvt_pk_bf16_f32 v16, v1, 0
	v_cvt_pk_bf16_f32 v20, v3, 0
	v_cvt_pk_bf16_f32 v2, v0, 0
	v_lshl_add_u64 v[0:1], s[20:21], 0, v[114:115]
	global_store_short v[18:19], v6, off offset:64
	global_store_short v[116:117], v16, off
	global_store_short v[0:1], v20, off
	v_lshl_add_u64 v[0:1], s[18:19], 0, v[114:115]
	global_store_short v[0:1], v2, off
	v_lshlrev_b32_e32 v0, 16, v2
	v_lshlrev_b32_e32 v2, 16, v6
	v_lshlrev_b32_e32 v18, 16, v216
	v_lshlrev_b32_e32 v19, 16, v16
	v_mov_b32_e32 v1, v18
	v_fmac_f32_e32 v103, v0, v18
	v_pk_mul_f32 v[0:1], v[0:1], v[18:19]
	s_nop 0
	v_add_f32_dpp v3, v103, v103 quad_perm:[1,0,3,2] row_mask:0xf bank_mask:0xf bound_ctrl:1
	s_nop 1
	v_add_f32_dpp v3, v3, v3 quad_perm:[2,3,0,1] row_mask:0xf bank_mask:0xf bound_ctrl:1
	v_mov_b32_e32 v16, v5
	v_mov_b32_e32 v5, v68
	v_add_f32_dpp v3, v3, v3 row_half_mirror row_mask:0xf bank_mask:0xf bound_ctrl:1
	v_mul_f32_e32 v21, 0xbfb8aa3b, v2
	v_exp_f32_e32 v21, v21
	v_mov_b32_e32 v0, v19
	v_add_f32_dpp v3, v3, v3 row_mirror row_mask:0xf bank_mask:0xf bound_ctrl:1
	ds_bpermute_b32 v6, v199, v3
	v_mov_b32_e32 v19, v204
	v_lshlrev_b32_e32 v20, 16, v20
	s_waitcnt lgkmcnt(0)
	v_add_f32_e32 v6, v3, v6
	v_pk_fma_f32 v[2:3], v[16:17], v[4:5], 0 op_sel_hi:[1,1,0]
	v_mul_f32_e32 v5, v6, v34
	v_pk_fma_f32 v[0:1], v[0:1], v[18:19], v[2:3]
	v_lshlrev_b64 v[16:17], 11, v[112:113]
	v_fma_f32 v4, v33, v4, -v5
	v_mov_b32_dpp v2, v0 quad_perm:[1,0,3,2] row_mask:0xf bank_mask:0xf bound_ctrl:1
	v_mov_b32_dpp v3, v1 quad_perm:[1,0,3,2] row_mask:0xf bank_mask:0xf bound_ctrl:1
	v_pk_add_f32 v[0:1], v[0:1], v[2:3]
	v_lshl_add_u64 v[16:17], v[64:65], 0, v[16:17]
	v_cvt_pk_bf16_f32 v4, v4, s0
	v_mov_b32_dpp v2, v0 quad_perm:[2,3,0,1] row_mask:0xf bank_mask:0xf bound_ctrl:1
	v_mov_b32_dpp v3, v1 quad_perm:[2,3,0,1] row_mask:0xf bank_mask:0xf bound_ctrl:1
	v_pk_add_f32 v[0:1], v[0:1], v[2:3]
	global_store_short v[16:17], v4, off
	v_mul_f32_e32 v4, v6, v20
	v_mov_b32_dpp v2, v0 row_half_mirror row_mask:0xf bank_mask:0xf bound_ctrl:1
	v_mov_b32_dpp v3, v1 row_half_mirror row_mask:0xf bank_mask:0xf bound_ctrl:1
	v_pk_add_f32 v[0:1], v[0:1], v[2:3]
	v_fma_f32 v4, v21, v18, -v4
	v_cvt_pk_bf16_f32 v4, v4, s0
	v_mov_b32_dpp v2, v0 row_mirror row_mask:0xf bank_mask:0xf bound_ctrl:1
	v_mov_b32_dpp v3, v1 row_mirror row_mask:0xf bank_mask:0xf bound_ctrl:1
	v_pk_add_f32 v[0:1], v[0:1], v[2:3]
	ds_bpermute_b32 v2, v199, v0
	ds_bpermute_b32 v3, v199, v1
	global_store_short v[16:17], v4, off offset:64
	s_and_saveexec_b64 s[0:1], s[2:3]
	s_cbranch_execz .LBB0_553
	v_lshlrev_b64 v[4:5], 7, v[112:113]
	v_lshl_add_u64 v[4:5], s[72:73], 0, v[4:5]
	s_waitcnt lgkmcnt(0)
	v_pk_add_f32 v[0:1], v[0:1], v[2:3]
	global_store_dwordx2 v[4:5], v[0:1], off
.LBB0_553:
	s_or_b64 exec, exec, s[0:1]
	v_lshlrev_b32_e32 v1, 16, v215
	v_lshlrev_b32_e32 v0, 16, v214
	s_waitcnt lgkmcnt(0)
	v_pk_mul_f32 v[2:3], v[100:101], v[0:1]
	v_add_f32_e32 v7, v7, v206
	v_pk_mul_f32 v[4:5], v[2:3], v[2:3]
	s_nop 0
	v_add_f32_e32 v4, v4, v5
	s_nop 1
	v_add_f32_dpp v4, v4, v4 quad_perm:[1,0,3,2] row_mask:0xf bank_mask:0xf bound_ctrl:1
	s_nop 1
	v_add_f32_dpp v4, v4, v4 quad_perm:[2,3,0,1] row_mask:0xf bank_mask:0xf bound_ctrl:1
	s_nop 1
	v_add_f32_dpp v4, v4, v4 row_half_mirror row_mask:0xf bank_mask:0xf bound_ctrl:1
	s_nop 1
	v_add_f32_dpp v4, v4, v4 row_mirror row_mask:0xf bank_mask:0xf bound_ctrl:1
	ds_bpermute_b32 v5, v199, v4
	s_waitcnt lgkmcnt(0)
	v_add_f32_e32 v4, v4, v5
	v_mul_f32_e32 v5, 0x4f800000, v4
	v_cmp_gt_f32_e32 vcc, s75, v4
	s_nop 1
	v_cndmask_b32_e32 v4, v4, v5, vcc
	v_sqrt_f32_e32 v5, v4
	s_nop 0
	v_add_u32_e32 v6, -1, v5
	v_add_u32_e32 v16, 1, v5
	v_fma_f32 v17, -v6, v5, v4
	v_fma_f32 v18, -v16, v5, v4
	v_cmp_ge_f32_e64 s[0:1], 0, v17
	v_add_f32_e32 v17, v55, v210
	v_max_f32_e64 v49, -v17, 0
	v_cndmask_b32_e64 v5, v5, v6, s[0:1]
	v_cmp_lt_f32_e64 s[0:1], 0, v18
	s_nop 1
	v_cndmask_b32_e64 v5, v5, v16, s[0:1]
	v_mul_f32_e32 v6, 0x37800000, v5
	v_cndmask_b32_e32 v5, v5, v6, vcc
	v_cmp_class_f32_e32 vcc, v4, v201
	s_nop 1
	v_cndmask_b32_e32 v4, v5, v4, vcc
	v_max_f32_e32 v6, 0x2b8cbccc, v4
	s_nop 1
	v_mul_f32_e64 v50, |v17|, s76
	v_exp_f32_e32 v50, v50
	s_nop 1
	v_add_f32_e32 v4, 1.0, v50
	v_log_f32_e32 v4, v4
	s_nop 0
	v_mul_f32_e32 v4, 0x3f317218, v4
	v_add_f32_e32 v4, v49, v4
	v_sub_f32_e32 v4, -0.5, v4
	v_add_f32_e32 v17, v39, v209
	v_rcp_f32_e32 v6, v6
	s_nop 0
	v_mul_f32_e32 v2, v2, v6
	v_cvt_pk_bf16_f32 v50, v2, 0
	v_mul_f32_e32 v16, 0xbfb8aa3b, v17
	v_exp_f32_e32 v16, v16
	s_nop 0
	v_add_f32_e32 v16, 1.0, v16
	v_mul_f32_e32 v3, v3, v6
	s_nop 0
	s_nop 1
	v_mul_f32_e32 v4, 0x3fb8aa3b, v4
	v_exp_f32_e32 v4, v4
	v_rcp_f32_e32 v5, v16
	s_nop 0
	v_add_f32_e32 v16, -1.0, v5
	v_fma_f32 v16, v208, v16, 1.0
	v_mul_f32_e32 v0, v16, v0
	v_cvt_pk_bf16_f32 v16, v4, 0
	v_mul_f32_e32 v2, v5, v2
	v_lshl_add_u64 v[18:19], s[54:55], 0, v[108:109]
	v_lshl_add_u64 v[4:5], s[20:21], 0, v[108:109]
	v_cvt_pk_bf16_f32 v0, v0, 0
	v_cvt_pk_bf16_f32 v2, v2, 0
	global_store_short v[18:19], v16, off
	global_store_short v[110:111], v0, off
	global_store_short v[4:5], v50, off
	v_lshl_add_u64 v[4:5], s[18:19], 0, v[108:109]
	global_store_short v[4:5], v2, off
	v_lshlrev_b32_e32 v5, 16, v0
	v_lshlrev_b32_e32 v0, 16, v2
	v_lshlrev_b32_e32 v2, 16, v16
	v_mul_f32_e32 v16, 0xbfb8aa3b, v2
	v_fma_f32 v17, v2, s76, -v16
	v_rndne_f32_e32 v20, v16
	v_fmac_f32_e32 v17, 0xb2a5705f, v2
	v_sub_f32_e32 v16, v16, v20
	v_add_f32_e32 v16, v16, v17
	s_waitcnt vmcnt(62)
	v_lshlrev_b32_e32 v4, 16, v213
	v_mul_f32_e32 v21, 0xbfb8aa3b, v2
	v_exp_f32_e32 v21, v21
	v_mov_b32_e32 v17, v4
	v_pk_mul_f32 v[16:17], v[16:17], v[4:5]
	v_fma_f32 v51, v0, v4, 0
	v_add_f32_e32 v16, v23, v207
	v_mov_b32_e32 v0, v21
	v_max_f32_e64 v52, -v16, 0
	s_nop 1
	v_mul_f32_e64 v16, |v16|, s76
	v_exp_f32_e32 v16, v16
	v_lshlrev_b32_e32 v33, 16, v50
	s_nop 0
	v_add_f32_e32 v20, 1.0, v16
	v_log_f32_e32 v20, v20
	s_nop 0
	v_mul_f32_e32 v16, 0x3f317218, v20
	v_add_f32_e32 v16, v52, v16
	v_sub_f32_e32 v16, -0.5, v16
	v_mul_f32_e32 v20, 0x3fb8aa3b, v16
	v_exp_f32_e32 v20, v20
	v_mov_b32_e32 v32, v0
	v_mov_b32_e32 v0, v20
	s_nop 0
	s_nop 1
	v_mul_f32_e32 v2, 0xbfb8aa3b, v7
	v_exp_f32_e32 v2, v2
	s_nop 0
	v_add_f32_e32 v2, 1.0, v2
	v_div_scale_f32 v7, s[0:1], v2, v2, 1.0
	v_rcp_f32_e32 v2, v2
	s_nop 0
	v_add_f32_e32 v6, -1.0, v2
	v_fma_f32 v6, v205, v6, 1.0
	v_mul_f32_e32 v1, v6, v1
	v_cvt_pk_bf16_f32 v16, v0, 0
	v_mul_f32_e32 v0, v2, v3
	v_cvt_pk_bf16_f32 v6, v1, 0
	v_cvt_pk_bf16_f32 v20, v3, 0
	v_cvt_pk_bf16_f32 v2, v0, 0
	v_lshl_add_u64 v[0:1], s[20:21], 0, v[104:105]
	global_store_short v[18:19], v16, off offset:64
	global_store_short v[106:107], v6, off
	global_store_short v[0:1], v20, off
	v_lshl_add_u64 v[0:1], s[18:19], 0, v[104:105]
	global_store_short v[0:1], v2, off
	v_lshlrev_b32_e32 v0, 16, v2
	v_lshlrev_b32_e32 v2, 16, v16
	v_lshlrev_b32_e32 v7, 16, v6
	v_lshlrev_b32_e32 v6, 16, v212
	v_mov_b32_e32 v1, v6
	v_fmac_f32_e32 v51, v0, v6
	v_pk_mul_f32 v[0:1], v[0:1], v[6:7]
	s_nop 0
	v_add_f32_dpp v3, v51, v51 quad_perm:[1,0,3,2] row_mask:0xf bank_mask:0xf bound_ctrl:1
	s_nop 1
	v_add_f32_dpp v3, v3, v3 quad_perm:[2,3,0,1] row_mask:0xf bank_mask:0xf bound_ctrl:1
	v_lshlrev_b32_e32 v19, 16, v20
	v_mul_f32_e32 v18, 0xbfb8aa3b, v2
	v_exp_f32_e32 v18, v18
	v_add_f32_dpp v3, v3, v3 row_half_mirror row_mask:0xf bank_mask:0xf bound_ctrl:1
	v_mov_b32_e32 v0, v7
	v_mov_b32_e32 v7, v204
	v_add_f32_dpp v3, v3, v3 row_mirror row_mask:0xf bank_mask:0xf bound_ctrl:1
	ds_bpermute_b32 v16, v199, v3
	s_waitcnt lgkmcnt(0)
	v_add_f32_e32 v20, v3, v16
	v_mov_b32_e32 v16, v5
	v_mov_b32_e32 v5, v68
	v_pk_fma_f32 v[2:3], v[16:17], v[4:5], 0 op_sel_hi:[1,1,0]
	v_mul_f32_e32 v5, v20, v33
	v_pk_fma_f32 v[0:1], v[0:1], v[6:7], v[2:3]
	v_lshlrev_b64 v[16:17], 11, v[66:67]
	v_fma_f32 v4, v32, v4, -v5
	v_mov_b32_dpp v2, v0 quad_perm:[1,0,3,2] row_mask:0xf bank_mask:0xf bound_ctrl:1
	v_mov_b32_dpp v3, v1 quad_perm:[1,0,3,2] row_mask:0xf bank_mask:0xf bound_ctrl:1
	v_pk_add_f32 v[0:1], v[0:1], v[2:3]
	v_lshl_add_u64 v[16:17], v[64:65], 0, v[16:17]
	v_cvt_pk_bf16_f32 v4, v4, s0
	v_mov_b32_dpp v2, v0 quad_perm:[2,3,0,1] row_mask:0xf bank_mask:0xf bound_ctrl:1
	v_mov_b32_dpp v3, v1 quad_perm:[2,3,0,1] row_mask:0xf bank_mask:0xf bound_ctrl:1
	v_pk_add_f32 v[0:1], v[0:1], v[2:3]
	global_store_short v[16:17], v4, off
	v_mul_f32_e32 v4, v20, v19
	v_mov_b32_dpp v2, v0 row_half_mirror row_mask:0xf bank_mask:0xf bound_ctrl:1
	v_mov_b32_dpp v3, v1 row_half_mirror row_mask:0xf bank_mask:0xf bound_ctrl:1
	v_pk_add_f32 v[0:1], v[0:1], v[2:3]
	v_fma_f32 v4, v18, v6, -v4
	v_cvt_pk_bf16_f32 v4, v4, s0
	v_mov_b32_dpp v2, v0 row_mirror row_mask:0xf bank_mask:0xf bound_ctrl:1
	v_mov_b32_dpp v3, v1 row_mirror row_mask:0xf bank_mask:0xf bound_ctrl:1
	v_pk_add_f32 v[0:1], v[0:1], v[2:3]
	ds_bpermute_b32 v2, v199, v0
	ds_bpermute_b32 v3, v199, v1
	global_store_short v[16:17], v4, off offset:64
	s_and_saveexec_b64 s[0:1], s[2:3]
	s_cbranch_execz .LBB0_555
	v_lshlrev_b64 v[4:5], 7, v[66:67]
	v_lshl_add_u64 v[4:5], s[72:73], 0, v[4:5]
	s_waitcnt lgkmcnt(0)
	v_pk_add_f32 v[0:1], v[0:1], v[2:3]
	global_store_dwordx2 v[4:5], v[0:1], off
.LBB0_555:
	s_or_b64 exec, exec, s[0:1]
	v_or_b32_e32 v128, 17, v102
	v_or_b32_e32 v118, 18, v102
	v_or_b32_e32 v108, 19, v102
	v_or_b32_e32 v138, 16, v102
	v_ashrrev_i32_e32 v129, 31, v128
	v_ashrrev_i32_e32 v119, 31, v118
	v_ashrrev_i32_e32 v109, 31, v108
	v_ashrrev_i32_e32 v139, 31, v138
	v_lshlrev_b64 v[0:1], 10, v[128:129]
	v_lshlrev_b64 v[4:5], 10, v[118:119]
	v_lshlrev_b64 v[16:17], 10, v[108:109]
	v_lshlrev_b64 v[140:141], 11, v[138:139]
	v_or_b32_e32 v0, v0, v211
	v_or_b32_e32 v4, v4, v211
	v_or_b32_e32 v16, v16, v211
	v_lshl_or_b32 v158, v211, 1, v140
	v_mov_b32_e32 v159, v141
	v_lshlrev_b64 v[134:135], 1, v[0:1]
	v_or_b32_e32 v0, 32, v0
	v_lshlrev_b64 v[124:125], 1, v[4:5]
	v_or_b32_e32 v4, 32, v4
	v_lshlrev_b64 v[114:115], 1, v[16:17]
	v_or_b32_e32 v16, 32, v16
	v_lshl_add_u64 v[160:161], s[26:27], 0, v[158:159]
	v_or_b32_e32 v142, 64, v158
	v_mov_b32_e32 v143, v141
	v_lshlrev_b64 v[130:131], 1, v[0:1]
	v_lshlrev_b64 v[120:121], 1, v[4:5]
	v_lshlrev_b64 v[110:111], 1, v[16:17]
	v_lshl_add_u64 v[152:153], s[26:27], 0, v[142:143]
	s_waitcnt lgkmcnt(0)
	v_lshl_add_u64 v[2:3], s[30:31], 0, v[134:135]
	v_lshl_add_u64 v[0:1], s[30:31], 0, v[130:131]
	v_lshl_add_u64 v[6:7], s[30:31], 0, v[124:125]
	v_lshl_add_u64 v[4:5], s[30:31], 0, v[120:121]
	v_lshl_add_u64 v[18:19], s[30:31], 0, v[114:115]
	v_lshl_add_u64 v[16:17], s[30:31], 0, v[110:111]
	global_load_ushort v99, v[160:161], off
	global_load_ushort v189, v[2:3], off
	global_load_ushort v188, v[0:1], off
	global_load_ushort v185, v[6:7], off
	global_load_ushort v184, v[4:5], off
	global_load_ushort v181, v[18:19], off
	global_load_ushort v180, v[16:17], off
	global_load_ushort v145, v[152:153], off
	v_or_b32_e32 v36, 25, v102
	v_lshl_add_u64 v[0:1], s[30:31], 0, v[142:143]
	v_ashrrev_i32_e32 v37, 31, v36
	global_load_ushort v192, v[0:1], off
	v_lshlrev_b64 v[0:1], 10, v[36:37]
	v_or_b32_e32 v0, v0, v211
	v_or_b32_e32 v18, 26, v102
	v_lshlrev_b64 v[50:51], 1, v[0:1]
	v_or_b32_e32 v0, 32, v0
	v_ashrrev_i32_e32 v19, 31, v18
	v_lshlrev_b64 v[38:39], 1, v[0:1]
	v_lshlrev_b64 v[0:1], 10, v[18:19]
	v_or_b32_e32 v0, v0, v211
	v_lshlrev_b64 v[32:33], 1, v[0:1]
	v_or_b32_e32 v0, 32, v0
	v_lshlrev_b64 v[20:21], 1, v[0:1]
	v_or_b32_e32 v0, 27, v102
	v_ashrrev_i32_e32 v1, 31, v0
	v_lshlrev_b64 v[2:3], 10, v[0:1]
	v_or_b32_e32 v2, v2, v211
	v_lshlrev_b64 v[6:7], 1, v[2:3]
	v_or_b32_e32 v2, 32, v2
	v_lshl_add_u64 v[54:55], s[30:31], 0, v[158:159]
	v_lshlrev_b64 v[2:3], 1, v[2:3]
	v_lshl_add_u64 v[52:53], s[26:27], 0, v[50:51]
	v_lshl_add_u64 v[48:49], s[26:27], 0, v[38:39]
	v_lshl_add_u64 v[34:35], s[26:27], 0, v[32:33]
	v_lshl_add_u64 v[22:23], s[26:27], 0, v[20:21]
	v_lshl_add_u64 v[16:17], s[26:27], 0, v[6:7]
	v_lshl_add_u64 v[4:5], s[26:27], 0, v[2:3]
	global_load_ushort v193, v[54:55], off
	global_load_ushort v174, v[52:53], off
	global_load_ushort v175, v[48:49], off
	global_load_ushort v170, v[34:35], off
	global_load_ushort v171, v[22:23], off
	global_load_ushort v166, v[16:17], off
	global_load_ushort v167, v[4:5], off
	v_or_b32_e32 v54, 24, v102
	v_ashrrev_i32_e32 v55, 31, v54
	v_lshlrev_b64 v[66:67], 10, v[54:55]
	v_or_b32_e32 v66, v66, v211
	v_lshlrev_b64 v[104:105], 1, v[66:67]
	v_or_b32_e32 v66, 32, v66
	v_lshlrev_b64 v[66:67], 1, v[66:67]
	v_lshl_add_u64 v[136:137], s[26:27], 0, v[134:135]
	v_lshl_add_u64 v[146:147], s[30:31], 0, v[104:105]
	v_lshl_add_u64 v[164:165], s[30:31], 0, v[50:51]
	v_lshl_add_u64 v[168:169], s[30:31], 0, v[38:39]
	v_add_f32_e32 v56, v56, v210
	v_lshl_add_u64 v[132:133], s[26:27], 0, v[130:131]
	v_lshl_add_u64 v[126:127], s[26:27], 0, v[124:125]
	v_lshl_add_u64 v[122:123], s[26:27], 0, v[120:121]
	v_lshl_add_u64 v[116:117], s[26:27], 0, v[114:115]
	v_lshl_add_u64 v[112:113], s[26:27], 0, v[110:111]
	v_lshl_add_u64 v[106:107], s[26:27], 0, v[104:105]
	v_lshl_add_u64 v[102:103], s[26:27], 0, v[66:67]
	global_load_ushort v190, v[136:137], off
	global_load_ushort v191, v[132:133], off
	global_load_ushort v186, v[126:127], off
	global_load_ushort v187, v[122:123], off
	global_load_ushort v182, v[116:117], off
	global_load_ushort v183, v[112:113], off
	global_load_ushort v178, v[106:107], off
	global_load_ushort v179, v[102:103], off
	v_lshl_add_u64 v[194:195], s[30:31], 0, v[32:33]
	v_lshl_add_u64 v[212:213], s[30:31], 0, v[20:21]
	v_lshl_add_u64 v[214:215], s[30:31], 0, v[6:7]
	v_lshl_add_u64 v[216:217], s[30:31], 0, v[2:3]
	v_max_f32_e64 v221, -v56, 0
	v_add_f32_e32 v40, v40, v209
	v_add_f32_e32 v24, v24, v207
	v_add_f32_e32 v8, v8, v206
	v_lshl_add_u64 v[140:141], v[64:65], 0, v[140:141]
	s_waitcnt vmcnt(23)
	v_lshlrev_b32_e32 v154, 16, v99
	s_waitcnt vmcnt(16)
	v_lshlrev_b32_e32 v155, 16, v145
	v_pk_mul_f32 v[156:157], v[100:101], v[154:155]
	s_nop 0
	v_pk_mul_f32 v[162:163], v[156:157], v[156:157]
	s_nop 0
	v_add_f32_e32 v99, v162, v163
	v_lshl_add_u64 v[162:163], s[30:31], 0, v[66:67]
	s_nop 0
	v_add_f32_dpp v99, v99, v99 quad_perm:[1,0,3,2] row_mask:0xf bank_mask:0xf bound_ctrl:1
	s_nop 1
	v_add_f32_dpp v99, v99, v99 quad_perm:[2,3,0,1] row_mask:0xf bank_mask:0xf bound_ctrl:1
	s_nop 1
	v_add_f32_dpp v99, v99, v99 row_half_mirror row_mask:0xf bank_mask:0xf bound_ctrl:1
	s_nop 1
	v_add_f32_dpp v99, v99, v99 row_mirror row_mask:0xf bank_mask:0xf bound_ctrl:1
	ds_bpermute_b32 v145, v199, v99
	s_waitcnt lgkmcnt(0)
	v_add_f32_e32 v99, v99, v145
	v_mul_f32_e32 v145, 0x4f800000, v99
	v_cmp_gt_f32_e32 vcc, s75, v99
	s_nop 1
	v_cndmask_b32_e32 v99, v99, v145, vcc
	v_sqrt_f32_e32 v145, v99
	s_nop 0
	v_add_u32_e32 v172, -1, v145
	v_fma_f32 v173, -v172, v145, v99
	v_cmp_ge_f32_e64 s[0:1], 0, v173
	v_add_u32_e32 v173, 1, v145
	s_nop 0
	v_cndmask_b32_e64 v172, v145, v172, s[0:1]
	v_fma_f32 v145, -v173, v145, v99
	v_cmp_lt_f32_e64 s[0:1], 0, v145
	s_nop 1
	v_cndmask_b32_e64 v145, v172, v173, s[0:1]
	v_mul_f32_e32 v172, 0x37800000, v145
	v_cndmask_b32_e32 v145, v145, v172, vcc
	v_cmp_class_f32_e32 vcc, v99, v201
	global_load_ushort v177, v[146:147], off
	global_load_ushort v176, v[162:163], off
	global_load_ushort v173, v[164:165], off
	global_load_ushort v172, v[168:169], off
	s_nop 0
	global_load_ushort v169, v[194:195], off
	global_load_ushort v168, v[212:213], off
	global_load_ushort v165, v[214:215], off
	global_load_ushort v164, v[216:217], off
	v_cndmask_b32_e32 v99, v145, v99, vcc
	v_max_f32_e32 v145, 0x2b8cbccc, v99
	s_nop 1
	v_mul_f32_e64 v56, |v56|, s76
	v_exp_f32_e32 v56, v56
	s_nop 1
	v_add_f32_e32 v99, 1.0, v56
	v_log_f32_e32 v99, v99
	s_nop 0
	v_mul_f32_e32 v56, 0x3f317218, v99
	v_add_f32_e32 v56, v221, v56
	v_sub_f32_e32 v56, -0.5, v56
	v_rcp_f32_e32 v145, v145
	s_nop 1
	v_mul_f32_e32 v40, 0xbfb8aa3b, v40
	v_exp_f32_e32 v40, v40
	s_nop 0
	v_add_f32_e32 v40, 1.0, v40
	s_nop 1
	v_mul_f32_e32 v56, 0x3fb8aa3b, v56
	v_exp_f32_e32 v56, v56
	v_rcp_f32_e32 v40, v40
	s_nop 0
	v_add_f32_e32 v146, -1.0, v40
	v_fma_f32 v146, v208, v146, 1.0
	v_mul_f32_e32 v99, v156, v145
	v_mul_f32_e32 v146, v146, v154
	v_cvt_pk_bf16_f32 v56, v56, 0
	v_lshl_add_u64 v[162:163], s[54:55], 0, v[158:159]
	v_cvt_pk_bf16_f32 v154, v146, 0
	v_cvt_pk_bf16_f32 v156, v99, 0
	v_mul_f32_e32 v40, v40, v99
	global_store_short v[162:163], v56, off
	global_store_short v[160:161], v154, off
	v_lshl_add_u64 v[146:147], s[20:21], 0, v[158:159]
	v_lshlrev_b32_e32 v56, 16, v56
	v_cvt_pk_bf16_f32 v40, v40, 0
	global_store_short v[146:147], v156, off
	v_lshl_add_u64 v[146:147], s[18:19], 0, v[158:159]
	global_store_short v[146:147], v40, off
	s_waitcnt vmcnt(26)
	v_lshlrev_b32_e32 v158, 16, v193
	v_lshlrev_b32_e32 v159, 16, v154
	v_mov_b32_e32 v99, v158
	v_pk_mul_f32 v[160:161], v[98:99], v[158:159]
	v_max_f32_e64 v160, -v24, 0
	v_lshlrev_b32_e32 v40, 16, v40
	v_fma_f32 v40, v40, v158, 0
	s_nop 0
	s_nop 1
	v_mul_f32_e64 v24, |v24|, s76
	v_exp_f32_e32 v24, v24
	s_nop 1
	v_add_f32_e32 v99, 1.0, v24
	v_log_f32_e32 v99, v99
	s_nop 0
	v_mul_f32_e32 v24, 0x3f317218, v99
	v_add_f32_e32 v24, v160, v24
	v_sub_f32_e32 v24, -0.5, v24
	v_mul_f32_e32 v56, 0xbfb8aa3b, v56
	v_exp_f32_e32 v56, v56
	v_lshlrev_b32_e32 v154, 16, v156
	s_nop 0
	s_nop 1
	v_mul_f32_e32 v8, 0xbfb8aa3b, v8
	v_exp_f32_e32 v8, v8
	s_nop 0
	v_add_f32_e32 v8, 1.0, v8
	v_div_scale_f32 v146, s[0:1], v8, v8, 1.0
	s_nop 1
	v_mul_f32_e32 v24, 0x3fb8aa3b, v24
	v_exp_f32_e32 v24, v24
	v_rcp_f32_e32 v8, v8
	v_mul_f32_e32 v99, v157, v145
	v_add_f32_e32 v145, -1.0, v8
	v_fma_f32 v145, v205, v145, 1.0
	v_mul_f32_e32 v145, v145, v155
	v_cvt_pk_bf16_f32 v24, v24, 0
	v_cvt_pk_bf16_f32 v145, v145, 0
	v_mul_f32_e32 v8, v8, v99
	global_store_short v[162:163], v24, off offset:64
	global_store_short v[152:153], v145, off
	v_lshlrev_b32_e32 v24, 16, v24
	v_cvt_pk_bf16_f32 v155, v99, 0
	v_cvt_pk_bf16_f32 v8, v8, 0
	v_lshl_add_u64 v[146:147], s[20:21], 0, v[142:143]
	v_lshl_add_u64 v[142:143], s[18:19], 0, v[142:143]
	global_store_short v[142:143], v8, off
	global_store_short v[146:147], v155, off
	v_lshlrev_b32_e32 v147, 16, v145
	v_mul_f32_e32 v145, 0xbfb8aa3b, v24
	v_exp_f32_e32 v145, v145
	v_lshlrev_b32_e32 v146, 16, v192
	v_mov_b32_e32 v99, v146
	v_lshlrev_b32_e32 v8, 16, v8
	v_pk_mul_f32 v[142:143], v[98:99], v[146:147]
	v_mov_b32_e32 v160, v159
	v_mov_b32_e32 v159, v68
	v_fmac_f32_e32 v40, v8, v146
	v_mov_b32_e32 v8, v145
	v_pk_fma_f32 v[152:153], v[160:161], v[158:159], 0 op_sel_hi:[1,1,0]
	v_mov_b32_e32 v142, v147
	v_mov_b32_e32 v147, v204
	v_pk_fma_f32 v[142:143], v[142:143], v[146:147], v[152:153]
	v_add_f32_dpp v40, v40, v40 quad_perm:[1,0,3,2] row_mask:0xf bank_mask:0xf bound_ctrl:1
	s_nop 0
	v_mov_b32_dpp v152, v142 quad_perm:[1,0,3,2] row_mask:0xf bank_mask:0xf bound_ctrl:1
	v_mov_b32_dpp v153, v143 quad_perm:[1,0,3,2] row_mask:0xf bank_mask:0xf bound_ctrl:1
	v_add_f32_dpp v40, v40, v40 quad_perm:[2,3,0,1] row_mask:0xf bank_mask:0xf bound_ctrl:1
	v_pk_add_f32 v[142:143], v[142:143], v[152:153]
	s_nop 0
	v_add_f32_dpp v40, v40, v40 row_half_mirror row_mask:0xf bank_mask:0xf bound_ctrl:1
	v_mov_b32_dpp v152, v142 quad_perm:[2,3,0,1] row_mask:0xf bank_mask:0xf bound_ctrl:1
	v_mov_b32_dpp v153, v143 quad_perm:[2,3,0,1] row_mask:0xf bank_mask:0xf bound_ctrl:1
	v_add_f32_dpp v40, v40, v40 row_mirror row_mask:0xf bank_mask:0xf bound_ctrl:1
	v_pk_add_f32 v[142:143], v[142:143], v[152:153]
	ds_bpermute_b32 v99, v199, v40
	s_nop 0
	v_mov_b32_dpp v152, v142 row_half_mirror row_mask:0xf bank_mask:0xf bound_ctrl:1
	v_mov_b32_dpp v153, v143 row_half_mirror row_mask:0xf bank_mask:0xf bound_ctrl:1
	v_pk_add_f32 v[142:143], v[142:143], v[152:153]
	v_lshlrev_b32_e32 v24, 16, v155
	s_waitcnt lgkmcnt(0)
	v_add_f32_e32 v40, v40, v99
	v_mov_b32_dpp v152, v142 row_mirror row_mask:0xf bank_mask:0xf bound_ctrl:1
	v_mov_b32_dpp v153, v143 row_mirror row_mask:0xf bank_mask:0xf bound_ctrl:1
	v_pk_add_f32 v[142:143], v[142:143], v[152:153]
	ds_bpermute_b32 v152, v199, v142
	ds_bpermute_b32 v153, v199, v143
	v_mul_f32_e32 v99, v40, v154
	v_mul_f32_e32 v24, v40, v24
	v_fma_f32 v56, v56, v158, -v99
	v_fma_f32 v8, v8, v146, -v24
	v_cvt_pk_bf16_f32 v56, v56, s0
	v_cvt_pk_bf16_f32 v8, v8, s0
	global_store_short v[140:141], v56, off
	global_store_short v[140:141], v8, off offset:64
	s_and_saveexec_b64 s[0:1], s[2:3]
	s_cbranch_execz .LBB0_557
	v_lshlrev_b64 v[138:139], 7, v[138:139]
	v_lshl_add_u64 v[138:139], s[72:73], 0, v[138:139]
	s_waitcnt lgkmcnt(0)
	v_pk_add_f32 v[140:141], v[142:143], v[152:153]
	global_store_dwordx2 v[138:139], v[140:141], off
.LBB0_557:
	s_or_b64 exec, exec, s[0:1]
	s_waitcnt vmcnt(24)
	v_lshlrev_b32_e32 v139, 16, v191
	v_lshlrev_b32_e32 v138, 16, v190
	v_pk_mul_f32 v[140:141], v[100:101], v[138:139]
	v_add_f32_e32 v57, v57, v210
	v_pk_mul_f32 v[142:143], v[140:141], v[140:141]
	v_max_f32_e64 v160, -v57, 0
	v_add_f32_e32 v8, v142, v143
	v_add_f32_e32 v41, v41, v209
	v_add_f32_e32 v25, v25, v207
	v_add_f32_dpp v8, v8, v8 quad_perm:[1,0,3,2] row_mask:0xf bank_mask:0xf bound_ctrl:1
	v_add_f32_e32 v9, v9, v206
	s_nop 0
	v_add_f32_dpp v8, v8, v8 quad_perm:[2,3,0,1] row_mask:0xf bank_mask:0xf bound_ctrl:1
	s_nop 1
	v_add_f32_dpp v8, v8, v8 row_half_mirror row_mask:0xf bank_mask:0xf bound_ctrl:1
	s_nop 1
	v_add_f32_dpp v8, v8, v8 row_mirror row_mask:0xf bank_mask:0xf bound_ctrl:1
	ds_bpermute_b32 v24, v199, v8
	s_waitcnt lgkmcnt(0)
	v_add_f32_e32 v8, v8, v24
	v_mul_f32_e32 v24, 0x4f800000, v8
	v_cmp_gt_f32_e32 vcc, s75, v8
	s_nop 1
	v_cndmask_b32_e32 v8, v8, v24, vcc
	v_sqrt_f32_e32 v24, v8
	s_nop 0
	v_add_u32_e32 v40, -1, v24
	v_add_u32_e32 v56, 1, v24
	v_fma_f32 v99, -v40, v24, v8
	v_fma_f32 v142, -v56, v24, v8
	v_cmp_ge_f32_e64 s[0:1], 0, v99
	s_nop 1
	v_cndmask_b32_e64 v24, v24, v40, s[0:1]
	v_cmp_lt_f32_e64 s[0:1], 0, v142
	s_nop 1
	v_cndmask_b32_e64 v24, v24, v56, s[0:1]
	v_mul_f32_e32 v40, 0x37800000, v24
	v_cndmask_b32_e32 v24, v24, v40, vcc
	v_cmp_class_f32_e32 vcc, v8, v201
	s_nop 1
	v_cndmask_b32_e32 v8, v24, v8, vcc
	v_max_f32_e32 v8, 0x2b8cbccc, v8
	v_rcp_f32_e32 v8, v8
	s_nop 0
	v_mul_f32_e64 v161, |v57|, s76
	v_exp_f32_e32 v161, v161
	v_max_f32_e64 v159, -v25, 0
	s_nop 1
	v_add_f32_e32 v56, 1.0, v161
	v_log_f32_e32 v56, v56
	s_nop 0
	v_mul_f32_e32 v56, 0x3f317218, v56
	v_add_f32_e32 v56, v160, v56
	v_sub_f32_e32 v56, -0.5, v56
	v_mul_f32_e32 v57, 0x3fb8aa3b, v56
	v_exp_f32_e32 v57, v57
	s_nop 0
	v_mov_b32_e32 v24, v57
	s_nop 0
	v_mul_f32_e32 v40, 0xbfb8aa3b, v41
	v_exp_f32_e32 v40, v40
	s_nop 0
	v_add_f32_e32 v40, 1.0, v40
	v_rcp_f32_e32 v40, v40
	v_mul_f32_e32 v41, v140, v8
	v_add_f32_e32 v56, -1.0, v40
	v_fma_f32 v56, v208, v56, 1.0
	v_cvt_pk_bf16_f32 v24, v24, 0
	v_mul_f32_e32 v40, v40, v41
	v_mul_f32_e32 v56, v56, v138
	v_cvt_pk_bf16_f32 v138, v41, 0
	v_cvt_pk_bf16_f32 v57, v40, 0
	v_lshl_add_u64 v[142:143], s[54:55], 0, v[134:135]
	v_lshl_add_u64 v[40:41], s[20:21], 0, v[134:135]
	v_lshlrev_b32_e32 v140, 16, v24
	v_cvt_pk_bf16_f32 v56, v56, 0
	global_store_short v[142:143], v24, off
	global_store_short v[136:137], v56, off
	global_store_short v[40:41], v138, off
	v_lshl_add_u64 v[40:41], s[18:19], 0, v[134:135]
	global_store_short v[40:41], v57, off
	v_lshlrev_b32_e32 v41, 16, v56
	v_lshlrev_b32_e32 v56, 16, v57
	v_lshlrev_b32_e32 v40, 16, v189
	v_mov_b32_e32 v57, v40
	v_fma_f32 v145, v56, v40, 0
	v_pk_mul_f32 v[56:57], v[56:57], v[40:41]
	v_mul_f32_e32 v8, v141, v8
	s_nop 0
	s_nop 1
	v_mul_f32_e64 v56, |v25|, s76
	v_exp_f32_e32 v56, v56
	v_lshlrev_b32_e32 v136, 16, v138
	s_nop 0
	v_add_f32_e32 v24, 1.0, v56
	v_log_f32_e32 v24, v24
	s_nop 0
	v_mul_f32_e32 v24, 0x3f317218, v24
	v_add_f32_e32 v24, v159, v24
	v_sub_f32_e32 v24, -0.5, v24
	v_mul_f32_e32 v135, 0xbfb8aa3b, v140
	v_exp_f32_e32 v135, v135
	s_nop 1
	v_mul_f32_e32 v9, 0xbfb8aa3b, v9
	v_exp_f32_e32 v9, v9
	s_nop 0
	v_add_f32_e32 v9, 1.0, v9
	v_div_scale_f32 v56, s[0:1], v9, v9, 1.0
	s_nop 1
	v_mul_f32_e32 v24, 0x3fb8aa3b, v24
	v_exp_f32_e32 v24, v24
	v_rcp_f32_e32 v9, v9
	s_nop 0
	v_add_f32_e32 v25, -1.0, v9
	v_fma_f32 v25, v205, v25, 1.0
	v_cvt_pk_bf16_f32 v56, v8, 0
	v_mul_f32_e32 v8, v9, v8
	v_mul_f32_e32 v25, v25, v139
	v_cvt_pk_bf16_f32 v24, v24, 0
	v_cvt_pk_bf16_f32 v99, v8, 0
	v_lshl_add_u64 v[8:9], s[20:21], 0, v[130:131]
	v_cvt_pk_bf16_f32 v25, v25, 0
	global_store_short v[142:143], v24, off offset:64
	global_store_short v[132:133], v25, off
	global_store_short v[8:9], v56, off
	v_lshl_add_u64 v[8:9], s[18:19], 0, v[130:131]
	v_lshlrev_b32_e32 v24, 16, v24
	global_store_short v[8:9], v99, off
	v_lshlrev_b32_e32 v131, 16, v25
	v_lshlrev_b32_e32 v8, 16, v99
	v_lshlrev_b32_e32 v130, 16, v188
	v_mov_b32_e32 v9, v130
	v_fmac_f32_e32 v145, v8, v130
	v_pk_mul_f32 v[8:9], v[8:9], v[130:131]
	s_nop 0
	v_add_f32_dpp v25, v145, v145 quad_perm:[1,0,3,2] row_mask:0xf bank_mask:0xf bound_ctrl:1
	s_nop 1
	v_add_f32_dpp v25, v25, v25 quad_perm:[2,3,0,1] row_mask:0xf bank_mask:0xf bound_ctrl:1
	v_lshlrev_b32_e32 v133, 16, v56
	v_mov_b32_e32 v56, v41
	v_add_f32_dpp v25, v25, v25 row_half_mirror row_mask:0xf bank_mask:0xf bound_ctrl:1
	v_mov_b32_e32 v41, v68
	v_mul_f32_e32 v132, 0xbfb8aa3b, v24
	v_exp_f32_e32 v132, v132
	v_add_f32_dpp v25, v25, v25 row_mirror row_mask:0xf bank_mask:0xf bound_ctrl:1
	ds_bpermute_b32 v99, v199, v25
	v_mov_b32_e32 v8, v131
	v_mov_b32_e32 v131, v204
	s_waitcnt lgkmcnt(0)
	v_add_f32_e32 v99, v25, v99
	v_pk_fma_f32 v[24:25], v[56:57], v[40:41], 0 op_sel_hi:[1,1,0]
	v_mul_f32_e32 v41, v99, v136
	v_pk_fma_f32 v[8:9], v[8:9], v[130:131], v[24:25]
	v_lshlrev_b64 v[56:57], 11, v[128:129]
	v_fma_f32 v40, v135, v40, -v41
	v_mov_b32_dpp v24, v8 quad_perm:[1,0,3,2] row_mask:0xf bank_mask:0xf bound_ctrl:1
	v_mov_b32_dpp v25, v9 quad_perm:[1,0,3,2] row_mask:0xf bank_mask:0xf bound_ctrl:1
	v_pk_add_f32 v[8:9], v[8:9], v[24:25]
	v_lshl_add_u64 v[56:57], v[64:65], 0, v[56:57]
	v_cvt_pk_bf16_f32 v40, v40, s0
	v_mov_b32_dpp v24, v8 quad_perm:[2,3,0,1] row_mask:0xf bank_mask:0xf bound_ctrl:1
	v_mov_b32_dpp v25, v9 quad_perm:[2,3,0,1] row_mask:0xf bank_mask:0xf bound_ctrl:1
	v_pk_add_f32 v[8:9], v[8:9], v[24:25]
	global_store_short v[56:57], v40, off
	v_mul_f32_e32 v40, v99, v133
	v_mov_b32_dpp v24, v8 row_half_mirror row_mask:0xf bank_mask:0xf bound_ctrl:1
	v_mov_b32_dpp v25, v9 row_half_mirror row_mask:0xf bank_mask:0xf bound_ctrl:1
	v_pk_add_f32 v[8:9], v[8:9], v[24:25]
	v_fma_f32 v40, v132, v130, -v40
	v_cvt_pk_bf16_f32 v40, v40, s0
	v_mov_b32_dpp v24, v8 row_mirror row_mask:0xf bank_mask:0xf bound_ctrl:1
	v_mov_b32_dpp v25, v9 row_mirror row_mask:0xf bank_mask:0xf bound_ctrl:1
	v_pk_add_f32 v[8:9], v[8:9], v[24:25]
	ds_bpermute_b32 v24, v199, v8
	ds_bpermute_b32 v25, v199, v9
	global_store_short v[56:57], v40, off offset:64
	s_and_saveexec_b64 s[0:1], s[2:3]
	s_cbranch_execz .LBB0_559
	v_lshlrev_b64 v[40:41], 7, v[128:129]
	v_lshl_add_u64 v[40:41], s[72:73], 0, v[40:41]
	s_waitcnt lgkmcnt(0)
	v_pk_add_f32 v[8:9], v[8:9], v[24:25]
	global_store_dwordx2 v[40:41], v[8:9], off
.LBB0_559:
	s_or_b64 exec, exec, s[0:1]
	s_waitcnt vmcnt(32)
	v_lshlrev_b32_e32 v9, 16, v187
	v_lshlrev_b32_e32 v8, 16, v186
	s_waitcnt lgkmcnt(0)
	v_pk_mul_f32 v[24:25], v[100:101], v[8:9]
	v_add_f32_e32 v42, v42, v209
	v_pk_mul_f32 v[40:41], v[24:25], v[24:25]
	v_add_f32_e32 v26, v26, v207
	v_add_f32_e32 v40, v40, v41
	v_add_f32_e32 v10, v10, v206
	s_nop 0
	v_add_f32_dpp v40, v40, v40 quad_perm:[1,0,3,2] row_mask:0xf bank_mask:0xf bound_ctrl:1
	s_nop 1
	v_add_f32_dpp v40, v40, v40 quad_perm:[2,3,0,1] row_mask:0xf bank_mask:0xf bound_ctrl:1
	s_nop 1
	v_add_f32_dpp v40, v40, v40 row_half_mirror row_mask:0xf bank_mask:0xf bound_ctrl:1
	s_nop 1
	v_add_f32_dpp v40, v40, v40 row_mirror row_mask:0xf bank_mask:0xf bound_ctrl:1
	ds_bpermute_b32 v41, v199, v40
	s_waitcnt lgkmcnt(0)
	v_add_f32_e32 v40, v40, v41
	v_mul_f32_e32 v41, 0x4f800000, v40
	v_cmp_gt_f32_e32 vcc, s75, v40
	s_nop 1
	v_cndmask_b32_e32 v40, v40, v41, vcc
	v_sqrt_f32_e32 v41, v40
	s_nop 0
	v_add_u32_e32 v56, -1, v41
	v_add_u32_e32 v57, 1, v41
	v_fma_f32 v99, -v56, v41, v40
	v_fma_f32 v128, -v57, v41, v40
	v_cmp_ge_f32_e64 s[0:1], 0, v99
	s_nop 1
	v_cndmask_b32_e64 v41, v41, v56, s[0:1]
	v_cmp_lt_f32_e64 s[0:1], 0, v128
	s_nop 1
	v_cndmask_b32_e64 v41, v41, v57, s[0:1]
	v_mul_f32_e32 v56, 0x37800000, v41
	v_cndmask_b32_e32 v41, v41, v56, vcc
	v_cmp_class_f32_e32 vcc, v40, v201
	v_add_f32_e32 v57, v58, v210
	s_nop 0
	v_cndmask_b32_e32 v40, v41, v40, vcc
	v_max_f32_e32 v138, 0x2b8cbccc, v40
	v_max_f32_e64 v142, -v57, 0
	s_nop 0
	s_nop 1
	v_mul_f32_e64 v58, |v57|, s76
	v_exp_f32_e32 v58, v58
	v_lshl_add_u64 v[128:129], s[54:55], 0, v[124:125]
	s_nop 0
	v_add_f32_e32 v40, 1.0, v58
	v_log_f32_e32 v40, v40
	s_nop 0
	v_mul_f32_e32 v40, 0x3f317218, v40
	v_add_f32_e32 v40, v142, v40
	v_sub_f32_e32 v40, -0.5, v40
	v_rcp_f32_e32 v140, v138
	s_nop 0
	v_mul_f32_e32 v24, v24, v140
	v_max_f32_e64 v142, -v26, 0
	v_mul_f32_e32 v42, 0xbfb8aa3b, v42
	v_exp_f32_e32 v42, v42
	s_nop 0
	v_add_f32_e32 v42, 1.0, v42
	s_nop 1
	v_mul_f32_e32 v40, 0x3fb8aa3b, v40
	v_exp_f32_e32 v40, v40
	v_rcp_f32_e32 v41, v42
	s_nop 0
	v_add_f32_e32 v42, -1.0, v41
	v_fma_f32 v42, v208, v42, 1.0
	v_mul_f32_e32 v8, v42, v8
	v_cvt_pk_bf16_f32 v42, v40, 0
	v_cvt_pk_bf16_f32 v58, v24, 0
	v_mul_f32_e32 v24, v41, v24
	v_lshl_add_u64 v[40:41], s[20:21], 0, v[124:125]
	v_cvt_pk_bf16_f32 v8, v8, 0
	v_cvt_pk_bf16_f32 v24, v24, 0
	global_store_short v[128:129], v42, off
	global_store_short v[126:127], v8, off
	global_store_short v[40:41], v58, off
	v_lshl_add_u64 v[40:41], s[18:19], 0, v[124:125]
	global_store_short v[40:41], v24, off
	v_lshlrev_b32_e32 v41, 16, v8
	v_lshlrev_b32_e32 v8, 16, v24
	v_lshlrev_b32_e32 v24, 16, v42
	v_mul_f32_e32 v42, 0xbfb8aa3b, v24
	v_fma_f32 v56, v24, s76, -v42
	v_fmac_f32_e32 v56, 0xb2a5705f, v24
	v_mul_f32_e32 v42, 0xbfb8aa3b, v24
	v_exp_f32_e32 v42, v42
	v_lshlrev_b32_e32 v40, 16, v185
	v_mov_b32_e32 v57, v40
	v_fma_f32 v141, v8, v40, 0
	v_pk_mul_f32 v[56:57], v[56:57], v[40:41]
	v_mov_b32_e32 v8, v42
	v_lshlrev_b32_e32 v58, 16, v58
	s_nop 1
	v_mul_f32_e64 v26, |v26|, s76
	v_exp_f32_e32 v26, v26
	s_nop 1
	v_add_f32_e32 v42, 1.0, v26
	v_log_f32_e32 v42, v42
	s_nop 0
	v_mul_f32_e32 v26, 0x3f317218, v42
	v_add_f32_e32 v26, v142, v26
	v_sub_f32_e32 v26, -0.5, v26
	v_mul_f32_e32 v42, 0x3fb8aa3b, v26
	v_exp_f32_e32 v42, v42
	v_mov_b32_e32 v125, v8
	v_mov_b32_e32 v8, v42
	s_nop 0
	s_nop 1
	v_mul_f32_e32 v10, 0xbfb8aa3b, v10
	v_exp_f32_e32 v10, v10
	s_nop 0
	v_add_f32_e32 v10, 1.0, v10
	v_div_scale_f32 v24, s[0:1], v10, v10, 1.0
	v_rcp_f32_e32 v10, v10
	v_mul_f32_e32 v24, v25, v140
	v_add_f32_e32 v25, -1.0, v10
	v_fma_f32 v25, v205, v25, 1.0
	v_mul_f32_e32 v9, v25, v9
	v_cvt_pk_bf16_f32 v25, v8, 0
	v_mul_f32_e32 v8, v10, v24
	v_cvt_pk_bf16_f32 v26, v9, 0
	v_cvt_pk_bf16_f32 v42, v24, 0
	v_cvt_pk_bf16_f32 v10, v8, 0
	v_lshl_add_u64 v[8:9], s[20:21], 0, v[120:121]
	global_store_short v[128:129], v25, off offset:64
	global_store_short v[122:123], v26, off
	global_store_short v[8:9], v42, off
	v_lshl_add_u64 v[8:9], s[18:19], 0, v[120:121]
	global_store_short v[8:9], v10, off
	v_lshlrev_b32_e32 v8, 16, v10
	v_lshlrev_b32_e32 v10, 16, v25
	v_lshlrev_b32_e32 v120, 16, v184
	v_lshlrev_b32_e32 v121, 16, v26
	v_mov_b32_e32 v9, v120
	v_fmac_f32_e32 v141, v8, v120
	v_pk_mul_f32 v[8:9], v[8:9], v[120:121]
	s_nop 0
	v_add_f32_dpp v24, v141, v141 quad_perm:[1,0,3,2] row_mask:0xf bank_mask:0xf bound_ctrl:1
	s_nop 1
	v_add_f32_dpp v24, v24, v24 quad_perm:[2,3,0,1] row_mask:0xf bank_mask:0xf bound_ctrl:1
	v_mov_b32_e32 v56, v41
	v_mov_b32_e32 v41, v68
	v_add_f32_dpp v24, v24, v24 row_half_mirror row_mask:0xf bank_mask:0xf bound_ctrl:1
	v_mul_f32_e32 v10, 0xbfb8aa3b, v10
	v_exp_f32_e32 v10, v10
	v_lshlrev_b32_e32 v26, 16, v42
	v_add_f32_dpp v24, v24, v24 row_mirror row_mask:0xf bank_mask:0xf bound_ctrl:1
	ds_bpermute_b32 v25, v199, v24
	v_mov_b32_e32 v8, v121
	v_mov_b32_e32 v121, v204
	s_waitcnt lgkmcnt(0)
	v_add_f32_e32 v42, v24, v25
	v_pk_fma_f32 v[24:25], v[56:57], v[40:41], 0 op_sel_hi:[1,1,0]
	v_mul_f32_e32 v41, v42, v58
	v_pk_fma_f32 v[8:9], v[8:9], v[120:121], v[24:25]
	v_mul_f32_e32 v26, v42, v26
	v_lshlrev_b64 v[56:57], 11, v[118:119]
	v_mov_b32_dpp v24, v8 quad_perm:[1,0,3,2] row_mask:0xf bank_mask:0xf bound_ctrl:1
	v_mov_b32_dpp v25, v9 quad_perm:[1,0,3,2] row_mask:0xf bank_mask:0xf bound_ctrl:1
	v_pk_add_f32 v[8:9], v[8:9], v[24:25]
	v_fma_f32 v40, v125, v40, -v41
	v_fma_f32 v10, v10, v120, -v26
	v_mov_b32_dpp v24, v8 quad_perm:[2,3,0,1] row_mask:0xf bank_mask:0xf bound_ctrl:1
	v_mov_b32_dpp v25, v9 quad_perm:[2,3,0,1] row_mask:0xf bank_mask:0xf bound_ctrl:1
	v_pk_add_f32 v[8:9], v[8:9], v[24:25]
	v_lshl_add_u64 v[56:57], v[64:65], 0, v[56:57]
	v_cvt_pk_bf16_f32 v40, v40, s0
	v_mov_b32_dpp v24, v8 row_half_mirror row_mask:0xf bank_mask:0xf bound_ctrl:1
	v_mov_b32_dpp v25, v9 row_half_mirror row_mask:0xf bank_mask:0xf bound_ctrl:1
	v_pk_add_f32 v[8:9], v[8:9], v[24:25]
	v_cvt_pk_bf16_f32 v10, v10, s0
	global_store_short v[56:57], v40, off
	v_mov_b32_dpp v24, v8 row_mirror row_mask:0xf bank_mask:0xf bound_ctrl:1
	v_mov_b32_dpp v25, v9 row_mirror row_mask:0xf bank_mask:0xf bound_ctrl:1
	v_pk_add_f32 v[8:9], v[8:9], v[24:25]
	ds_bpermute_b32 v24, v199, v8
	ds_bpermute_b32 v25, v199, v9
	global_store_short v[56:57], v10, off offset:64
	s_and_saveexec_b64 s[0:1], s[2:3]
	s_cbranch_execz .LBB0_561
	v_lshlrev_b64 v[40:41], 7, v[118:119]
	v_lshl_add_u64 v[40:41], s[72:73], 0, v[40:41]
	s_waitcnt lgkmcnt(0)
	v_pk_add_f32 v[8:9], v[8:9], v[24:25]
	global_store_dwordx2 v[40:41], v[8:9], off
.LBB0_561:
	s_or_b64 exec, exec, s[0:1]
	s_waitcnt vmcnt(40)
	v_lshlrev_b32_e32 v9, 16, v183
	v_lshlrev_b32_e32 v8, 16, v182
	s_waitcnt lgkmcnt(0)
	v_pk_mul_f32 v[24:25], v[100:101], v[8:9]
	v_add_f32_e32 v43, v43, v209
	v_pk_mul_f32 v[40:41], v[24:25], v[24:25]
	v_add_f32_e32 v11, v11, v206
	v_add_f32_e32 v10, v40, v41
	s_nop 1
	v_add_f32_dpp v10, v10, v10 quad_perm:[1,0,3,2] row_mask:0xf bank_mask:0xf bound_ctrl:1
	s_nop 1
	v_add_f32_dpp v10, v10, v10 quad_perm:[2,3,0,1] row_mask:0xf bank_mask:0xf bound_ctrl:1
	s_nop 1
	v_add_f32_dpp v10, v10, v10 row_half_mirror row_mask:0xf bank_mask:0xf bound_ctrl:1
	s_nop 1
	v_add_f32_dpp v10, v10, v10 row_mirror row_mask:0xf bank_mask:0xf bound_ctrl:1
	ds_bpermute_b32 v26, v199, v10
	s_waitcnt lgkmcnt(0)
	v_add_f32_e32 v10, v10, v26
	v_mul_f32_e32 v26, 0x4f800000, v10
	v_cmp_gt_f32_e32 vcc, s75, v10
	s_nop 1
	v_cndmask_b32_e32 v10, v10, v26, vcc
	v_sqrt_f32_e32 v26, v10
	s_nop 0
	v_add_u32_e32 v40, -1, v26
	v_add_u32_e32 v41, 1, v26
	v_fma_f32 v42, -v40, v26, v10
	v_fma_f32 v56, -v41, v26, v10
	v_cmp_ge_f32_e64 s[0:1], 0, v42
	s_nop 1
	v_cndmask_b32_e64 v26, v26, v40, s[0:1]
	v_cmp_lt_f32_e64 s[0:1], 0, v56
	v_add_f32_e32 v56, v59, v210
	s_nop 0
	v_cndmask_b32_e64 v26, v26, v41, s[0:1]
	v_mul_f32_e32 v40, 0x37800000, v26
	v_cndmask_b32_e32 v26, v26, v40, vcc
	v_cmp_class_f32_e32 vcc, v10, v201
	s_nop 1
	v_cndmask_b32_e32 v10, v26, v10, vcc
	v_max_f32_e32 v10, 0x2b8cbccc, v10
	v_max_f32_e64 v127, -v56, 0
	v_rcp_f32_e32 v10, v10
	v_mul_f32_e64 v128, |v56|, s76
	v_exp_f32_e32 v128, v128
	v_mul_f32_e32 v24, v24, v10
	v_mul_f32_e32 v10, v25, v10
	v_cvt_pk_bf16_f32 v124, v24, 0
	s_nop 1
	v_add_f32_e32 v40, 1.0, v128
	v_log_f32_e32 v40, v40
	s_nop 0
	v_mul_f32_e32 v40, 0x3f317218, v40
	v_add_f32_e32 v40, v127, v40
	v_sub_f32_e32 v40, -0.5, v40
	v_mul_f32_e32 v41, 0x3fb8aa3b, v40
	v_exp_f32_e32 v41, v41
	s_nop 0
	v_mov_b32_e32 v26, v41
	s_nop 1
	v_mul_f32_e32 v41, 0xbfb8aa3b, v43
	v_exp_f32_e32 v41, v41
	s_nop 0
	v_add_f32_e32 v41, 1.0, v41
	v_rcp_f32_e32 v40, v41
	s_nop 0
	v_add_f32_e32 v41, -1.0, v40
	v_fma_f32 v41, v208, v41, 1.0
	v_mul_f32_e32 v8, v41, v8
	v_cvt_pk_bf16_f32 v26, v26, 0
	v_mul_f32_e32 v24, v40, v24
	v_lshl_add_u64 v[56:57], s[54:55], 0, v[114:115]
	v_lshl_add_u64 v[40:41], s[20:21], 0, v[114:115]
	v_cvt_pk_bf16_f32 v8, v8, 0
	v_cvt_pk_bf16_f32 v24, v24, 0
	global_store_short v[56:57], v26, off
	global_store_short v[116:117], v8, off
	global_store_short v[40:41], v124, off
	v_lshl_add_u64 v[40:41], s[18:19], 0, v[114:115]
	global_store_short v[40:41], v24, off
	v_lshlrev_b32_e32 v41, 16, v8
	v_lshlrev_b32_e32 v8, 16, v24
	v_lshlrev_b32_e32 v24, 16, v26
	v_mul_f32_e32 v26, 0xbfb8aa3b, v24
	v_fma_f32 v42, v24, s76, -v26
	v_fmac_f32_e32 v42, 0xb2a5705f, v24
	v_mul_f32_e32 v26, 0xbfb8aa3b, v24
	v_exp_f32_e32 v26, v26
	v_lshlrev_b32_e32 v40, 16, v181
	v_fma_f32 v125, v8, v40, 0
	v_mov_b32_e32 v43, v40
	v_mov_b32_e32 v8, v26
	v_add_f32_e32 v26, v27, v207
	v_pk_mul_f32 v[42:43], v[42:43], v[40:41]
	v_max_f32_e64 v126, -v26, 0
	s_nop 1
	v_mul_f32_e64 v42, |v26|, s76
	v_exp_f32_e32 v42, v42
	v_lshlrev_b32_e32 v114, 16, v124
	s_nop 0
	v_add_f32_e32 v26, 1.0, v42
	v_log_f32_e32 v26, v26
	s_nop 0
	v_mul_f32_e32 v26, 0x3f317218, v26
	v_add_f32_e32 v26, v126, v26
	v_sub_f32_e32 v26, -0.5, v26
	v_mul_f32_e32 v27, 0x3fb8aa3b, v26
	v_exp_f32_e32 v27, v27
	v_mov_b32_e32 v99, v8
	v_mov_b32_e32 v8, v27
	s_nop 0
	s_nop 1
	v_mul_f32_e32 v11, 0xbfb8aa3b, v11
	v_exp_f32_e32 v11, v11
	s_nop 0
	v_add_f32_e32 v11, 1.0, v11
	v_div_scale_f32 v24, s[0:1], v11, v11, 1.0
	v_rcp_f32_e32 v11, v11
	s_nop 0
	v_add_f32_e32 v24, -1.0, v11
	v_fma_f32 v24, v205, v24, 1.0
	v_mul_f32_e32 v9, v24, v9
	v_cvt_pk_bf16_f32 v26, v8, 0
	v_mul_f32_e32 v8, v11, v10
	v_cvt_pk_bf16_f32 v24, v9, 0
	v_cvt_pk_bf16_f32 v27, v10, 0
	v_cvt_pk_bf16_f32 v10, v8, 0
	v_lshl_add_u64 v[8:9], s[20:21], 0, v[110:111]
	global_store_short v[56:57], v26, off offset:64
	global_store_short v[112:113], v24, off
	global_store_short v[8:9], v27, off
	v_lshl_add_u64 v[8:9], s[18:19], 0, v[110:111]
	global_store_short v[8:9], v10, off
	v_lshlrev_b32_e32 v8, 16, v10
	v_lshlrev_b32_e32 v10, 16, v26
	v_lshlrev_b32_e32 v25, 16, v24
	v_lshlrev_b32_e32 v24, 16, v180
	v_mov_b32_e32 v9, v24
	v_fmac_f32_e32 v125, v8, v24
	v_pk_mul_f32 v[8:9], v[8:9], v[24:25]
	s_nop 0
	v_add_f32_dpp v11, v125, v125 quad_perm:[1,0,3,2] row_mask:0xf bank_mask:0xf bound_ctrl:1
	s_nop 1
	v_add_f32_dpp v11, v11, v11 quad_perm:[2,3,0,1] row_mask:0xf bank_mask:0xf bound_ctrl:1
	v_mov_b32_e32 v42, v41
	v_mov_b32_e32 v41, v68
	v_add_f32_dpp v11, v11, v11 row_half_mirror row_mask:0xf bank_mask:0xf bound_ctrl:1
	v_mul_f32_e32 v56, 0xbfb8aa3b, v10
	v_exp_f32_e32 v56, v56
	v_mov_b32_e32 v8, v25
	v_add_f32_dpp v11, v11, v11 row_mirror row_mask:0xf bank_mask:0xf bound_ctrl:1
	ds_bpermute_b32 v26, v199, v11
	v_mov_b32_e32 v25, v204
	v_lshlrev_b32_e32 v57, 16, v27
	s_waitcnt lgkmcnt(0)
	v_add_f32_e32 v58, v11, v26
	v_pk_fma_f32 v[10:11], v[42:43], v[40:41], 0 op_sel_hi:[1,1,0]
	v_lshlrev_b64 v[26:27], 11, v[108:109]
	v_pk_fma_f32 v[8:9], v[8:9], v[24:25], v[10:11]
	v_mul_f32_e32 v25, v58, v114
	v_fma_f32 v25, v99, v40, -v25
	v_mov_b32_dpp v10, v8 quad_perm:[1,0,3,2] row_mask:0xf bank_mask:0xf bound_ctrl:1
	v_mov_b32_dpp v11, v9 quad_perm:[1,0,3,2] row_mask:0xf bank_mask:0xf bound_ctrl:1
	v_pk_add_f32 v[8:9], v[8:9], v[10:11]
	v_lshl_add_u64 v[26:27], v[64:65], 0, v[26:27]
	v_cvt_pk_bf16_f32 v25, v25, s0
	v_mov_b32_dpp v10, v8 quad_perm:[2,3,0,1] row_mask:0xf bank_mask:0xf bound_ctrl:1
	v_mov_b32_dpp v11, v9 quad_perm:[2,3,0,1] row_mask:0xf bank_mask:0xf bound_ctrl:1
	v_pk_add_f32 v[8:9], v[8:9], v[10:11]
	global_store_short v[26:27], v25, off
	v_mul_f32_e32 v25, v58, v57
	v_mov_b32_dpp v10, v8 row_half_mirror row_mask:0xf bank_mask:0xf bound_ctrl:1
	v_mov_b32_dpp v11, v9 row_half_mirror row_mask:0xf bank_mask:0xf bound_ctrl:1
	v_pk_add_f32 v[8:9], v[8:9], v[10:11]
	v_fma_f32 v24, v56, v24, -v25
	v_cvt_pk_bf16_f32 v24, v24, s0
	v_mov_b32_dpp v10, v8 row_mirror row_mask:0xf bank_mask:0xf bound_ctrl:1
	v_mov_b32_dpp v11, v9 row_mirror row_mask:0xf bank_mask:0xf bound_ctrl:1
	v_pk_add_f32 v[8:9], v[8:9], v[10:11]
	ds_bpermute_b32 v10, v199, v8
	ds_bpermute_b32 v11, v199, v9
	global_store_short v[26:27], v24, off offset:64
	s_and_saveexec_b64 s[0:1], s[2:3]
	s_cbranch_execz .LBB0_563
	v_lshlrev_b64 v[24:25], 7, v[108:109]
	v_lshl_add_u64 v[24:25], s[72:73], 0, v[24:25]
	s_waitcnt lgkmcnt(0)
	v_pk_add_f32 v[8:9], v[8:9], v[10:11]
	global_store_dwordx2 v[24:25], v[8:9], off
.LBB0_563:
	s_or_b64 exec, exec, s[0:1]
	s_waitcnt vmcnt(48)
	v_lshlrev_b32_e32 v9, 16, v179
	v_lshlrev_b32_e32 v8, 16, v178
	s_waitcnt lgkmcnt(0)
	v_pk_mul_f32 v[10:11], v[100:101], v[8:9]
	v_add_f32_e32 v12, v12, v206
	v_pk_mul_f32 v[24:25], v[10:11], v[10:11]
	s_nop 0
	v_add_f32_e32 v24, v24, v25
	s_nop 1
	v_add_f32_dpp v24, v24, v24 quad_perm:[1,0,3,2] row_mask:0xf bank_mask:0xf bound_ctrl:1
	s_nop 1
	v_add_f32_dpp v24, v24, v24 quad_perm:[2,3,0,1] row_mask:0xf bank_mask:0xf bound_ctrl:1
	s_nop 1
	v_add_f32_dpp v24, v24, v24 row_half_mirror row_mask:0xf bank_mask:0xf bound_ctrl:1
	s_nop 1
	v_add_f32_dpp v24, v24, v24 row_mirror row_mask:0xf bank_mask:0xf bound_ctrl:1
	ds_bpermute_b32 v25, v199, v24
	s_waitcnt lgkmcnt(0)
	v_add_f32_e32 v24, v24, v25
	v_mul_f32_e32 v25, 0x4f800000, v24
	v_cmp_gt_f32_e32 vcc, s75, v24
	s_nop 1
	v_cndmask_b32_e32 v24, v24, v25, vcc
	v_sqrt_f32_e32 v25, v24
	s_nop 0
	v_add_u32_e32 v26, -1, v25
	v_add_u32_e32 v27, 1, v25
	v_fma_f32 v40, -v26, v25, v24
	v_fma_f32 v41, -v27, v25, v24
	v_cmp_ge_f32_e64 s[0:1], 0, v40
	s_nop 1
	v_cndmask_b32_e64 v25, v25, v26, s[0:1]
	v_cmp_lt_f32_e64 s[0:1], 0, v41
	s_nop 1
	v_cndmask_b32_e64 v25, v25, v27, s[0:1]
	v_mul_f32_e32 v26, 0x37800000, v25
	v_cndmask_b32_e32 v25, v25, v26, vcc
	v_cmp_class_f32_e32 vcc, v24, v201
	v_add_f32_e32 v27, v60, v210
	s_nop 0
	v_cndmask_b32_e32 v24, v25, v24, vcc
	v_max_f32_e32 v110, 0x2b8cbccc, v24
	v_max_f32_e64 v113, -v27, 0
	s_nop 0
	s_nop 1
	v_mul_f32_e64 v114, |v27|, s76
	v_exp_f32_e32 v114, v114
	s_nop 1
	v_add_f32_e32 v24, 1.0, v114
	v_log_f32_e32 v24, v24
	s_nop 0
	v_mul_f32_e32 v24, 0x3f317218, v24
	v_add_f32_e32 v24, v113, v24
	v_sub_f32_e32 v24, -0.5, v24
	v_add_f32_e32 v27, v44, v209
	v_rcp_f32_e32 v44, v110
	s_nop 0
	v_mul_f32_e32 v10, v10, v44
	v_cvt_pk_bf16_f32 v60, v10, 0
	v_mul_f32_e32 v26, 0xbfb8aa3b, v27
	v_exp_f32_e32 v26, v26
	s_nop 0
	v_add_f32_e32 v26, 1.0, v26
	v_mul_f32_e32 v11, v11, v44
	s_nop 0
	s_nop 1
	v_mul_f32_e32 v24, 0x3fb8aa3b, v24
	v_exp_f32_e32 v24, v24
	v_rcp_f32_e32 v25, v26
	s_nop 0
	v_add_f32_e32 v26, -1.0, v25
	v_fma_f32 v26, v208, v26, 1.0
	v_mul_f32_e32 v8, v26, v8
	v_cvt_pk_bf16_f32 v26, v24, 0
	v_mul_f32_e32 v10, v25, v10
	v_lshl_add_u64 v[40:41], s[54:55], 0, v[104:105]
	v_lshl_add_u64 v[24:25], s[20:21], 0, v[104:105]
	v_cvt_pk_bf16_f32 v8, v8, 0
	v_cvt_pk_bf16_f32 v10, v10, 0
	global_store_short v[40:41], v26, off
	global_store_short v[106:107], v8, off
	global_store_short v[24:25], v60, off
	v_lshl_add_u64 v[24:25], s[18:19], 0, v[104:105]
	global_store_short v[24:25], v10, off
	v_lshlrev_b32_e32 v25, 16, v8
	v_lshlrev_b32_e32 v8, 16, v10
	v_lshlrev_b32_e32 v10, 16, v26
	v_mul_f32_e32 v26, 0xbfb8aa3b, v10
	v_fma_f32 v27, v10, s76, -v26
	v_rndne_f32_e32 v42, v26
	v_fmac_f32_e32 v27, 0xb2a5705f, v10
	v_sub_f32_e32 v26, v26, v42
	s_waitcnt vmcnt(51)
	v_lshlrev_b32_e32 v24, 16, v177
	v_add_f32_e32 v26, v26, v27
	v_mul_f32_e32 v43, 0xbfb8aa3b, v10
	v_exp_f32_e32 v43, v43
	v_mov_b32_e32 v27, v24
	v_pk_mul_f32 v[26:27], v[26:27], v[24:25]
	v_fma_f32 v112, v8, v24, 0
	v_add_f32_e32 v26, v28, v207
	v_mov_b32_e32 v8, v43
	v_max_f32_e64 v113, -v26, 0
	s_nop 1
	v_mul_f32_e64 v26, |v26|, s76
	v_exp_f32_e32 v26, v26
	v_lshlrev_b32_e32 v58, 16, v60
	s_nop 0
	v_add_f32_e32 v28, 1.0, v26
	v_log_f32_e32 v28, v28
	s_nop 0
	v_mul_f32_e32 v26, 0x3f317218, v28
	v_add_f32_e32 v26, v113, v26
	v_sub_f32_e32 v26, -0.5, v26
	v_mul_f32_e32 v28, 0x3fb8aa3b, v26
	v_exp_f32_e32 v28, v28
	v_mov_b32_e32 v57, v8
	v_mov_b32_e32 v8, v28
	s_nop 0
	s_nop 1
	v_mul_f32_e32 v10, 0xbfb8aa3b, v12
	v_exp_f32_e32 v10, v10
	s_nop 0
	v_add_f32_e32 v10, 1.0, v10
	v_div_scale_f32 v12, s[0:1], v10, v10, 1.0
	v_rcp_f32_e32 v10, v10
	s_nop 0
	v_add_f32_e32 v12, -1.0, v10
	v_fma_f32 v12, v205, v12, 1.0
	v_mul_f32_e32 v9, v12, v9
	v_cvt_pk_bf16_f32 v12, v8, 0
	v_mul_f32_e32 v8, v10, v11
	v_cvt_pk_bf16_f32 v26, v9, 0
	v_cvt_pk_bf16_f32 v28, v11, 0
	v_cvt_pk_bf16_f32 v10, v8, 0
	v_lshl_add_u64 v[8:9], s[20:21], 0, v[66:67]
	global_store_short v[40:41], v12, off offset:64
	global_store_short v[102:103], v26, off
	global_store_short v[8:9], v28, off
	v_lshl_add_u64 v[8:9], s[18:19], 0, v[66:67]
	global_store_short v[8:9], v10, off
	v_lshlrev_b32_e32 v8, 16, v10
	v_lshlrev_b32_e32 v10, 16, v12
	s_waitcnt vmcnt(54)
	v_lshlrev_b32_e32 v40, 16, v176
	v_lshlrev_b32_e32 v41, 16, v26
	v_mov_b32_e32 v9, v40
	v_fmac_f32_e32 v112, v8, v40
	v_pk_mul_f32 v[8:9], v[8:9], v[40:41]
	s_nop 0
	v_add_f32_dpp v11, v112, v112 quad_perm:[1,0,3,2] row_mask:0xf bank_mask:0xf bound_ctrl:1
	s_nop 1
	v_add_f32_dpp v11, v11, v11 quad_perm:[2,3,0,1] row_mask:0xf bank_mask:0xf bound_ctrl:1
	v_mov_b32_e32 v26, v25
	v_mov_b32_e32 v25, v68
	v_add_f32_dpp v11, v11, v11 row_half_mirror row_mask:0xf bank_mask:0xf bound_ctrl:1
	v_mul_f32_e32 v42, 0xbfb8aa3b, v10
	v_exp_f32_e32 v42, v42
	v_mov_b32_e32 v8, v41
	v_add_f32_dpp v11, v11, v11 row_mirror row_mask:0xf bank_mask:0xf bound_ctrl:1
	ds_bpermute_b32 v12, v199, v11
	v_mov_b32_e32 v41, v204
	v_lshlrev_b32_e32 v28, 16, v28
	s_waitcnt lgkmcnt(0)
	v_add_f32_e32 v12, v11, v12
	v_pk_fma_f32 v[10:11], v[26:27], v[24:25], 0 op_sel_hi:[1,1,0]
	v_mul_f32_e32 v25, v12, v58
	v_pk_fma_f32 v[8:9], v[8:9], v[40:41], v[10:11]
	v_mul_f32_e32 v12, v12, v28
	v_lshlrev_b64 v[26:27], 11, v[54:55]
	v_mov_b32_dpp v10, v8 quad_perm:[1,0,3,2] row_mask:0xf bank_mask:0xf bound_ctrl:1
	v_mov_b32_dpp v11, v9 quad_perm:[1,0,3,2] row_mask:0xf bank_mask:0xf bound_ctrl:1
	v_pk_add_f32 v[8:9], v[8:9], v[10:11]
	v_fma_f32 v24, v57, v24, -v25
	v_fma_f32 v12, v42, v40, -v12
	v_mov_b32_dpp v10, v8 quad_perm:[2,3,0,1] row_mask:0xf bank_mask:0xf bound_ctrl:1
	v_mov_b32_dpp v11, v9 quad_perm:[2,3,0,1] row_mask:0xf bank_mask:0xf bound_ctrl:1
	v_pk_add_f32 v[8:9], v[8:9], v[10:11]
	v_lshl_add_u64 v[26:27], v[64:65], 0, v[26:27]
	v_cvt_pk_bf16_f32 v24, v24, s0
	v_mov_b32_dpp v10, v8 row_half_mirror row_mask:0xf bank_mask:0xf bound_ctrl:1
	v_mov_b32_dpp v11, v9 row_half_mirror row_mask:0xf bank_mask:0xf bound_ctrl:1
	v_pk_add_f32 v[8:9], v[8:9], v[10:11]
	v_cvt_pk_bf16_f32 v12, v12, s0
	global_store_short v[26:27], v24, off
	v_mov_b32_dpp v10, v8 row_mirror row_mask:0xf bank_mask:0xf bound_ctrl:1
	v_mov_b32_dpp v11, v9 row_mirror row_mask:0xf bank_mask:0xf bound_ctrl:1
	v_pk_add_f32 v[8:9], v[8:9], v[10:11]
	ds_bpermute_b32 v10, v199, v8
	ds_bpermute_b32 v11, v199, v9
	global_store_short v[26:27], v12, off offset:64
	s_and_saveexec_b64 s[0:1], s[2:3]
	s_cbranch_execz .LBB0_565
	v_lshlrev_b64 v[24:25], 7, v[54:55]
	v_lshl_add_u64 v[24:25], s[72:73], 0, v[24:25]
	s_waitcnt lgkmcnt(0)
	v_pk_add_f32 v[8:9], v[8:9], v[10:11]
	global_store_dwordx2 v[24:25], v[8:9], off
.LBB0_565:
	s_or_b64 exec, exec, s[0:1]
	v_lshlrev_b32_e32 v9, 16, v175
	v_lshlrev_b32_e32 v8, 16, v174
	s_waitcnt lgkmcnt(0)
	v_pk_mul_f32 v[10:11], v[100:101], v[8:9]
	v_add_f32_e32 v13, v13, v206
	v_pk_mul_f32 v[24:25], v[10:11], v[10:11]
	s_nop 0
	v_add_f32_e32 v12, v24, v25
	s_nop 1
	v_add_f32_dpp v12, v12, v12 quad_perm:[1,0,3,2] row_mask:0xf bank_mask:0xf bound_ctrl:1
	s_nop 1
	v_add_f32_dpp v12, v12, v12 quad_perm:[2,3,0,1] row_mask:0xf bank_mask:0xf bound_ctrl:1
	s_nop 1
	v_add_f32_dpp v12, v12, v12 row_half_mirror row_mask:0xf bank_mask:0xf bound_ctrl:1
	s_nop 1
	v_add_f32_dpp v12, v12, v12 row_mirror row_mask:0xf bank_mask:0xf bound_ctrl:1
	ds_bpermute_b32 v24, v199, v12
	s_waitcnt lgkmcnt(0)
	v_add_f32_e32 v12, v12, v24
	v_mul_f32_e32 v24, 0x4f800000, v12
	v_cmp_gt_f32_e32 vcc, s75, v12
	s_nop 1
	v_cndmask_b32_e32 v12, v12, v24, vcc
	v_sqrt_f32_e32 v24, v12
	s_nop 0
	v_add_u32_e32 v25, -1, v24
	v_add_u32_e32 v26, 1, v24
	v_fma_f32 v27, -v25, v24, v12
	v_fma_f32 v28, -v26, v24, v12
	v_cmp_ge_f32_e64 s[0:1], 0, v27
	v_add_f32_e32 v27, v61, v210
	s_nop 0
	v_cndmask_b32_e64 v24, v24, v25, s[0:1]
	v_cmp_lt_f32_e64 s[0:1], 0, v28
	s_nop 1
	v_cndmask_b32_e64 v24, v24, v26, s[0:1]
	v_mul_f32_e32 v25, 0x37800000, v24
	v_cndmask_b32_e32 v24, v24, v25, vcc
	v_cmp_class_f32_e32 vcc, v12, v201
	s_nop 1
	v_cndmask_b32_e32 v12, v24, v12, vcc
	v_max_f32_e32 v12, 0x2b8cbccc, v12
	v_max_f32_e64 v61, -v27, 0
	v_rcp_f32_e32 v12, v12
	s_nop 0
	v_mul_f32_e32 v10, v10, v12
	v_mul_f32_e64 v66, |v27|, s76
	v_exp_f32_e32 v66, v66
	v_mul_f32_e32 v11, v11, v12
	s_nop 0
	v_cvt_pk_bf16_f32 v58, v10, 0
	s_nop 1
	v_add_f32_e32 v24, 1.0, v66
	v_log_f32_e32 v24, v24
	s_nop 0
	v_mul_f32_e32 v24, 0x3f317218, v24
	v_add_f32_e32 v24, v61, v24
	v_sub_f32_e32 v24, -0.5, v24
	v_add_f32_e32 v27, v45, v209
	s_nop 1
	v_mul_f32_e32 v26, 0xbfb8aa3b, v27
	v_exp_f32_e32 v26, v26
	s_nop 0
	v_add_f32_e32 v26, 1.0, v26
	s_nop 1
	v_mul_f32_e32 v24, 0x3fb8aa3b, v24
	v_exp_f32_e32 v24, v24
	v_rcp_f32_e32 v25, v26
	s_nop 0
	v_add_f32_e32 v26, -1.0, v25
	v_fma_f32 v26, v208, v26, 1.0
	v_mul_f32_e32 v8, v26, v8
	v_cvt_pk_bf16_f32 v26, v24, 0
	v_mul_f32_e32 v10, v25, v10
	v_lshl_add_u64 v[40:41], s[54:55], 0, v[50:51]
	v_lshl_add_u64 v[24:25], s[20:21], 0, v[50:51]
	v_cvt_pk_bf16_f32 v8, v8, 0
	v_cvt_pk_bf16_f32 v10, v10, 0
	global_store_short v[40:41], v26, off
	global_store_short v[52:53], v8, off
	global_store_short v[24:25], v58, off
	v_lshl_add_u64 v[24:25], s[18:19], 0, v[50:51]
	global_store_short v[24:25], v10, off
	v_lshlrev_b32_e32 v25, 16, v8
	v_lshlrev_b32_e32 v8, 16, v10
	v_lshlrev_b32_e32 v10, 16, v26
	v_mul_f32_e32 v26, 0xbfb8aa3b, v10
	v_fma_f32 v27, v10, s76, -v26
	v_rndne_f32_e32 v28, v26
	v_fmac_f32_e32 v27, 0xb2a5705f, v10
	v_sub_f32_e32 v26, v26, v28
	v_add_f32_e32 v26, v26, v27
	s_waitcnt vmcnt(59)
	v_lshlrev_b32_e32 v24, 16, v173
	v_mul_f32_e32 v42, 0xbfb8aa3b, v10
	v_exp_f32_e32 v42, v42
	v_mov_b32_e32 v27, v24
	v_pk_mul_f32 v[26:27], v[26:27], v[24:25]
	v_fma_f32 v59, v8, v24, 0
	v_add_f32_e32 v26, v29, v207
	v_mov_b32_e32 v8, v42
	v_max_f32_e64 v60, -v26, 0
	s_nop 1
	v_mul_f32_e64 v26, |v26|, s76
	v_exp_f32_e32 v26, v26
	v_lshlrev_b32_e32 v45, 16, v58
	s_nop 0
	v_add_f32_e32 v28, 1.0, v26
	v_log_f32_e32 v28, v28
	s_nop 0
	v_mul_f32_e32 v26, 0x3f317218, v28
	v_add_f32_e32 v26, v60, v26
	v_sub_f32_e32 v26, -0.5, v26
	v_mul_f32_e32 v28, 0x3fb8aa3b, v26
	v_exp_f32_e32 v28, v28
	v_mov_b32_e32 v44, v8
	v_mov_b32_e32 v8, v28
	s_nop 0
	s_nop 1
	v_mul_f32_e32 v10, 0xbfb8aa3b, v13
	v_exp_f32_e32 v10, v10
	s_nop 0
	v_add_f32_e32 v10, 1.0, v10
	v_div_scale_f32 v13, s[0:1], v10, v10, 1.0
	v_rcp_f32_e32 v10, v10
	s_nop 0
	v_add_f32_e32 v12, -1.0, v10
	v_fma_f32 v12, v205, v12, 1.0
	v_mul_f32_e32 v9, v12, v9
	v_cvt_pk_bf16_f32 v26, v8, 0
	v_mul_f32_e32 v8, v10, v11
	v_cvt_pk_bf16_f32 v12, v9, 0
	v_cvt_pk_bf16_f32 v28, v11, 0
	v_cvt_pk_bf16_f32 v10, v8, 0
	v_lshl_add_u64 v[8:9], s[20:21], 0, v[38:39]
	global_store_short v[40:41], v26, off offset:64
	global_store_short v[48:49], v12, off
	global_store_short v[8:9], v28, off
	v_lshl_add_u64 v[8:9], s[18:19], 0, v[38:39]
	global_store_short v[8:9], v10, off
	v_lshlrev_b32_e32 v8, 16, v10
	v_lshlrev_b32_e32 v10, 16, v26
	v_lshlrev_b32_e32 v13, 16, v12
	s_waitcnt vmcnt(62)
	v_lshlrev_b32_e32 v12, 16, v172
	v_mov_b32_e32 v9, v12
	v_fmac_f32_e32 v59, v8, v12
	v_pk_mul_f32 v[8:9], v[8:9], v[12:13]
	s_nop 0
	v_add_f32_dpp v11, v59, v59 quad_perm:[1,0,3,2] row_mask:0xf bank_mask:0xf bound_ctrl:1
	s_nop 1
	v_add_f32_dpp v11, v11, v11 quad_perm:[2,3,0,1] row_mask:0xf bank_mask:0xf bound_ctrl:1
	v_lshlrev_b32_e32 v28, 16, v28
	v_mul_f32_e32 v29, 0xbfb8aa3b, v10
	v_exp_f32_e32 v29, v29
	v_add_f32_dpp v11, v11, v11 row_half_mirror row_mask:0xf bank_mask:0xf bound_ctrl:1
	v_mov_b32_e32 v8, v13
	v_mov_b32_e32 v13, v204
	v_add_f32_dpp v11, v11, v11 row_mirror row_mask:0xf bank_mask:0xf bound_ctrl:1
	ds_bpermute_b32 v26, v199, v11
	s_waitcnt lgkmcnt(0)
	v_add_f32_e32 v38, v11, v26
	v_mov_b32_e32 v26, v25
	v_mov_b32_e32 v25, v68
	v_pk_fma_f32 v[10:11], v[26:27], v[24:25], 0 op_sel_hi:[1,1,0]
	v_lshlrev_b64 v[26:27], 11, v[36:37]
	v_pk_fma_f32 v[8:9], v[8:9], v[12:13], v[10:11]
	v_mul_f32_e32 v13, v38, v45
	v_fma_f32 v13, v44, v24, -v13
	v_mov_b32_dpp v10, v8 quad_perm:[1,0,3,2] row_mask:0xf bank_mask:0xf bound_ctrl:1
	v_mov_b32_dpp v11, v9 quad_perm:[1,0,3,2] row_mask:0xf bank_mask:0xf bound_ctrl:1
	v_pk_add_f32 v[8:9], v[8:9], v[10:11]
	v_lshl_add_u64 v[26:27], v[64:65], 0, v[26:27]
	v_cvt_pk_bf16_f32 v13, v13, s0
	v_mov_b32_dpp v10, v8 quad_perm:[2,3,0,1] row_mask:0xf bank_mask:0xf bound_ctrl:1
	v_mov_b32_dpp v11, v9 quad_perm:[2,3,0,1] row_mask:0xf bank_mask:0xf bound_ctrl:1
	v_pk_add_f32 v[8:9], v[8:9], v[10:11]
	global_store_short v[26:27], v13, off
	v_mul_f32_e32 v13, v38, v28
	v_mov_b32_dpp v10, v8 row_half_mirror row_mask:0xf bank_mask:0xf bound_ctrl:1
	v_mov_b32_dpp v11, v9 row_half_mirror row_mask:0xf bank_mask:0xf bound_ctrl:1
	v_pk_add_f32 v[8:9], v[8:9], v[10:11]
	v_fma_f32 v12, v29, v12, -v13
	v_cvt_pk_bf16_f32 v12, v12, s0
	v_mov_b32_dpp v10, v8 row_mirror row_mask:0xf bank_mask:0xf bound_ctrl:1
	v_mov_b32_dpp v11, v9 row_mirror row_mask:0xf bank_mask:0xf bound_ctrl:1
	v_pk_add_f32 v[8:9], v[8:9], v[10:11]
	ds_bpermute_b32 v10, v199, v8
	ds_bpermute_b32 v11, v199, v9
	global_store_short v[26:27], v12, off offset:64
	s_and_saveexec_b64 s[0:1], s[2:3]
	s_cbranch_execz .LBB0_567
	v_lshlrev_b64 v[12:13], 7, v[36:37]
	v_lshl_add_u64 v[12:13], s[72:73], 0, v[12:13]
	s_waitcnt lgkmcnt(0)
	v_pk_add_f32 v[8:9], v[8:9], v[10:11]
	global_store_dwordx2 v[12:13], v[8:9], off
.LBB0_567:
	s_or_b64 exec, exec, s[0:1]
	v_lshlrev_b32_e32 v9, 16, v171
	v_lshlrev_b32_e32 v8, 16, v170
	s_waitcnt lgkmcnt(0)
	v_pk_mul_f32 v[10:11], v[100:101], v[8:9]
	v_add_f32_e32 v14, v14, v206
	v_pk_mul_f32 v[12:13], v[10:11], v[10:11]
	s_nop 0
	v_add_f32_e32 v12, v12, v13
	s_nop 1
	v_add_f32_dpp v12, v12, v12 quad_perm:[1,0,3,2] row_mask:0xf bank_mask:0xf bound_ctrl:1
	s_nop 1
	v_add_f32_dpp v12, v12, v12 quad_perm:[2,3,0,1] row_mask:0xf bank_mask:0xf bound_ctrl:1
	s_nop 1
	v_add_f32_dpp v12, v12, v12 row_half_mirror row_mask:0xf bank_mask:0xf bound_ctrl:1
	s_nop 1
	v_add_f32_dpp v12, v12, v12 row_mirror row_mask:0xf bank_mask:0xf bound_ctrl:1
	ds_bpermute_b32 v13, v199, v12
	s_waitcnt lgkmcnt(0)
	v_add_f32_e32 v12, v12, v13
	v_mul_f32_e32 v13, 0x4f800000, v12
	v_cmp_gt_f32_e32 vcc, s75, v12
	s_nop 1
	v_cndmask_b32_e32 v12, v12, v13, vcc
	v_sqrt_f32_e32 v13, v12
	s_nop 0
	v_add_u32_e32 v24, -1, v13
	v_add_u32_e32 v25, 1, v13
	v_fma_f32 v26, -v24, v13, v12
	v_fma_f32 v27, -v25, v13, v12
	v_cmp_ge_f32_e64 s[0:1], 0, v26
	s_nop 1
	v_cndmask_b32_e64 v13, v13, v24, s[0:1]
	v_cmp_lt_f32_e64 s[0:1], 0, v27
	s_nop 1
	v_cndmask_b32_e64 v13, v13, v25, s[0:1]
	v_mul_f32_e32 v24, 0x37800000, v13
	v_cndmask_b32_e32 v13, v13, v24, vcc
	v_cmp_class_f32_e32 vcc, v12, v201
	v_add_f32_e32 v25, v62, v210
	s_nop 0
	v_cndmask_b32_e32 v12, v13, v12, vcc
	v_max_f32_e32 v42, 0x2b8cbccc, v12
	v_max_f32_e64 v48, -v25, 0
	s_nop 0
	s_nop 1
	v_mul_f32_e64 v49, |v25|, s76
	v_exp_f32_e32 v49, v49
	s_nop 1
	v_add_f32_e32 v12, 1.0, v49
	v_log_f32_e32 v12, v12
	s_nop 0
	v_mul_f32_e32 v12, 0x3f317218, v12
	v_add_f32_e32 v12, v48, v12
	v_sub_f32_e32 v12, -0.5, v12
	v_add_f32_e32 v25, v46, v209
	v_rcp_f32_e32 v44, v42
	s_nop 0
	v_mul_f32_e32 v10, v10, v44
	v_cvt_pk_bf16_f32 v45, v10, 0
	v_mul_f32_e32 v24, 0xbfb8aa3b, v25
	v_exp_f32_e32 v24, v24
	s_nop 0
	v_add_f32_e32 v24, 1.0, v24
	v_mul_f32_e32 v11, v11, v44
	s_nop 0
	s_nop 1
	v_mul_f32_e32 v12, 0x3fb8aa3b, v12
	v_exp_f32_e32 v12, v12
	v_rcp_f32_e32 v13, v24
	s_nop 0
	v_add_f32_e32 v24, -1.0, v13
	v_fma_f32 v24, v208, v24, 1.0
	v_mul_f32_e32 v8, v24, v8
	v_cvt_pk_bf16_f32 v24, v12, 0
	v_mul_f32_e32 v10, v13, v10
	v_lshl_add_u64 v[26:27], s[54:55], 0, v[32:33]
	v_lshl_add_u64 v[12:13], s[20:21], 0, v[32:33]
	v_cvt_pk_bf16_f32 v8, v8, 0
	v_cvt_pk_bf16_f32 v10, v10, 0
	global_store_short v[26:27], v24, off
	global_store_short v[34:35], v8, off
	global_store_short v[12:13], v45, off
	v_lshl_add_u64 v[12:13], s[18:19], 0, v[32:33]
	global_store_short v[12:13], v10, off
	v_lshlrev_b32_e32 v13, 16, v8
	v_lshlrev_b32_e32 v8, 16, v10
	v_lshlrev_b32_e32 v10, 16, v24
	v_mul_f32_e32 v24, 0xbfb8aa3b, v10
	v_fma_f32 v25, v10, s76, -v24
	v_rndne_f32_e32 v28, v24
	v_fmac_f32_e32 v25, 0xb2a5705f, v10
	v_sub_f32_e32 v24, v24, v28
	v_add_f32_e32 v24, v24, v25
	s_waitcnt vmcnt(62)
	v_lshlrev_b32_e32 v12, 16, v169
	v_mul_f32_e32 v29, 0xbfb8aa3b, v10
	v_exp_f32_e32 v29, v29
	v_mov_b32_e32 v25, v12
	v_pk_mul_f32 v[24:25], v[24:25], v[12:13]
	v_fma_f32 v46, v8, v12, 0
	v_add_f32_e32 v24, v30, v207
	v_mov_b32_e32 v8, v29
	v_max_f32_e64 v30, -v24, 0
	s_nop 1
	v_mul_f32_e64 v24, |v24|, s76
	v_exp_f32_e32 v24, v24
	v_lshlrev_b32_e32 v34, 16, v45
	s_nop 0
	v_add_f32_e32 v28, 1.0, v24
	v_log_f32_e32 v28, v28
	s_nop 0
	v_mul_f32_e32 v24, 0x3f317218, v28
	v_add_f32_e32 v24, v30, v24
	v_sub_f32_e32 v24, -0.5, v24
	v_mul_f32_e32 v28, 0x3fb8aa3b, v24
	v_exp_f32_e32 v28, v28
	v_mov_b32_e32 v33, v8
	v_mov_b32_e32 v8, v28
	s_nop 0
	s_nop 1
	v_mul_f32_e32 v10, 0xbfb8aa3b, v14
	v_exp_f32_e32 v10, v10
	s_nop 0
	v_add_f32_e32 v10, 1.0, v10
	v_div_scale_f32 v14, s[0:1], v10, v10, 1.0
	v_rcp_f32_e32 v10, v10
	s_nop 0
	v_add_f32_e32 v14, -1.0, v10
	v_fma_f32 v14, v205, v14, 1.0
	v_mul_f32_e32 v9, v14, v9
	v_cvt_pk_bf16_f32 v14, v8, 0
	v_mul_f32_e32 v8, v10, v11
	v_cvt_pk_bf16_f32 v24, v9, 0
	v_cvt_pk_bf16_f32 v28, v11, 0
	v_cvt_pk_bf16_f32 v10, v8, 0
	v_lshl_add_u64 v[8:9], s[20:21], 0, v[20:21]
	global_store_short v[26:27], v14, off offset:64
	global_store_short v[22:23], v24, off
	global_store_short v[8:9], v28, off
	v_lshl_add_u64 v[8:9], s[18:19], 0, v[20:21]
	global_store_short v[8:9], v10, off
	v_lshlrev_b32_e32 v8, 16, v10
	v_lshlrev_b32_e32 v10, 16, v14
	v_lshlrev_b32_e32 v20, 16, v168
	v_lshlrev_b32_e32 v21, 16, v24
	v_mov_b32_e32 v9, v20
	v_fmac_f32_e32 v46, v8, v20
	v_pk_mul_f32 v[8:9], v[8:9], v[20:21]
	s_nop 0
	v_add_f32_dpp v11, v46, v46 quad_perm:[1,0,3,2] row_mask:0xf bank_mask:0xf bound_ctrl:1
	s_nop 1
	v_add_f32_dpp v11, v11, v11 quad_perm:[2,3,0,1] row_mask:0xf bank_mask:0xf bound_ctrl:1
	v_mov_b32_e32 v24, v13
	v_mov_b32_e32 v13, v68
	v_add_f32_dpp v11, v11, v11 row_half_mirror row_mask:0xf bank_mask:0xf bound_ctrl:1
	v_mul_f32_e32 v26, 0xbfb8aa3b, v10
	v_exp_f32_e32 v26, v26
	v_mov_b32_e32 v8, v21
	v_add_f32_dpp v11, v11, v11 row_mirror row_mask:0xf bank_mask:0xf bound_ctrl:1
	ds_bpermute_b32 v14, v199, v11
	v_mov_b32_e32 v21, v204
	v_lshlrev_b64 v[22:23], 11, v[18:19]
	v_lshlrev_b32_e32 v27, 16, v28
	v_lshl_add_u64 v[22:23], v[64:65], 0, v[22:23]
	s_waitcnt lgkmcnt(0)
	v_add_f32_e32 v14, v11, v14
	v_pk_fma_f32 v[10:11], v[24:25], v[12:13], 0 op_sel_hi:[1,1,0]
	v_mul_f32_e32 v13, v14, v34
	v_pk_fma_f32 v[8:9], v[8:9], v[20:21], v[10:11]
	v_fma_f32 v12, v33, v12, -v13
	v_cvt_pk_bf16_f32 v12, v12, s0
	v_mov_b32_dpp v10, v8 quad_perm:[1,0,3,2] row_mask:0xf bank_mask:0xf bound_ctrl:1
	v_mov_b32_dpp v11, v9 quad_perm:[1,0,3,2] row_mask:0xf bank_mask:0xf bound_ctrl:1
	v_pk_add_f32 v[8:9], v[8:9], v[10:11]
	global_store_short v[22:23], v12, off
	v_mul_f32_e32 v12, v14, v27
	v_mov_b32_dpp v10, v8 quad_perm:[2,3,0,1] row_mask:0xf bank_mask:0xf bound_ctrl:1
	v_mov_b32_dpp v11, v9 quad_perm:[2,3,0,1] row_mask:0xf bank_mask:0xf bound_ctrl:1
	v_pk_add_f32 v[8:9], v[8:9], v[10:11]
	v_fma_f32 v12, v26, v20, -v12
	v_cvt_pk_bf16_f32 v12, v12, s0
	v_mov_b32_dpp v10, v8 row_half_mirror row_mask:0xf bank_mask:0xf bound_ctrl:1
	v_mov_b32_dpp v11, v9 row_half_mirror row_mask:0xf bank_mask:0xf bound_ctrl:1
	v_pk_add_f32 v[8:9], v[8:9], v[10:11]
	global_store_short v[22:23], v12, off offset:64
	s_nop 0
	v_mov_b32_dpp v10, v8 row_mirror row_mask:0xf bank_mask:0xf bound_ctrl:1
	v_mov_b32_dpp v11, v9 row_mirror row_mask:0xf bank_mask:0xf bound_ctrl:1
	v_pk_add_f32 v[8:9], v[8:9], v[10:11]
	ds_bpermute_b32 v10, v199, v8
	ds_bpermute_b32 v11, v199, v9
	s_and_saveexec_b64 s[0:1], s[2:3]
	s_cbranch_execz .LBB0_569
	v_lshlrev_b64 v[12:13], 7, v[18:19]
	v_lshl_add_u64 v[12:13], s[72:73], 0, v[12:13]
	s_waitcnt lgkmcnt(0)
	v_pk_add_f32 v[8:9], v[8:9], v[10:11]
	global_store_dwordx2 v[12:13], v[8:9], off
.LBB0_569:
	s_or_b64 exec, exec, s[0:1]
	v_lshlrev_b32_e32 v9, 16, v167
	v_lshlrev_b32_e32 v8, 16, v166
	s_waitcnt lgkmcnt(0)
	v_pk_mul_f32 v[10:11], v[100:101], v[8:9]
	v_add_f32_e32 v15, v15, v206
	v_pk_mul_f32 v[12:13], v[10:11], v[10:11]
	s_nop 0
	v_add_f32_e32 v12, v12, v13
	s_nop 1
	v_add_f32_dpp v12, v12, v12 quad_perm:[1,0,3,2] row_mask:0xf bank_mask:0xf bound_ctrl:1
	s_nop 1
	v_add_f32_dpp v12, v12, v12 quad_perm:[2,3,0,1] row_mask:0xf bank_mask:0xf bound_ctrl:1
	s_nop 1
	v_add_f32_dpp v12, v12, v12 row_half_mirror row_mask:0xf bank_mask:0xf bound_ctrl:1
	s_nop 1
	v_add_f32_dpp v12, v12, v12 row_mirror row_mask:0xf bank_mask:0xf bound_ctrl:1
	ds_bpermute_b32 v13, v199, v12
	s_waitcnt lgkmcnt(0)
	v_add_f32_e32 v12, v12, v13
	v_mul_f32_e32 v13, 0x4f800000, v12
	v_cmp_gt_f32_e32 vcc, s75, v12
	s_nop 1
	v_cndmask_b32_e32 v12, v12, v13, vcc
	v_sqrt_f32_e32 v13, v12
	s_nop 0
	v_add_u32_e32 v14, -1, v13
	v_add_u32_e32 v18, 1, v13
	v_fma_f32 v19, -v14, v13, v12
	v_fma_f32 v20, -v18, v13, v12
	v_cmp_ge_f32_e64 s[0:1], 0, v19
	v_add_f32_e32 v19, v63, v210
	v_max_f32_e64 v34, -v19, 0
	v_cndmask_b32_e64 v13, v13, v14, s[0:1]
	v_cmp_lt_f32_e64 s[0:1], 0, v20
	s_nop 1
	v_cndmask_b32_e64 v13, v13, v18, s[0:1]
	v_mul_f32_e32 v14, 0x37800000, v13
	v_cndmask_b32_e32 v13, v13, v14, vcc
	v_cmp_class_f32_e32 vcc, v12, v201
	s_nop 1
	v_cndmask_b32_e32 v12, v13, v12, vcc
	v_max_f32_e32 v14, 0x2b8cbccc, v12
	s_nop 1
	v_mul_f32_e64 v35, |v19|, s76
	v_exp_f32_e32 v35, v35
	s_nop 1
	v_add_f32_e32 v12, 1.0, v35
	v_log_f32_e32 v12, v12
	s_nop 0
	v_mul_f32_e32 v12, 0x3f317218, v12
	v_add_f32_e32 v12, v34, v12
	v_sub_f32_e32 v12, -0.5, v12
	v_add_f32_e32 v19, v47, v209
	v_rcp_f32_e32 v14, v14
	s_nop 0
	v_mul_f32_e32 v10, v10, v14
	v_cvt_pk_bf16_f32 v32, v10, 0
	v_mul_f32_e32 v18, 0xbfb8aa3b, v19
	v_exp_f32_e32 v18, v18
	s_nop 0
	v_add_f32_e32 v18, 1.0, v18
	v_mul_f32_e32 v11, v11, v14
	v_cvt_pk_bf16_f32 v14, v11, 0
	s_nop 1
	v_mul_f32_e32 v12, 0x3fb8aa3b, v12
	v_exp_f32_e32 v12, v12
	v_rcp_f32_e32 v13, v18
	s_nop 0
	v_add_f32_e32 v18, -1.0, v13
	v_fma_f32 v18, v208, v18, 1.0
	v_mul_f32_e32 v8, v18, v8
	v_mul_f32_e32 v10, v13, v10
	v_cvt_pk_bf16_f32 v20, v12, 0
	v_cvt_pk_bf16_f32 v8, v8, 0
	v_cvt_pk_bf16_f32 v10, v10, 0
	v_lshl_add_u64 v[18:19], s[54:55], 0, v[6:7]
	v_lshl_add_u64 v[12:13], s[20:21], 0, v[6:7]
	v_lshl_add_u64 v[6:7], s[18:19], 0, v[6:7]
	global_store_short v[18:19], v20, off
	global_store_short v[16:17], v8, off
	global_store_short v[6:7], v10, off
	v_lshlrev_b32_e32 v7, 16, v8
	v_lshlrev_b32_e32 v8, 16, v10
	v_lshlrev_b32_e32 v10, 16, v20
	global_store_short v[12:13], v32, off
	v_mul_f32_e32 v12, 0xbfb8aa3b, v10
	v_fma_f32 v13, v10, s76, -v12
	v_rndne_f32_e32 v16, v12
	v_fmac_f32_e32 v13, 0xb2a5705f, v10
	v_sub_f32_e32 v12, v12, v16
	v_add_f32_e32 v12, v12, v13
	v_lshlrev_b32_e32 v6, 16, v165
	v_mul_f32_e32 v17, 0xbfb8aa3b, v10
	v_exp_f32_e32 v17, v17
	v_mov_b32_e32 v13, v6
	v_pk_mul_f32 v[12:13], v[12:13], v[6:7]
	v_fma_f32 v33, v8, v6, 0
	v_add_f32_e32 v12, v31, v207
	v_mov_b32_e32 v8, v17
	v_max_f32_e64 v34, -v12, 0
	s_nop 1
	v_mul_f32_e64 v12, |v12|, s76
	v_exp_f32_e32 v12, v12
	v_lshlrev_b32_e32 v23, 16, v32
	s_nop 0
	v_add_f32_e32 v16, 1.0, v12
	v_log_f32_e32 v16, v16
	s_nop 0
	v_mul_f32_e32 v12, 0x3f317218, v16
	v_add_f32_e32 v12, v34, v12
	v_sub_f32_e32 v12, -0.5, v12
	v_mul_f32_e32 v16, 0x3fb8aa3b, v12
	v_exp_f32_e32 v16, v16
	v_mov_b32_e32 v22, v8
	v_mov_b32_e32 v8, v16
	s_nop 0
	s_nop 1
	v_mul_f32_e32 v10, 0xbfb8aa3b, v15
	v_exp_f32_e32 v10, v10
	s_nop 0
	v_add_f32_e32 v10, 1.0, v10
	v_div_scale_f32 v15, s[0:1], v10, v10, 1.0
	v_rcp_f32_e32 v16, v15
	s_nop 0
	v_fma_f32 v12, -v15, v16, 1.0
	v_fmac_f32_e32 v16, v12, v16
	v_div_scale_f32 v12, vcc, 1.0, v10, 1.0
	v_mul_f32_e32 v17, v12, v16
	v_fma_f32 v20, -v15, v17, v12
	v_fmac_f32_e32 v17, v20, v16
	v_rcp_f32_e32 v10, v10
	s_nop 0
	v_add_f32_e32 v12, -1.0, v10
	v_fma_f32 v12, v205, v12, 1.0
	v_mul_f32_e32 v9, v12, v9
	v_cvt_pk_bf16_f32 v12, v8, 0
	v_cvt_pk_bf16_f32 v8, v9, 0
	v_mul_f32_e32 v9, v10, v11
	global_store_short v[18:19], v12, off offset:64
	global_store_short v[4:5], v8, off
	v_lshl_add_u64 v[4:5], s[20:21], 0, v[2:3]
	v_cvt_pk_bf16_f32 v10, v9, 0
	global_store_short v[4:5], v14, off
	v_lshl_add_u64 v[2:3], s[18:19], 0, v[2:3]
	v_lshlrev_b32_e32 v4, 16, v12
	global_store_short v[2:3], v10, off
	v_lshlrev_b32_e32 v2, 16, v10
	v_lshlrev_b32_e32 v9, 16, v8
	v_lshlrev_b32_e32 v8, 16, v164
	v_mov_b32_e32 v3, v8
	v_fmac_f32_e32 v33, v2, v8
	v_pk_mul_f32 v[2:3], v[2:3], v[8:9]
	s_nop 0
	v_add_f32_dpp v5, v33, v33 quad_perm:[1,0,3,2] row_mask:0xf bank_mask:0xf bound_ctrl:1
	v_cmp_ngt_f32_e32 vcc, s79, v4
	s_nop 0
	v_add_f32_dpp v5, v5, v5 quad_perm:[2,3,0,1] row_mask:0xf bank_mask:0xf bound_ctrl:1
	v_mov_b32_e32 v12, v7
	v_mov_b32_e32 v7, v68
	v_add_f32_dpp v5, v5, v5 row_half_mirror row_mask:0xf bank_mask:0xf bound_ctrl:1
	v_mul_f32_e32 v15, 0xbfb8aa3b, v4
	v_exp_f32_e32 v15, v15
	v_mov_b32_e32 v2, v9
	v_add_f32_dpp v5, v5, v5 row_mirror row_mask:0xf bank_mask:0xf bound_ctrl:1
	ds_bpermute_b32 v10, v199, v5
	v_mov_b32_e32 v9, v204
	v_lshlrev_b32_e32 v14, 16, v14
	s_waitcnt lgkmcnt(0)
	v_add_f32_e32 v16, v5, v10
	v_pk_fma_f32 v[4:5], v[12:13], v[6:7], 0 op_sel_hi:[1,1,0]
	v_mul_f32_e32 v7, v16, v23
	v_pk_fma_f32 v[2:3], v[2:3], v[8:9], v[4:5]
	v_lshlrev_b64 v[10:11], 11, v[0:1]
	v_fma_f32 v6, v22, v6, -v7
	v_mov_b32_dpp v4, v2 quad_perm:[1,0,3,2] row_mask:0xf bank_mask:0xf bound_ctrl:1
	v_mov_b32_dpp v5, v3 quad_perm:[1,0,3,2] row_mask:0xf bank_mask:0xf bound_ctrl:1
	v_pk_add_f32 v[2:3], v[2:3], v[4:5]
	v_lshl_add_u64 v[10:11], v[64:65], 0, v[10:11]
	v_cvt_pk_bf16_f32 v6, v6, s0
	v_mov_b32_dpp v4, v2 quad_perm:[2,3,0,1] row_mask:0xf bank_mask:0xf bound_ctrl:1
	v_mov_b32_dpp v5, v3 quad_perm:[2,3,0,1] row_mask:0xf bank_mask:0xf bound_ctrl:1
	v_pk_add_f32 v[2:3], v[2:3], v[4:5]
	global_store_short v[10:11], v6, off
	v_mul_f32_e32 v6, v16, v14
	v_mov_b32_dpp v4, v2 row_half_mirror row_mask:0xf bank_mask:0xf bound_ctrl:1
	v_mov_b32_dpp v5, v3 row_half_mirror row_mask:0xf bank_mask:0xf bound_ctrl:1
	v_pk_add_f32 v[2:3], v[2:3], v[4:5]
	v_fma_f32 v6, v15, v8, -v6
	v_cvt_pk_bf16_f32 v6, v6, s0
	v_mov_b32_dpp v4, v2 row_mirror row_mask:0xf bank_mask:0xf bound_ctrl:1
	v_mov_b32_dpp v5, v3 row_mirror row_mask:0xf bank_mask:0xf bound_ctrl:1
	v_pk_add_f32 v[2:3], v[2:3], v[4:5]
	ds_bpermute_b32 v4, v199, v2
	ds_bpermute_b32 v5, v199, v3
	global_store_short v[10:11], v6, off offset:64
	s_and_saveexec_b64 s[0:1], s[2:3]
	s_cbranch_execz .LBB0_538
	v_lshlrev_b64 v[0:1], 7, v[0:1]
	v_lshl_add_u64 v[0:1], s[72:73], 0, v[0:1]
	s_waitcnt lgkmcnt(0)
	v_pk_add_f32 v[2:3], v[2:3], v[4:5]
	global_store_dwordx2 v[0:1], v[2:3], off
	s_branch .LBB0_538

.LBB0_1004:
	s_and_b64 s[0:1], s[70:71], exec
	s_cselect_b32 s0, s47, 0x14000000
	v_lshl_or_b32 v0, v177, 4, v175
	s_add_u32 s0, s16, s0
	v_ashrrev_i32_e32 v1, 31, v0
	s_addc_u32 s1, s17, 0
	v_lshlrev_b64 v[0:1], 20, v[0:1]
	v_lshl_add_u64 v[0:1], s[0:1], 0, v[0:1]
	v_lshlrev_b32_e32 v130, 7, v173
	v_lshl_add_u64 v[146:147], v[0:1], 0, v[130:131]
	v_cvt_pk_bf16_f32 v0, v48, s0
	v_add_u32_e32 v1, v198, v199
	ds_write_b16 v1, v0
	v_cvt_pk_bf16_f32 v0, v49, s0
	ds_write_b16 v1, v0 offset:144
	v_cvt_pk_bf16_f32 v0, v50, s0
	ds_write_b16 v1, v0 offset:288
	v_cvt_pk_bf16_f32 v0, v51, s0
	v_add_u32_e32 v48, v198, v200
	ds_write_b16 v48, v0
	v_cvt_pk_bf16_f32 v0, v52, s0
	ds_write_b16 v1, v0 offset:1152
	v_cvt_pk_bf16_f32 v0, v53, s0
	ds_write_b16 v1, v0 offset:1296
	v_cvt_pk_bf16_f32 v0, v54, s0
	ds_write_b16 v1, v0 offset:1440
	v_cvt_pk_bf16_f32 v0, v55, s0
	v_add_u32_e32 v48, v198, v201
	ds_write_b16 v48, v0
	v_cvt_pk_bf16_f32 v0, v56, s0
	ds_write_b16 v1, v0 offset:2304
	v_cvt_pk_bf16_f32 v0, v57, s0
	ds_write_b16 v1, v0 offset:2448
	v_cvt_pk_bf16_f32 v0, v58, s0
	ds_write_b16 v1, v0 offset:2592
	v_cvt_pk_bf16_f32 v0, v59, s0
	v_add_u32_e32 v48, v198, v202
	ds_write_b16 v48, v0
	v_cvt_pk_bf16_f32 v0, v60, s0
	ds_write_b16 v1, v0 offset:3456
	v_cvt_pk_bf16_f32 v0, v61, s0
	ds_write_b16 v1, v0 offset:3600
	v_cvt_pk_bf16_f32 v0, v62, s0
	ds_write_b16 v1, v0 offset:3744
	v_cvt_pk_bf16_f32 v0, v141, s0
	v_add_u32_e32 v48, v198, v203
	ds_write_b16 v48, v0
	v_cvt_pk_bf16_f32 v0, v32, s0
	v_add_u32_e32 v32, v204, v199
	ds_write_b16 v32, v0
	v_cvt_pk_bf16_f32 v0, v33, s0
	ds_write_b16 v32, v0 offset:144
	v_cvt_pk_bf16_f32 v0, v34, s0
	ds_write_b16 v32, v0 offset:288
	v_cvt_pk_bf16_f32 v0, v35, s0
	v_add_u32_e32 v33, v204, v200
	ds_write_b16 v33, v0
	v_cvt_pk_bf16_f32 v0, v36, s0
	ds_write_b16 v32, v0 offset:1152
	v_cvt_pk_bf16_f32 v0, v37, s0
	ds_write_b16 v32, v0 offset:1296
	v_cvt_pk_bf16_f32 v0, v38, s0
	ds_write_b16 v32, v0 offset:1440
	v_cvt_pk_bf16_f32 v0, v39, s0
	v_add_u32_e32 v33, v204, v201
	ds_write_b16 v33, v0
	v_cvt_pk_bf16_f32 v0, v40, s0
	ds_write_b16 v32, v0 offset:2304
	v_cvt_pk_bf16_f32 v0, v41, s0
	ds_write_b16 v32, v0 offset:2448
	v_cvt_pk_bf16_f32 v0, v42, s0
	ds_write_b16 v32, v0 offset:2592
	v_cvt_pk_bf16_f32 v0, v43, s0
	v_add_u32_e32 v33, v204, v202
	ds_write_b16 v33, v0
	v_cvt_pk_bf16_f32 v0, v44, s0
	ds_write_b16 v32, v0 offset:3456
	v_cvt_pk_bf16_f32 v0, v45, s0
	ds_write_b16 v32, v0 offset:3600
	v_cvt_pk_bf16_f32 v0, v46, s0
	ds_write_b16 v32, v0 offset:3744
	v_cvt_pk_bf16_f32 v0, v47, s0
	v_add_u32_e32 v33, v204, v203
	ds_write_b16 v33, v0
	v_cvt_pk_bf16_f32 v0, v63, s0
	ds_write_b16 v1, v0 offset:4608
	v_cvt_pk_bf16_f32 v0, v143, s0
	ds_write_b16 v1, v0 offset:4752
	v_cvt_pk_bf16_f32 v0, v18, s0
	ds_write_b16 v1, v0 offset:4896
	v_cvt_pk_bf16_f32 v0, v19, s0
	v_add_u32_e32 v18, v198, v205
	ds_write_b16 v18, v0
	v_cvt_pk_bf16_f32 v0, v20, s0
	ds_write_b16 v1, v0 offset:5760
	v_cvt_pk_bf16_f32 v0, v21, s0
	ds_write_b16 v1, v0 offset:5904
	v_cvt_pk_bf16_f32 v0, v22, s0
	ds_write_b16 v1, v0 offset:6048
	v_cvt_pk_bf16_f32 v0, v23, s0
	v_add_u32_e32 v18, v198, v206
	ds_write_b16 v18, v0
	v_cvt_pk_bf16_f32 v0, v24, s0
	ds_write_b16 v1, v0 offset:6912
	v_cvt_pk_bf16_f32 v0, v25, s0
	ds_write_b16 v1, v0 offset:7056
	v_cvt_pk_bf16_f32 v0, v26, s0
	ds_write_b16 v1, v0 offset:7200
	v_cvt_pk_bf16_f32 v0, v27, s0
	v_add_u32_e32 v18, v198, v207
	ds_write_b16 v18, v0
	v_cvt_pk_bf16_f32 v0, v28, s0
	ds_write_b16 v1, v0 offset:8064
	v_cvt_pk_bf16_f32 v0, v29, s0
	ds_write_b16 v1, v0 offset:8208
	v_cvt_pk_bf16_f32 v0, v30, s0
	ds_write_b16 v1, v0 offset:8352
	v_cvt_pk_bf16_f32 v0, v31, s0
	v_add_u32_e32 v1, v198, v208
	ds_write_b16 v1, v0
	v_cvt_pk_bf16_f32 v0, v16, s0
	ds_write_b16 v32, v0 offset:4608
	v_cvt_pk_bf16_f32 v0, v17, s0
	ds_write_b16 v32, v0 offset:4752
	v_cvt_pk_bf16_f32 v0, v2, s0
	ds_write_b16 v32, v0 offset:4896
	v_cvt_pk_bf16_f32 v0, v3, s0
	v_add_u32_e32 v1, v204, v205
	ds_write_b16 v1, v0
	v_cvt_pk_bf16_f32 v0, v4, s0
	ds_write_b16 v32, v0 offset:5760
	v_cvt_pk_bf16_f32 v0, v5, s0
	ds_write_b16 v32, v0 offset:5904
	v_cvt_pk_bf16_f32 v0, v6, s0
	ds_write_b16 v32, v0 offset:6048
	v_cvt_pk_bf16_f32 v0, v7, s0
	v_add_u32_e32 v1, v204, v206
	ds_write_b16 v1, v0
	v_cvt_pk_bf16_f32 v0, v8, s0
	ds_write_b16 v32, v0 offset:6912
	v_cvt_pk_bf16_f32 v0, v9, s0
	ds_write_b16 v32, v0 offset:7056
	v_cvt_pk_bf16_f32 v0, v10, s0
	ds_write_b16 v32, v0 offset:7200
	v_cvt_pk_bf16_f32 v0, v11, s0
	v_add_u32_e32 v1, v204, v207
	ds_write_b16 v1, v0
	v_cvt_pk_bf16_f32 v0, v12, s0
	ds_write_b16 v32, v0 offset:8064
	v_cvt_pk_bf16_f32 v0, v13, s0
	ds_write_b16 v32, v0 offset:8208
	v_cvt_pk_bf16_f32 v0, v14, s0
	ds_write_b16 v32, v0 offset:8352
	v_cvt_pk_bf16_f32 v0, v15, s0
	v_add_u32_e32 v1, v204, v208
	v_add_u32_e32 v8, v209, v210
	ds_write_b16 v1, v0
	ds_read_b128 v[0:3], v8
	v_lshlrev_b32_e32 v130, 1, v132
	v_lshl_add_u64 v[4:5], v[146:147], 0, v[130:131]
	v_mov_b32_e32 v173, v131
	v_lshl_add_u64 v[6:7], v[4:5], 0, v[172:173]
	s_waitcnt lgkmcnt(0)
	global_store_dwordx4 v[6:7], v[0:3], off sc0 sc1
	ds_read_b128 v[0:3], v8 offset:1152
	v_mov_b32_e32 v175, v131
	v_lshl_add_u64 v[6:7], v[4:5], 0, v[174:175]
	v_mov_b32_e32 v177, v131
	v_mov_b32_e32 v179, v131
	s_waitcnt lgkmcnt(0)
	global_store_dwordx4 v[6:7], v[0:3], off sc0 sc1
	ds_read_b128 v[0:3], v8 offset:2304
	v_lshl_add_u64 v[6:7], v[4:5], 0, v[176:177]
	v_mov_b32_e32 v181, v131
	v_mov_b32_e32 v183, v131
	v_mov_b32_e32 v185, v131
	s_waitcnt lgkmcnt(0)
	global_store_dwordx4 v[6:7], v[0:3], off sc0 sc1
	ds_read_b128 v[0:3], v8 offset:3456
	v_lshl_add_u64 v[6:7], v[4:5], 0, v[178:179]
	v_mov_b32_e32 v187, v131
	s_waitcnt lgkmcnt(0)
	global_store_dwordx4 v[6:7], v[0:3], off sc0 sc1
	ds_read_b128 v[0:3], v8 offset:4608
	v_lshl_add_u64 v[6:7], v[4:5], 0, v[180:181]
	s_waitcnt lgkmcnt(0)
	global_store_dwordx4 v[6:7], v[0:3], off sc0 sc1
	ds_read_b128 v[0:3], v8 offset:5760
	v_lshl_add_u64 v[6:7], v[4:5], 0, v[182:183]
	s_waitcnt lgkmcnt(0)
	global_store_dwordx4 v[6:7], v[0:3], off sc0 sc1
	ds_read_b128 v[0:3], v8 offset:6912
	v_lshl_add_u64 v[6:7], v[4:5], 0, v[184:185]
	v_lshl_add_u64 v[4:5], v[4:5], 0, v[186:187]
	s_waitcnt lgkmcnt(0)
	global_store_dwordx4 v[6:7], v[0:3], off sc0 sc1
	ds_read_b128 v[0:3], v8 offset:8064
	s_waitcnt lgkmcnt(0)
	global_store_dwordx4 v[4:5], v[0:3], off sc0 sc1

.LBB0_1018:
	s_lshl_b32 s0, s48, 1
	s_ashr_i32 s73, s48, 3
	s_cmp_lt_u32 s48, 8
	v_lshl_add_u32 v188, s70, 7, v145
	s_cselect_b64 s[70:71], -1, 0
	s_cmp_eq_u32 s73, 2
	s_cselect_b64 s[8:9], -1, 0
	v_and_or_b32 v175, s0, 14, v133
	s_or_b64 s[0:1], s[70:71], s[8:9]
	v_ashrrev_i32_e32 v177, 13, v188
	v_and_b32_e32 v173, 0x1fc0, v188
	s_andn2_b64 vcc, exec, s[0:1]
	s_mov_b64 s[0:1], -1
	s_cbranch_vccz .LBB0_1024
	s_cmp_eq_u32 s73, 1
	s_cbranch_scc1 .LBB0_1021
	v_mul_f32_e32 v130, 0xbfb8aa3b, v32
	v_exp_f32_e32 v130, v130
	s_nop 0
	v_add_f32_e32 v130, 1.0, v130
	s_nop 0
	v_rcp_f32_e32 v135, v130
	s_nop 0
	v_mul_f32_e32 v130, v32, v135
	v_mul_f32_e32 v135, 0xbfb8aa3b, v33
	v_exp_f32_e32 v135, v135
	s_nop 0
	v_add_f32_e32 v135, 1.0, v135
	s_nop 0
	v_rcp_f32_e32 v137, v135
	s_nop 0
	v_mul_f32_e32 v137, v33, v137
	v_mul_f32_e32 v135, 0xbfb8aa3b, v34
	v_exp_f32_e32 v135, v135
	s_nop 0
	v_add_f32_e32 v135, 1.0, v135
	s_nop 0
	v_rcp_f32_e32 v139, v135
	s_nop 0
	v_mul_f32_e32 v139, v34, v139
	v_mul_f32_e32 v135, 0xbfb8aa3b, v35
	v_exp_f32_e32 v135, v135
	s_nop 0
	v_add_f32_e32 v135, 1.0, v135
	s_nop 0
	v_rcp_f32_e32 v141, v135
	s_nop 0
	v_mul_f32_e32 v141, v35, v141
	v_mul_f32_e32 v135, 0xbfb8aa3b, v36
	v_exp_f32_e32 v135, v135
	s_nop 0
	v_add_f32_e32 v135, 1.0, v135
	s_nop 0
	v_rcp_f32_e32 v143, v135
	s_nop 0
	v_mul_f32_e32 v143, v36, v143
	v_mul_f32_e32 v135, 0xbfb8aa3b, v37
	v_exp_f32_e32 v135, v135
	s_nop 0
	v_add_f32_e32 v135, 1.0, v135
	s_nop 0
	v_rcp_f32_e32 v146, v135
	s_nop 0
	v_mul_f32_e32 v149, v37, v146
	v_mul_f32_e32 v135, 0xbfb8aa3b, v38
	v_exp_f32_e32 v135, v135
	s_nop 0
	v_add_f32_e32 v135, 1.0, v135
	s_nop 0
	v_rcp_f32_e32 v146, v135
	s_nop 0
	v_mul_f32_e32 v151, v38, v146
	v_mul_f32_e32 v135, 0xbfb8aa3b, v39
	v_exp_f32_e32 v135, v135
	s_nop 0
	v_add_f32_e32 v135, 1.0, v135
	s_nop 0
	v_rcp_f32_e32 v146, v135
	s_nop 0
	v_mul_f32_e32 v153, v39, v146
	v_mul_f32_e32 v135, 0xbfb8aa3b, v40
	v_exp_f32_e32 v135, v135
	s_nop 0
	v_add_f32_e32 v135, 1.0, v135
	s_nop 0
	v_rcp_f32_e32 v146, v135
	s_nop 0
	v_mul_f32_e32 v155, v40, v146
	v_mul_f32_e32 v135, 0xbfb8aa3b, v41
	v_exp_f32_e32 v135, v135
	s_nop 0
	v_add_f32_e32 v135, 1.0, v135
	s_nop 0
	v_rcp_f32_e32 v146, v135
	s_nop 0
	v_mul_f32_e32 v157, v41, v146
	v_mul_f32_e32 v135, 0xbfb8aa3b, v42
	v_exp_f32_e32 v135, v135
	s_nop 0
	v_add_f32_e32 v135, 1.0, v135
	s_nop 0
	v_rcp_f32_e32 v146, v135
	s_nop 0
	v_mul_f32_e32 v159, v42, v146
	v_mul_f32_e32 v135, 0xbfb8aa3b, v43
	v_exp_f32_e32 v135, v135
	s_nop 0
	v_add_f32_e32 v135, 1.0, v135
	s_nop 0
	v_rcp_f32_e32 v146, v135
	s_nop 0
	v_mul_f32_e32 v161, v43, v146
	v_mul_f32_e32 v135, 0xbfb8aa3b, v44
	v_exp_f32_e32 v135, v135
	s_nop 0
	v_add_f32_e32 v135, 1.0, v135
	s_nop 0
	v_rcp_f32_e32 v146, v135
	s_nop 0
	v_mul_f32_e32 v163, v44, v146
	v_mul_f32_e32 v135, 0xbfb8aa3b, v45
	v_exp_f32_e32 v135, v135
	s_nop 0
	v_add_f32_e32 v135, 1.0, v135
	s_nop 0
	v_rcp_f32_e32 v146, v135
	s_nop 0
	v_mul_f32_e32 v165, v45, v146
	v_mul_f32_e32 v135, 0xbfb8aa3b, v46
	v_exp_f32_e32 v135, v135
	s_nop 0
	v_add_f32_e32 v135, 1.0, v135
	s_nop 0
	v_rcp_f32_e32 v146, v135
	s_nop 0
	v_mul_f32_e32 v167, v46, v146
	v_mul_f32_e32 v135, 0xbfb8aa3b, v47
	v_exp_f32_e32 v135, v135
	s_nop 0
	v_add_f32_e32 v135, 1.0, v135
	s_nop 0
	v_rcp_f32_e32 v146, v135
	s_nop 0
	v_mul_f32_e32 v169, v47, v146
	v_mul_f32_e32 v135, 0xbfb8aa3b, v48
	v_exp_f32_e32 v135, v135
	s_nop 0
	v_add_f32_e32 v135, 1.0, v135
	s_nop 0
	v_rcp_f32_e32 v146, v135
	s_nop 0
	v_mul_f32_e32 v171, v48, v146
	v_mul_f32_e32 v135, 0xbfb8aa3b, v49
	v_exp_f32_e32 v135, v135
	s_nop 0
	v_add_f32_e32 v135, 1.0, v135
	s_nop 0
	v_rcp_f32_e32 v146, v135
	s_nop 0
	v_mul_f32_e32 v179, v49, v146
	v_mul_f32_e32 v135, 0xbfb8aa3b, v50
	v_exp_f32_e32 v135, v135
	s_nop 0
	v_add_f32_e32 v135, 1.0, v135
	s_nop 0
	v_rcp_f32_e32 v146, v135
	s_nop 0
	v_mul_f32_e32 v181, v50, v146
	v_mul_f32_e32 v135, 0xbfb8aa3b, v51
	v_exp_f32_e32 v135, v135
	s_nop 0
	v_add_f32_e32 v135, 1.0, v135
	s_nop 0
	v_rcp_f32_e32 v146, v135
	s_nop 0
	v_mul_f32_e32 v183, v51, v146
	v_mul_f32_e32 v135, 0xbfb8aa3b, v52
	v_exp_f32_e32 v135, v135
	s_nop 0
	v_add_f32_e32 v135, 1.0, v135
	s_nop 0
	v_rcp_f32_e32 v146, v135
	s_nop 0
	v_mul_f32_e32 v185, v52, v146
	v_mul_f32_e32 v135, 0xbfb8aa3b, v53
	v_exp_f32_e32 v135, v135
	s_nop 0
	v_add_f32_e32 v135, 1.0, v135
	s_nop 0
	v_rcp_f32_e32 v146, v135
	s_nop 0
	v_mul_f32_e32 v187, v53, v146
	v_mul_f32_e32 v135, 0xbfb8aa3b, v54
	v_exp_f32_e32 v135, v135
	s_nop 0
	v_add_f32_e32 v135, 1.0, v135
	s_nop 0
	v_rcp_f32_e32 v146, v135
	s_nop 0
	v_mul_f32_e32 v190, v54, v146
	v_mul_f32_e32 v135, 0xbfb8aa3b, v55
	v_exp_f32_e32 v135, v135
	s_nop 0
	v_add_f32_e32 v135, 1.0, v135
	s_nop 0
	v_rcp_f32_e32 v146, v135
	s_nop 0
	v_mul_f32_e32 v191, v55, v146
	v_mul_f32_e32 v135, 0xbfb8aa3b, v56
	v_exp_f32_e32 v135, v135
	s_nop 0
	v_add_f32_e32 v135, 1.0, v135
	s_nop 0
	v_rcp_f32_e32 v146, v135
	s_nop 0
	v_mul_f32_e32 v192, v56, v146
	v_mul_f32_e32 v135, 0xbfb8aa3b, v57
	v_exp_f32_e32 v135, v135
	s_nop 0
	v_add_f32_e32 v135, 1.0, v135
	s_nop 0
	v_rcp_f32_e32 v146, v135
	s_nop 0
	v_mul_f32_e32 v193, v57, v146
	v_mul_f32_e32 v135, 0xbfb8aa3b, v58
	v_exp_f32_e32 v135, v135
	s_nop 0
	v_add_f32_e32 v135, 1.0, v135
	s_nop 0
	v_rcp_f32_e32 v146, v135
	s_nop 0
	v_mul_f32_e32 v194, v58, v146
	v_mul_f32_e32 v135, 0xbfb8aa3b, v59
	v_exp_f32_e32 v135, v135
	s_nop 0
	v_add_f32_e32 v135, 1.0, v135
	s_nop 0
	v_rcp_f32_e32 v146, v135
	s_nop 0
	v_mul_f32_e32 v195, v59, v146
	v_mul_f32_e32 v135, 0xbfb8aa3b, v60
	v_exp_f32_e32 v135, v135
	s_nop 0
	v_add_f32_e32 v135, 1.0, v135
	s_nop 0
	v_rcp_f32_e32 v146, v135
	s_nop 0
	v_mul_f32_e32 v217, v60, v146
	v_mul_f32_e32 v135, 0xbfb8aa3b, v61
	v_exp_f32_e32 v135, v135
	s_nop 0
	v_add_f32_e32 v135, 1.0, v135
	s_nop 0
	v_rcp_f32_e32 v146, v135
	s_nop 0
	v_mul_f32_e32 v218, v61, v146
	v_mul_f32_e32 v135, 0xbfb8aa3b, v62
	v_exp_f32_e32 v135, v135
	s_nop 0
	v_add_f32_e32 v135, 1.0, v135
	s_nop 0
	v_rcp_f32_e32 v146, v135
	s_nop 0
	v_mul_f32_e32 v219, v62, v146
	v_mul_f32_e32 v135, 0xbfb8aa3b, v63
	v_exp_f32_e32 v135, v135
	s_nop 0
	v_add_f32_e32 v135, 1.0, v135
	s_nop 0
	v_rcp_f32_e32 v146, v135
	s_nop 0
	v_mul_f32_e32 v220, v63, v146
	v_mul_f32_e32 v135, 0xbfb8aa3b, v0
	v_exp_f32_e32 v135, v135
	s_nop 0
	v_add_f32_e32 v135, 1.0, v135
	s_nop 0
	v_rcp_f32_e32 v146, v135
	s_nop 0
	v_mul_f32_e32 v221, v0, v146
	v_mul_f32_e32 v135, 0xbfb8aa3b, v1
	v_exp_f32_e32 v135, v135
	s_nop 0
	v_add_f32_e32 v135, 1.0, v135
	s_nop 0
	v_rcp_f32_e32 v146, v135
	s_nop 0
	v_mul_f32_e32 v222, v1, v146
	v_mul_f32_e32 v135, 0xbfb8aa3b, v2
	v_exp_f32_e32 v135, v135
	s_nop 0
	v_add_f32_e32 v135, 1.0, v135
	s_nop 0
	v_rcp_f32_e32 v146, v135
	s_nop 0
	v_mul_f32_e32 v223, v2, v146
	v_mul_f32_e32 v135, 0xbfb8aa3b, v3
	v_exp_f32_e32 v135, v135
	s_nop 0
	v_add_f32_e32 v135, 1.0, v135
	s_nop 0
	v_rcp_f32_e32 v146, v135
	s_nop 0
	v_mul_f32_e32 v224, v3, v146
	v_mul_f32_e32 v135, 0xbfb8aa3b, v4
	v_exp_f32_e32 v135, v135
	s_nop 0
	v_add_f32_e32 v135, 1.0, v135
	s_nop 0
	v_rcp_f32_e32 v146, v135
	s_nop 0
	v_mul_f32_e32 v225, v4, v146
	v_mul_f32_e32 v135, 0xbfb8aa3b, v5
	v_exp_f32_e32 v135, v135
	s_nop 0
	v_add_f32_e32 v135, 1.0, v135
	s_nop 0
	v_rcp_f32_e32 v146, v135
	s_nop 0
	v_mul_f32_e32 v226, v5, v146
	v_mul_f32_e32 v135, 0xbfb8aa3b, v6
	v_exp_f32_e32 v135, v135
	s_nop 0
	v_add_f32_e32 v135, 1.0, v135
	s_nop 0
	v_rcp_f32_e32 v146, v135
	s_nop 0
	v_mul_f32_e32 v227, v6, v146
	v_mul_f32_e32 v135, 0xbfb8aa3b, v7
	v_exp_f32_e32 v135, v135
	s_nop 0
	v_add_f32_e32 v135, 1.0, v135
	s_nop 0
	v_rcp_f32_e32 v146, v135
	s_nop 0
	v_mul_f32_e32 v228, v7, v146
	v_mul_f32_e32 v135, 0xbfb8aa3b, v8
	v_exp_f32_e32 v135, v135
	s_nop 0
	v_add_f32_e32 v135, 1.0, v135
	s_nop 0
	v_rcp_f32_e32 v146, v135
	s_nop 0
	v_mul_f32_e32 v229, v8, v146
	v_mul_f32_e32 v135, 0xbfb8aa3b, v9
	v_exp_f32_e32 v135, v135
	s_nop 0
	v_add_f32_e32 v135, 1.0, v135
	s_nop 0
	v_rcp_f32_e32 v146, v135
	s_nop 0
	v_mul_f32_e32 v230, v9, v146
	v_mul_f32_e32 v135, 0xbfb8aa3b, v10
	v_exp_f32_e32 v135, v135
	s_nop 0
	v_add_f32_e32 v135, 1.0, v135
	s_nop 0
	v_rcp_f32_e32 v146, v135
	s_nop 0
	v_mul_f32_e32 v231, v10, v146
	v_mul_f32_e32 v135, 0xbfb8aa3b, v11
	v_exp_f32_e32 v135, v135
	s_nop 0
	v_add_f32_e32 v135, 1.0, v135
	s_nop 0
	v_rcp_f32_e32 v146, v135
	s_nop 0
	v_mul_f32_e32 v232, v11, v146
	v_mul_f32_e32 v135, 0xbfb8aa3b, v12
	v_exp_f32_e32 v135, v135
	s_nop 0
	v_add_f32_e32 v135, 1.0, v135
	s_nop 0
	v_rcp_f32_e32 v146, v135
	s_nop 0
	v_mul_f32_e32 v233, v12, v146
	v_mul_f32_e32 v135, 0xbfb8aa3b, v13
	v_exp_f32_e32 v135, v135
	s_nop 0
	v_add_f32_e32 v135, 1.0, v135
	s_nop 0
	v_rcp_f32_e32 v146, v135
	s_nop 0
	v_mul_f32_e32 v234, v13, v146
	v_mul_f32_e32 v135, 0xbfb8aa3b, v14
	v_exp_f32_e32 v135, v135
	s_nop 0
	v_add_f32_e32 v135, 1.0, v135
	s_nop 0
	v_rcp_f32_e32 v146, v135
	s_nop 0
	v_mul_f32_e32 v235, v14, v146
	v_mul_f32_e32 v135, 0xbfb8aa3b, v15
	v_exp_f32_e32 v135, v135
	s_nop 0
	v_add_f32_e32 v135, 1.0, v135
	s_nop 0
	v_rcp_f32_e32 v146, v135
	s_nop 0
	v_mul_f32_e32 v236, v15, v146
	v_mul_f32_e32 v135, 0xbfb8aa3b, v16
	v_exp_f32_e32 v135, v135
	s_nop 0
	v_add_f32_e32 v135, 1.0, v135
	s_nop 0
	v_rcp_f32_e32 v146, v135
	s_nop 0
	v_mul_f32_e32 v237, v16, v146
	v_mul_f32_e32 v135, 0xbfb8aa3b, v17
	v_exp_f32_e32 v135, v135
	s_nop 0
	v_add_f32_e32 v135, 1.0, v135
	s_nop 0
	v_rcp_f32_e32 v146, v135
	s_nop 0
	v_mul_f32_e32 v238, v17, v146
	v_mul_f32_e32 v135, 0xbfb8aa3b, v18
	v_exp_f32_e32 v135, v135
	s_nop 0
	v_add_f32_e32 v135, 1.0, v135
	s_nop 0
	v_rcp_f32_e32 v146, v135
	s_nop 0
	v_mul_f32_e32 v239, v18, v146
	v_mul_f32_e32 v135, 0xbfb8aa3b, v19
	v_exp_f32_e32 v135, v135
	s_nop 0
	v_add_f32_e32 v135, 1.0, v135
	s_nop 0
	v_rcp_f32_e32 v146, v135
	s_nop 0
	v_mul_f32_e32 v240, v19, v146
	v_mul_f32_e32 v135, 0xbfb8aa3b, v20
	v_exp_f32_e32 v135, v135
	s_nop 0
	v_add_f32_e32 v135, 1.0, v135
	s_nop 0
	v_rcp_f32_e32 v146, v135
	s_nop 0
	v_mul_f32_e32 v241, v20, v146
	v_mul_f32_e32 v135, 0xbfb8aa3b, v21
	v_exp_f32_e32 v135, v135
	s_nop 0
	v_add_f32_e32 v135, 1.0, v135
	s_nop 0
	v_rcp_f32_e32 v146, v135
	s_nop 0
	v_mul_f32_e32 v242, v21, v146
	v_mul_f32_e32 v135, 0xbfb8aa3b, v22
	v_exp_f32_e32 v135, v135
	s_nop 0
	v_add_f32_e32 v135, 1.0, v135
	s_nop 0
	v_rcp_f32_e32 v146, v135
	s_nop 0
	v_mul_f32_e32 v243, v22, v146
	v_mul_f32_e32 v135, 0xbfb8aa3b, v23
	v_exp_f32_e32 v135, v135
	s_nop 0
	v_add_f32_e32 v135, 1.0, v135
	s_nop 0
	v_rcp_f32_e32 v146, v135
	s_nop 0
	v_mul_f32_e32 v244, v23, v146
	v_mul_f32_e32 v135, 0xbfb8aa3b, v24
	v_exp_f32_e32 v135, v135
	s_nop 0
	v_add_f32_e32 v135, 1.0, v135
	s_nop 0
	v_rcp_f32_e32 v146, v135
	s_nop 0
	v_mul_f32_e32 v245, v24, v146
	v_mul_f32_e32 v135, 0xbfb8aa3b, v25
	v_exp_f32_e32 v135, v135
	s_nop 0
	v_add_f32_e32 v135, 1.0, v135
	s_nop 0
	v_rcp_f32_e32 v146, v135
	s_nop 0
	v_mul_f32_e32 v197, v25, v146
	v_mul_f32_e32 v135, 0xbfb8aa3b, v26
	v_exp_f32_e32 v135, v135
	s_nop 0
	v_add_f32_e32 v135, 1.0, v135
	s_nop 0
	v_rcp_f32_e32 v146, v135
	s_nop 0
	v_mul_f32_e32 v246, v26, v146
	v_mul_f32_e32 v135, 0xbfb8aa3b, v27
	v_exp_f32_e32 v135, v135
	s_nop 0
	v_add_f32_e32 v135, 1.0, v135
	s_nop 0
	v_rcp_f32_e32 v146, v135
	s_nop 0
	v_mul_f32_e32 v247, v27, v146
	v_mul_f32_e32 v135, 0xbfb8aa3b, v28
	v_exp_f32_e32 v135, v135
	s_nop 0
	v_add_f32_e32 v135, 1.0, v135
	s_nop 0
	v_rcp_f32_e32 v146, v135
	s_nop 0
	v_mul_f32_e32 v248, v28, v146
	v_mul_f32_e32 v135, 0xbfb8aa3b, v29
	v_exp_f32_e32 v135, v135
	s_nop 0
	v_add_f32_e32 v135, 1.0, v135
	s_nop 0
	v_rcp_f32_e32 v146, v135
	s_nop 0
	v_mul_f32_e32 v249, v29, v146
	v_mul_f32_e32 v135, 0xbfb8aa3b, v30
	v_exp_f32_e32 v135, v135
	s_nop 0
	v_add_f32_e32 v135, 1.0, v135
	s_nop 0
	v_rcp_f32_e32 v146, v135
	s_nop 0
	v_mul_f32_e32 v250, v30, v146
	v_mul_f32_e32 v135, 0xbfb8aa3b, v31
	v_exp_f32_e32 v135, v135
	s_nop 0
	v_add_f32_e32 v135, 1.0, v135
	v_div_scale_f32 v146, s[0:1], v135, v135, v31
	v_rcp_f32_e32 v147, v146
	s_lshl_b32 s0, s48, 8
	s_and_b32 s48, s0, 0x700
	v_cvt_pk_bf16_f32 v130, v130, s0
	v_fma_f32 v189, -v146, v147, 1.0
	v_fmac_f32_e32 v147, v189, v147
	v_div_scale_f32 v189, vcc, v31, v135, v31
	v_mul_f32_e32 v251, v189, v147
	v_fma_f32 v252, -v146, v251, v189
	v_ashrrev_i32_e32 v189, 31, v188
	v_rcp_f32_e32 v146, v135
	s_nop 0
	v_mul_f32_e32 v251, v31, v146
	v_lshlrev_b64 v[146:147], 11, v[188:189]
	v_lshl_add_u64 v[146:147], s[42:43], 0, v[146:147]
	v_lshl_add_u64 v[146:147], v[146:147], 0, s[48:49]
	v_mov_b32_e32 v135, v131
	v_lshl_add_u64 v[146:147], v[146:147], 0, v[134:135]
	v_add_u32_e32 v135, v198, v199
	ds_write_b16 v135, v130
	v_cvt_pk_bf16_f32 v130, v137, s0
	ds_write_b16 v135, v130 offset:144
	v_cvt_pk_bf16_f32 v130, v139, s0
	ds_write_b16 v135, v130 offset:288
	v_cvt_pk_bf16_f32 v130, v141, s0
	v_add_u32_e32 v137, v198, v200
	ds_write_b16 v137, v130
	v_cvt_pk_bf16_f32 v130, v143, s0
	ds_write_b16 v135, v130 offset:1152
	v_cvt_pk_bf16_f32 v130, v149, s0
	ds_write_b16 v135, v130 offset:1296
	v_cvt_pk_bf16_f32 v130, v151, s0
	ds_write_b16 v135, v130 offset:1440
	v_cvt_pk_bf16_f32 v130, v153, s0
	v_add_u32_e32 v137, v198, v201
	ds_write_b16 v137, v130
	v_cvt_pk_bf16_f32 v130, v155, s0
	ds_write_b16 v135, v130 offset:2304
	v_cvt_pk_bf16_f32 v130, v157, s0
	ds_write_b16 v135, v130 offset:2448
	v_cvt_pk_bf16_f32 v130, v159, s0
	ds_write_b16 v135, v130 offset:2592
	v_cvt_pk_bf16_f32 v130, v161, s0
	v_add_u32_e32 v137, v198, v202
	ds_write_b16 v137, v130
	v_cvt_pk_bf16_f32 v130, v163, s0
	ds_write_b16 v135, v130 offset:3456
	v_cvt_pk_bf16_f32 v130, v165, s0
	ds_write_b16 v135, v130 offset:3600
	v_cvt_pk_bf16_f32 v130, v167, s0
	ds_write_b16 v135, v130 offset:3744
	v_cvt_pk_bf16_f32 v130, v169, s0
	v_add_u32_e32 v137, v198, v203
	ds_write_b16 v137, v130
	v_cvt_pk_bf16_f32 v130, v171, s0
	v_add_u32_e32 v137, v204, v199
	ds_write_b16 v137, v130
	v_cvt_pk_bf16_f32 v130, v179, s0
	ds_write_b16 v137, v130 offset:144
	v_cvt_pk_bf16_f32 v130, v181, s0
	ds_write_b16 v137, v130 offset:288
	v_cvt_pk_bf16_f32 v130, v183, s0
	v_add_u32_e32 v139, v204, v200
	ds_write_b16 v139, v130
	v_cvt_pk_bf16_f32 v130, v185, s0
	ds_write_b16 v137, v130 offset:1152
	v_cvt_pk_bf16_f32 v130, v187, s0
	ds_write_b16 v137, v130 offset:1296
	v_cvt_pk_bf16_f32 v130, v190, s0
	ds_write_b16 v137, v130 offset:1440
	v_cvt_pk_bf16_f32 v130, v191, s0
	v_add_u32_e32 v139, v204, v201
	ds_write_b16 v139, v130
	v_cvt_pk_bf16_f32 v130, v192, s0
	ds_write_b16 v137, v130 offset:2304
	v_cvt_pk_bf16_f32 v130, v193, s0
	ds_write_b16 v137, v130 offset:2448
	v_cvt_pk_bf16_f32 v130, v194, s0
	ds_write_b16 v137, v130 offset:2592
	v_cvt_pk_bf16_f32 v130, v195, s0
	v_add_u32_e32 v139, v204, v202
	ds_write_b16 v139, v130
	v_cvt_pk_bf16_f32 v130, v217, s0
	ds_write_b16 v137, v130 offset:3456
	v_cvt_pk_bf16_f32 v130, v218, s0
	ds_write_b16 v137, v130 offset:3600
	v_cvt_pk_bf16_f32 v130, v219, s0
	ds_write_b16 v137, v130 offset:3744
	v_cvt_pk_bf16_f32 v130, v220, s0
	v_add_u32_e32 v139, v204, v203
	ds_write_b16 v139, v130
	v_cvt_pk_bf16_f32 v130, v221, s0
	ds_write_b16 v135, v130 offset:4608
	v_cvt_pk_bf16_f32 v130, v222, s0
	ds_write_b16 v135, v130 offset:4752
	v_cvt_pk_bf16_f32 v130, v223, s0
	ds_write_b16 v135, v130 offset:4896
	v_cvt_pk_bf16_f32 v130, v224, s0
	v_add_u32_e32 v139, v198, v205
	ds_write_b16 v139, v130
	v_cvt_pk_bf16_f32 v130, v225, s0
	ds_write_b16 v135, v130 offset:5760
	v_cvt_pk_bf16_f32 v130, v226, s0
	ds_write_b16 v135, v130 offset:5904
	v_cvt_pk_bf16_f32 v130, v227, s0
	ds_write_b16 v135, v130 offset:6048
	v_cvt_pk_bf16_f32 v130, v228, s0
	v_add_u32_e32 v139, v198, v206
	ds_write_b16 v139, v130
	v_cvt_pk_bf16_f32 v130, v229, s0
	ds_write_b16 v135, v130 offset:6912
	v_cvt_pk_bf16_f32 v130, v230, s0
	ds_write_b16 v135, v130 offset:7056
	v_cvt_pk_bf16_f32 v130, v231, s0
	ds_write_b16 v135, v130 offset:7200
	v_cvt_pk_bf16_f32 v130, v232, s0
	v_add_u32_e32 v139, v198, v207
	ds_write_b16 v139, v130
	v_cvt_pk_bf16_f32 v130, v233, s0
	ds_write_b16 v135, v130 offset:8064
	v_cvt_pk_bf16_f32 v130, v234, s0
	ds_write_b16 v135, v130 offset:8208
	v_cvt_pk_bf16_f32 v130, v235, s0
	ds_write_b16 v135, v130 offset:8352
	v_cvt_pk_bf16_f32 v130, v236, s0
	v_add_u32_e32 v135, v198, v208
	ds_write_b16 v135, v130
	v_cvt_pk_bf16_f32 v130, v237, s0
	ds_write_b16 v137, v130 offset:4608
	v_cvt_pk_bf16_f32 v130, v238, s0
	ds_write_b16 v137, v130 offset:4752
	v_cvt_pk_bf16_f32 v130, v239, s0
	ds_write_b16 v137, v130 offset:4896
	v_cvt_pk_bf16_f32 v130, v240, s0
	v_add_u32_e32 v135, v204, v205
	ds_write_b16 v135, v130
	v_cvt_pk_bf16_f32 v130, v241, s0
	ds_write_b16 v137, v130 offset:5760
	v_cvt_pk_bf16_f32 v130, v242, s0
	ds_write_b16 v137, v130 offset:5904
	v_cvt_pk_bf16_f32 v130, v243, s0
	ds_write_b16 v137, v130 offset:6048
	v_cvt_pk_bf16_f32 v130, v244, s0
	v_add_u32_e32 v135, v204, v206
	ds_write_b16 v135, v130
	v_cvt_pk_bf16_f32 v130, v245, s0
	ds_write_b16 v137, v130 offset:6912
	v_cvt_pk_bf16_f32 v130, v197, s0
	ds_write_b16 v137, v130 offset:7056
	v_cvt_pk_bf16_f32 v130, v246, s0
	ds_write_b16 v137, v130 offset:7200
	v_cvt_pk_bf16_f32 v130, v247, s0
	v_add_u32_e32 v135, v204, v207
	ds_write_b16 v135, v130
	v_cvt_pk_bf16_f32 v130, v248, s0
	ds_write_b16 v137, v130 offset:8064
	v_cvt_pk_bf16_f32 v130, v249, s0
	ds_write_b16 v137, v130 offset:8208
	v_cvt_pk_bf16_f32 v130, v250, s0
	ds_write_b16 v137, v130 offset:8352
	v_cvt_pk_bf16_f32 v130, v251, s0
	v_add_u32_e32 v135, v204, v208
	ds_write_b16 v135, v130
	v_lshlrev_b32_e32 v130, 1, v132
	v_lshl_add_u64 v[146:147], v[146:147], 0, v[130:131]
	v_add_u32_e32 v130, v209, v210
	ds_read_b128 v[190:193], v130
	v_mov_b32_e32 v137, v131
	v_lshl_add_u64 v[194:195], v[146:147], 0, v[136:137]
	v_mov_b32_e32 v139, v131
	v_mov_b32_e32 v141, v131
	s_waitcnt lgkmcnt(0)
	global_store_dwordx4 v[194:195], v[190:193], off
	ds_read_b128 v[190:193], v130 offset:1152
	v_lshl_add_u64 v[194:195], v[146:147], 0, v[138:139]
	v_mov_b32_e32 v143, v131
	v_mov_b32_e32 v149, v131
	v_mov_b32_e32 v151, v131
	s_waitcnt lgkmcnt(0)
	global_store_dwordx4 v[194:195], v[190:193], off
	ds_read_b128 v[190:193], v130 offset:2304
	v_lshl_add_u64 v[194:195], v[146:147], 0, v[140:141]
	v_mov_b32_e32 v153, v131
	v_mov_b32_e32 v155, v131
	v_and_b32_e32 v244, 63, v196
	s_waitcnt lgkmcnt(0)
	global_store_dwordx4 v[194:195], v[190:193], off
	ds_read_b128 v[190:193], v130 offset:3456
	v_lshl_add_u64 v[194:195], v[146:147], 0, v[142:143]
	s_mov_b64 s[0:1], 0
	s_waitcnt lgkmcnt(0)
	global_store_dwordx4 v[194:195], v[190:193], off
	ds_read_b128 v[190:193], v130 offset:4608
	v_lshl_add_u64 v[194:195], v[146:147], 0, v[148:149]
	s_waitcnt lgkmcnt(0)
	global_store_dwordx4 v[194:195], v[190:193], off
	ds_read_b128 v[190:193], v130 offset:5760
	v_lshl_add_u64 v[194:195], v[146:147], 0, v[150:151]
	s_waitcnt lgkmcnt(0)
	global_store_dwordx4 v[194:195], v[190:193], off
	ds_read_b128 v[190:193], v130 offset:6912
	v_lshl_add_u64 v[194:195], v[146:147], 0, v[152:153]
	v_lshl_add_u64 v[146:147], v[146:147], 0, v[154:155]
	s_waitcnt lgkmcnt(0)
	global_store_dwordx4 v[194:195], v[190:193], off
	ds_read_b128 v[190:193], v130 offset:8064
	s_waitcnt lgkmcnt(0)
	global_store_dwordx4 v[146:147], v[190:193], off
.LBB0_1021:
	s_andn2_b64 vcc, exec, s[0:1]
	s_cbranch_vccnz .LBB0_1023
	v_cvt_pk_bf16_f32 v190, v32, v33
	v_cvt_pk_bf16_f32 v191, v34, v35
	v_cvt_pk_bf16_f32 v192, v36, v37
	v_cvt_pk_bf16_f32 v193, v38, v39
	ds_write2_b64 v213, v[190:191], v[192:193] offset1:2
	v_cvt_pk_bf16_f32 v190, v40, v41
	v_cvt_pk_bf16_f32 v191, v42, v43
	v_cvt_pk_bf16_f32 v192, v44, v45
	v_cvt_pk_bf16_f32 v193, v46, v47
	ds_write2_b64 v213, v[190:191], v[192:193] offset0:4 offset1:6
	v_cvt_pk_bf16_f32 v190, v48, v49
	v_cvt_pk_bf16_f32 v191, v50, v51
	v_cvt_pk_bf16_f32 v192, v52, v53
	v_cvt_pk_bf16_f32 v193, v54, v55
	ds_write2_b64 v214, v[190:191], v[192:193] offset1:2
	v_cvt_pk_bf16_f32 v190, v56, v57
	v_cvt_pk_bf16_f32 v191, v58, v59
	v_cvt_pk_bf16_f32 v192, v60, v61
	v_cvt_pk_bf16_f32 v193, v62, v63
	ds_write2_b64 v214, v[190:191], v[192:193] offset0:4 offset1:6
	v_cvt_pk_bf16_f32 v190, v0, v1
	v_cvt_pk_bf16_f32 v191, v2, v3
	v_cvt_pk_bf16_f32 v192, v4, v5
	v_cvt_pk_bf16_f32 v193, v6, v7
	ds_write2_b64 v213, v[190:191], v[192:193] offset0:8 offset1:10
	v_cvt_pk_bf16_f32 v190, v8, v9
	v_cvt_pk_bf16_f32 v191, v10, v11
	v_cvt_pk_bf16_f32 v192, v12, v13
	v_cvt_pk_bf16_f32 v193, v14, v15
	v_lshl_or_b32 v146, v177, 4, v175
	ds_write2_b64 v213, v[190:191], v[192:193] offset0:12 offset1:14
	v_cvt_pk_bf16_f32 v190, v16, v17
	v_cvt_pk_bf16_f32 v191, v18, v19
	v_cvt_pk_bf16_f32 v192, v20, v21
	v_cvt_pk_bf16_f32 v193, v22, v23
	v_ashrrev_i32_e32 v147, 31, v146
	ds_write2_b64 v214, v[190:191], v[192:193] offset0:8 offset1:10
	v_cvt_pk_bf16_f32 v190, v24, v25
	v_cvt_pk_bf16_f32 v191, v26, v27
	v_cvt_pk_bf16_f32 v192, v28, v29
	v_cvt_pk_bf16_f32 v193, v30, v31
	v_add_u32_e32 v135, v209, v210
	v_lshlrev_b64 v[146:147], 20, v[146:147]
	ds_write2_b64 v214, v[190:191], v[192:193] offset0:12 offset1:14
	ds_read_b128 v[190:193], v135
	v_lshl_add_u64 v[146:147], s[40:41], 0, v[146:147]
	v_lshlrev_b32_e32 v130, 1, v173
	v_lshl_add_u64 v[146:147], v[146:147], 0, v[130:131]
	v_lshlrev_b32_e32 v130, 1, v132
	v_lshl_add_u64 v[146:147], v[146:147], 0, v[130:131]
	v_mov_b32_e32 v157, v131
	v_lshl_add_u64 v[194:195], v[146:147], 0, v[156:157]
	s_waitcnt lgkmcnt(0)
	global_store_dwordx4 v[194:195], v[190:193], off sc0 sc1
	ds_read_b128 v[190:193], v135 offset:1152
	v_mov_b32_e32 v159, v131
	v_lshl_add_u64 v[194:195], v[146:147], 0, v[158:159]
	v_mov_b32_e32 v161, v131
	v_mov_b32_e32 v163, v131
	s_waitcnt lgkmcnt(0)
	global_store_dwordx4 v[194:195], v[190:193], off sc0 sc1
	ds_read_b128 v[190:193], v135 offset:2304
	v_lshl_add_u64 v[194:195], v[146:147], 0, v[160:161]
	v_mov_b32_e32 v165, v131
	v_mov_b32_e32 v167, v131
	v_mov_b32_e32 v169, v131
	s_waitcnt lgkmcnt(0)
	global_store_dwordx4 v[194:195], v[190:193], off sc0 sc1
	ds_read_b128 v[190:193], v135 offset:3456
	v_lshl_add_u64 v[194:195], v[146:147], 0, v[162:163]
	v_mov_b32_e32 v171, v131
	s_waitcnt lgkmcnt(0)
	global_store_dwordx4 v[194:195], v[190:193], off sc0 sc1
	ds_read_b128 v[190:193], v135 offset:4608
	v_lshl_add_u64 v[194:195], v[146:147], 0, v[164:165]
	s_waitcnt lgkmcnt(0)
	global_store_dwordx4 v[194:195], v[190:193], off sc0 sc1
	ds_read_b128 v[190:193], v135 offset:5760
	v_lshl_add_u64 v[194:195], v[146:147], 0, v[166:167]
	s_waitcnt lgkmcnt(0)
	global_store_dwordx4 v[194:195], v[190:193], off sc0 sc1
	ds_read_b128 v[190:193], v135 offset:6912
	v_lshl_add_u64 v[194:195], v[146:147], 0, v[168:169]
	v_lshl_add_u64 v[146:147], v[146:147], 0, v[170:171]
	s_waitcnt lgkmcnt(0)
	global_store_dwordx4 v[194:195], v[190:193], off sc0 sc1
	ds_read_b128 v[190:193], v135 offset:8064
	s_waitcnt lgkmcnt(0)
	global_store_dwordx4 v[146:147], v[190:193], off sc0 sc1
